# GEMM epilogue stores (GU act, PROJ outputs, OUT/DOWN residual stream) issued with sc0 sc1 (write-through) so the grid barrier's L2 write-back has little left to flush
# speedup vs baseline: 1.0137x; 1.0129x over previous
.Lg16_proj_k:
	s_add_i32 s3, s1, 2
	s_lshl_b32 s96, s3, 13
	s_add_i32 m0, vcc_lo, 16384
	v_lshl_add_u64 v[160:161], v[188:189], 0, s[96:97]
	global_load_lds_dwordx4 v[160:161], off
	global_load_lds_dwordx4 v[160:161], off offset:1024
	ds_read_b128 v[236:239], v196 offset:0
	ds_read_b128 v[240:243], v162 offset:0
	ds_read_b128 v[244:247], v196 offset:2048
	ds_read_b128 v[248:251], v162 offset:2048
	s_add_i32 s3, s1, 2
	s_lshl_b32 s96, s3, 11
	v_lshl_add_u64 v[198:199], v[184:185], 0, s[96:97]
	v_lshl_add_u64 v[200:201], v[186:187], 0, s[96:97]
	s_waitcnt vmcnt(8) lgkmcnt(3)
	v_mfma_f32_16x16x32_bf16 v[16:19], v[236:239], v[128:131], v[16:19]
	v_mfma_f32_16x16x32_bf16 v[24:27], v[236:239], v[132:135], v[24:27]
	v_mfma_f32_16x16x32_bf16 v[0:3], v[236:239], v[136:139], v[0:3]
	v_mfma_f32_16x16x32_bf16 v[8:11], v[236:239], v[140:143], v[8:11]
	ds_read_b128 v[236:239], v196 offset:4096
	s_waitcnt lgkmcnt(3)
	v_mfma_f32_16x16x32_bf16 v[20:23], v[240:243], v[128:131], v[20:23]
	v_mfma_f32_16x16x32_bf16 v[28:31], v[240:243], v[132:135], v[28:31]
	v_mfma_f32_16x16x32_bf16 v[4:7], v[240:243], v[136:139], v[4:7]
	v_mfma_f32_16x16x32_bf16 v[12:15], v[240:243], v[140:143], v[12:15]
	ds_read_b128 v[240:243], v162 offset:4096
	s_waitcnt lgkmcnt(3)
	v_mfma_f32_16x16x32_bf16 v[112:115], v[244:247], v[128:131], v[112:115]
	v_mfma_f32_16x16x32_bf16 v[120:123], v[244:247], v[132:135], v[120:123]
	v_mfma_f32_16x16x32_bf16 v[96:99], v[244:247], v[136:139], v[96:99]
	v_mfma_f32_16x16x32_bf16 v[104:107], v[244:247], v[140:143], v[104:107]
	ds_read_b128 v[244:247], v196 offset:6144
	s_waitcnt lgkmcnt(3)
	v_mfma_f32_16x16x32_bf16 v[116:119], v[248:251], v[128:131], v[116:119]
	v_mfma_f32_16x16x32_bf16 v[124:127], v[248:251], v[132:135], v[124:127]
	v_mfma_f32_16x16x32_bf16 v[100:103], v[248:251], v[136:139], v[100:103]
	v_mfma_f32_16x16x32_bf16 v[108:111], v[248:251], v[140:143], v[108:111]
	ds_read_b128 v[248:251], v162 offset:6144
	s_waitcnt lgkmcnt(3)
	v_mfma_f32_16x16x32_bf16 v[80:83], v[236:239], v[128:131], v[80:83]
	v_mfma_f32_16x16x32_bf16 v[88:91], v[236:239], v[132:135], v[88:91]
	v_mfma_f32_16x16x32_bf16 v[48:51], v[236:239], v[136:139], v[48:51]
	v_mfma_f32_16x16x32_bf16 v[56:59], v[236:239], v[140:143], v[56:59]
	s_waitcnt lgkmcnt(2)
	v_mfma_f32_16x16x32_bf16 v[84:87], v[240:243], v[128:131], v[84:87]
	v_mfma_f32_16x16x32_bf16 v[92:95], v[240:243], v[132:135], v[92:95]
	v_mfma_f32_16x16x32_bf16 v[52:55], v[240:243], v[136:139], v[52:55]
	v_mfma_f32_16x16x32_bf16 v[60:63], v[240:243], v[140:143], v[60:63]
	s_waitcnt lgkmcnt(1)
	v_mfma_f32_16x16x32_bf16 v[64:67], v[244:247], v[128:131], v[64:67]
	v_mfma_f32_16x16x32_bf16 v[72:75], v[244:247], v[132:135], v[72:75]
	v_mfma_f32_16x16x32_bf16 v[32:35], v[244:247], v[136:139], v[32:35]
	v_mfma_f32_16x16x32_bf16 v[40:43], v[244:247], v[140:143], v[40:43]
	s_waitcnt lgkmcnt(0)
	v_mfma_f32_16x16x32_bf16 v[68:71], v[248:251], v[128:131], v[68:71]
	v_mfma_f32_16x16x32_bf16 v[76:79], v[248:251], v[132:135], v[76:79]
	v_mfma_f32_16x16x32_bf16 v[36:39], v[248:251], v[136:139], v[36:39]
	v_mfma_f32_16x16x32_bf16 v[44:47], v[248:251], v[140:143], v[44:47]
	global_load_dwordx4 v[128:131], v[198:199], off
	global_load_dwordx4 v[132:135], v[198:199], off offset:256
	global_load_dwordx4 v[136:139], v[200:201], off
	global_load_dwordx4 v[140:143], v[200:201], off offset:256
	s_waitcnt vmcnt(10)
	s_barrier
	s_add_i32 s3, s1, 3
	s_lshl_b32 s96, s3, 13
	s_mov_b32 m0, vcc_lo
	v_lshl_add_u64 v[160:161], v[188:189], 0, s[96:97]
	global_load_lds_dwordx4 v[160:161], off
	global_load_lds_dwordx4 v[160:161], off offset:1024
	ds_read_b128 v[236:239], v196 offset:8192
	ds_read_b128 v[240:243], v162 offset:8192
	ds_read_b128 v[244:247], v196 offset:10240
	ds_read_b128 v[248:251], v162 offset:10240
	s_add_i32 s3, s1, 3
	s_lshl_b32 s96, s3, 11
	v_lshl_add_u64 v[198:199], v[184:185], 0, s[96:97]
	v_lshl_add_u64 v[200:201], v[186:187], 0, s[96:97]
	s_waitcnt vmcnt(8) lgkmcnt(3)
	v_mfma_f32_16x16x32_bf16 v[16:19], v[236:239], v[144:147], v[16:19]
	v_mfma_f32_16x16x32_bf16 v[24:27], v[236:239], v[148:151], v[24:27]
	v_mfma_f32_16x16x32_bf16 v[0:3], v[236:239], v[152:155], v[0:3]
	v_mfma_f32_16x16x32_bf16 v[8:11], v[236:239], v[156:159], v[8:11]
	ds_read_b128 v[236:239], v196 offset:12288
	s_waitcnt lgkmcnt(3)
	v_mfma_f32_16x16x32_bf16 v[20:23], v[240:243], v[144:147], v[20:23]
	v_mfma_f32_16x16x32_bf16 v[28:31], v[240:243], v[148:151], v[28:31]
	v_mfma_f32_16x16x32_bf16 v[4:7], v[240:243], v[152:155], v[4:7]
	v_mfma_f32_16x16x32_bf16 v[12:15], v[240:243], v[156:159], v[12:15]
	ds_read_b128 v[240:243], v162 offset:12288
	s_waitcnt lgkmcnt(3)
	v_mfma_f32_16x16x32_bf16 v[112:115], v[244:247], v[144:147], v[112:115]
	v_mfma_f32_16x16x32_bf16 v[120:123], v[244:247], v[148:151], v[120:123]
	v_mfma_f32_16x16x32_bf16 v[96:99], v[244:247], v[152:155], v[96:99]
	v_mfma_f32_16x16x32_bf16 v[104:107], v[244:247], v[156:159], v[104:107]
	ds_read_b128 v[244:247], v196 offset:14336
	s_waitcnt lgkmcnt(3)
	v_mfma_f32_16x16x32_bf16 v[116:119], v[248:251], v[144:147], v[116:119]
	v_mfma_f32_16x16x32_bf16 v[124:127], v[248:251], v[148:151], v[124:127]
	v_mfma_f32_16x16x32_bf16 v[100:103], v[248:251], v[152:155], v[100:103]
	v_mfma_f32_16x16x32_bf16 v[108:111], v[248:251], v[156:159], v[108:111]
	ds_read_b128 v[248:251], v162 offset:14336
	s_waitcnt lgkmcnt(3)
	v_mfma_f32_16x16x32_bf16 v[80:83], v[236:239], v[144:147], v[80:83]
	v_mfma_f32_16x16x32_bf16 v[88:91], v[236:239], v[148:151], v[88:91]
	v_mfma_f32_16x16x32_bf16 v[48:51], v[236:239], v[152:155], v[48:51]
	v_mfma_f32_16x16x32_bf16 v[56:59], v[236:239], v[156:159], v[56:59]
	s_waitcnt lgkmcnt(2)
	v_mfma_f32_16x16x32_bf16 v[84:87], v[240:243], v[144:147], v[84:87]
	v_mfma_f32_16x16x32_bf16 v[92:95], v[240:243], v[148:151], v[92:95]
	v_mfma_f32_16x16x32_bf16 v[52:55], v[240:243], v[152:155], v[52:55]
	v_mfma_f32_16x16x32_bf16 v[60:63], v[240:243], v[156:159], v[60:63]
	s_waitcnt lgkmcnt(1)
	v_mfma_f32_16x16x32_bf16 v[64:67], v[244:247], v[144:147], v[64:67]
	v_mfma_f32_16x16x32_bf16 v[72:75], v[244:247], v[148:151], v[72:75]
	v_mfma_f32_16x16x32_bf16 v[32:35], v[244:247], v[152:155], v[32:35]
	v_mfma_f32_16x16x32_bf16 v[40:43], v[244:247], v[156:159], v[40:43]
	s_waitcnt lgkmcnt(0)
	v_mfma_f32_16x16x32_bf16 v[68:71], v[248:251], v[144:147], v[68:71]
	v_mfma_f32_16x16x32_bf16 v[76:79], v[248:251], v[148:151], v[76:79]
	v_mfma_f32_16x16x32_bf16 v[36:39], v[248:251], v[152:155], v[36:39]
	v_mfma_f32_16x16x32_bf16 v[44:47], v[248:251], v[156:159], v[44:47]
	global_load_dwordx4 v[144:147], v[198:199], off
	global_load_dwordx4 v[148:151], v[198:199], off offset:256
	global_load_dwordx4 v[152:155], v[200:201], off
	global_load_dwordx4 v[156:159], v[200:201], off offset:256
	s_waitcnt vmcnt(10)
	s_barrier
	s_add_i32 s3, s1, 4
	s_lshl_b32 s96, s3, 13
	s_add_i32 m0, vcc_lo, 8192
	v_lshl_add_u64 v[160:161], v[188:189], 0, s[96:97]
	global_load_lds_dwordx4 v[160:161], off
	global_load_lds_dwordx4 v[160:161], off offset:1024
	ds_read_b128 v[236:239], v196 offset:16384
	ds_read_b128 v[240:243], v162 offset:16384
	ds_read_b128 v[244:247], v196 offset:18432
	ds_read_b128 v[248:251], v162 offset:18432
	s_add_i32 s3, s1, 4
	s_lshl_b32 s96, s3, 11
	v_lshl_add_u64 v[198:199], v[184:185], 0, s[96:97]
	v_lshl_add_u64 v[200:201], v[186:187], 0, s[96:97]
	s_waitcnt vmcnt(8) lgkmcnt(3)
	v_mfma_f32_16x16x32_bf16 v[16:19], v[236:239], v[128:131], v[16:19]
	v_mfma_f32_16x16x32_bf16 v[24:27], v[236:239], v[132:135], v[24:27]
	v_mfma_f32_16x16x32_bf16 v[0:3], v[236:239], v[136:139], v[0:3]
	v_mfma_f32_16x16x32_bf16 v[8:11], v[236:239], v[140:143], v[8:11]
	ds_read_b128 v[236:239], v196 offset:20480
	s_waitcnt lgkmcnt(3)
	v_mfma_f32_16x16x32_bf16 v[20:23], v[240:243], v[128:131], v[20:23]
	v_mfma_f32_16x16x32_bf16 v[28:31], v[240:243], v[132:135], v[28:31]
	v_mfma_f32_16x16x32_bf16 v[4:7], v[240:243], v[136:139], v[4:7]
	v_mfma_f32_16x16x32_bf16 v[12:15], v[240:243], v[140:143], v[12:15]
	ds_read_b128 v[240:243], v162 offset:20480
	s_waitcnt lgkmcnt(3)
	v_mfma_f32_16x16x32_bf16 v[112:115], v[244:247], v[128:131], v[112:115]
	v_mfma_f32_16x16x32_bf16 v[120:123], v[244:247], v[132:135], v[120:123]
	v_mfma_f32_16x16x32_bf16 v[96:99], v[244:247], v[136:139], v[96:99]
	v_mfma_f32_16x16x32_bf16 v[104:107], v[244:247], v[140:143], v[104:107]
	ds_read_b128 v[244:247], v196 offset:22528
	s_waitcnt lgkmcnt(3)
	v_mfma_f32_16x16x32_bf16 v[116:119], v[248:251], v[128:131], v[116:119]
	v_mfma_f32_16x16x32_bf16 v[124:127], v[248:251], v[132:135], v[124:127]
	v_mfma_f32_16x16x32_bf16 v[100:103], v[248:251], v[136:139], v[100:103]
	v_mfma_f32_16x16x32_bf16 v[108:111], v[248:251], v[140:143], v[108:111]
	ds_read_b128 v[248:251], v162 offset:22528
	s_waitcnt lgkmcnt(3)
	v_mfma_f32_16x16x32_bf16 v[80:83], v[236:239], v[128:131], v[80:83]
	v_mfma_f32_16x16x32_bf16 v[88:91], v[236:239], v[132:135], v[88:91]
	v_mfma_f32_16x16x32_bf16 v[48:51], v[236:239], v[136:139], v[48:51]
	v_mfma_f32_16x16x32_bf16 v[56:59], v[236:239], v[140:143], v[56:59]
	s_waitcnt lgkmcnt(2)
	v_mfma_f32_16x16x32_bf16 v[84:87], v[240:243], v[128:131], v[84:87]
	v_mfma_f32_16x16x32_bf16 v[92:95], v[240:243], v[132:135], v[92:95]
	v_mfma_f32_16x16x32_bf16 v[52:55], v[240:243], v[136:139], v[52:55]
	v_mfma_f32_16x16x32_bf16 v[60:63], v[240:243], v[140:143], v[60:63]
	s_waitcnt lgkmcnt(1)
	v_mfma_f32_16x16x32_bf16 v[64:67], v[244:247], v[128:131], v[64:67]
	v_mfma_f32_16x16x32_bf16 v[72:75], v[244:247], v[132:135], v[72:75]
	v_mfma_f32_16x16x32_bf16 v[32:35], v[244:247], v[136:139], v[32:35]
	v_mfma_f32_16x16x32_bf16 v[40:43], v[244:247], v[140:143], v[40:43]
	s_waitcnt lgkmcnt(0)
	v_mfma_f32_16x16x32_bf16 v[68:71], v[248:251], v[128:131], v[68:71]
	v_mfma_f32_16x16x32_bf16 v[76:79], v[248:251], v[132:135], v[76:79]
	v_mfma_f32_16x16x32_bf16 v[36:39], v[248:251], v[136:139], v[36:39]
	v_mfma_f32_16x16x32_bf16 v[44:47], v[248:251], v[140:143], v[44:47]
	global_load_dwordx4 v[128:131], v[198:199], off
	global_load_dwordx4 v[132:135], v[198:199], off offset:256
	global_load_dwordx4 v[136:139], v[200:201], off
	global_load_dwordx4 v[140:143], v[200:201], off offset:256
	s_waitcnt vmcnt(10)
	s_barrier
	s_add_i32 s3, s1, 5
	s_lshl_b32 s96, s3, 13
	s_add_i32 m0, vcc_lo, 16384
	v_lshl_add_u64 v[160:161], v[188:189], 0, s[96:97]
	global_load_lds_dwordx4 v[160:161], off
	global_load_lds_dwordx4 v[160:161], off offset:1024
	ds_read_b128 v[236:239], v196 offset:0
	ds_read_b128 v[240:243], v162 offset:0
	ds_read_b128 v[244:247], v196 offset:2048
	ds_read_b128 v[248:251], v162 offset:2048
	s_add_i32 s3, s1, 5
	s_lshl_b32 s96, s3, 11
	v_lshl_add_u64 v[198:199], v[184:185], 0, s[96:97]
	v_lshl_add_u64 v[200:201], v[186:187], 0, s[96:97]
	s_waitcnt vmcnt(8) lgkmcnt(3)
	v_mfma_f32_16x16x32_bf16 v[16:19], v[236:239], v[144:147], v[16:19]
	v_mfma_f32_16x16x32_bf16 v[24:27], v[236:239], v[148:151], v[24:27]
	v_mfma_f32_16x16x32_bf16 v[0:3], v[236:239], v[152:155], v[0:3]
	v_mfma_f32_16x16x32_bf16 v[8:11], v[236:239], v[156:159], v[8:11]
	ds_read_b128 v[236:239], v196 offset:4096
	s_waitcnt lgkmcnt(3)
	v_mfma_f32_16x16x32_bf16 v[20:23], v[240:243], v[144:147], v[20:23]
	v_mfma_f32_16x16x32_bf16 v[28:31], v[240:243], v[148:151], v[28:31]
	v_mfma_f32_16x16x32_bf16 v[4:7], v[240:243], v[152:155], v[4:7]
	v_mfma_f32_16x16x32_bf16 v[12:15], v[240:243], v[156:159], v[12:15]
	ds_read_b128 v[240:243], v162 offset:4096
	s_waitcnt lgkmcnt(3)
	v_mfma_f32_16x16x32_bf16 v[112:115], v[244:247], v[144:147], v[112:115]
	v_mfma_f32_16x16x32_bf16 v[120:123], v[244:247], v[148:151], v[120:123]
	v_mfma_f32_16x16x32_bf16 v[96:99], v[244:247], v[152:155], v[96:99]
	v_mfma_f32_16x16x32_bf16 v[104:107], v[244:247], v[156:159], v[104:107]
	ds_read_b128 v[244:247], v196 offset:6144
	s_waitcnt lgkmcnt(3)
	v_mfma_f32_16x16x32_bf16 v[116:119], v[248:251], v[144:147], v[116:119]
	v_mfma_f32_16x16x32_bf16 v[124:127], v[248:251], v[148:151], v[124:127]
	v_mfma_f32_16x16x32_bf16 v[100:103], v[248:251], v[152:155], v[100:103]
	v_mfma_f32_16x16x32_bf16 v[108:111], v[248:251], v[156:159], v[108:111]
	ds_read_b128 v[248:251], v162 offset:6144
	s_waitcnt lgkmcnt(3)
	v_mfma_f32_16x16x32_bf16 v[80:83], v[236:239], v[144:147], v[80:83]
	v_mfma_f32_16x16x32_bf16 v[88:91], v[236:239], v[148:151], v[88:91]
	v_mfma_f32_16x16x32_bf16 v[48:51], v[236:239], v[152:155], v[48:51]
	v_mfma_f32_16x16x32_bf16 v[56:59], v[236:239], v[156:159], v[56:59]
	s_waitcnt lgkmcnt(2)
	v_mfma_f32_16x16x32_bf16 v[84:87], v[240:243], v[144:147], v[84:87]
	v_mfma_f32_16x16x32_bf16 v[92:95], v[240:243], v[148:151], v[92:95]
	v_mfma_f32_16x16x32_bf16 v[52:55], v[240:243], v[152:155], v[52:55]
	v_mfma_f32_16x16x32_bf16 v[60:63], v[240:243], v[156:159], v[60:63]
	s_waitcnt lgkmcnt(1)
	v_mfma_f32_16x16x32_bf16 v[64:67], v[244:247], v[144:147], v[64:67]
	v_mfma_f32_16x16x32_bf16 v[72:75], v[244:247], v[148:151], v[72:75]
	v_mfma_f32_16x16x32_bf16 v[32:35], v[244:247], v[152:155], v[32:35]
	v_mfma_f32_16x16x32_bf16 v[40:43], v[244:247], v[156:159], v[40:43]
	s_waitcnt lgkmcnt(0)
	v_mfma_f32_16x16x32_bf16 v[68:71], v[248:251], v[144:147], v[68:71]
	v_mfma_f32_16x16x32_bf16 v[76:79], v[248:251], v[148:151], v[76:79]
	v_mfma_f32_16x16x32_bf16 v[36:39], v[248:251], v[152:155], v[36:39]
	v_mfma_f32_16x16x32_bf16 v[44:47], v[248:251], v[156:159], v[44:47]
	global_load_dwordx4 v[144:147], v[198:199], off
	global_load_dwordx4 v[148:151], v[198:199], off offset:256
	global_load_dwordx4 v[152:155], v[200:201], off
	global_load_dwordx4 v[156:159], v[200:201], off offset:256
	s_waitcnt vmcnt(10)
	s_barrier
	s_add_i32 s3, s1, 6
	s_lshl_b32 s96, s3, 13
	s_mov_b32 m0, vcc_lo
	v_lshl_add_u64 v[160:161], v[188:189], 0, s[96:97]
	global_load_lds_dwordx4 v[160:161], off
	global_load_lds_dwordx4 v[160:161], off offset:1024
	ds_read_b128 v[236:239], v196 offset:8192
	ds_read_b128 v[240:243], v162 offset:8192
	ds_read_b128 v[244:247], v196 offset:10240
	ds_read_b128 v[248:251], v162 offset:10240
	s_add_i32 s3, s1, 6
	s_lshl_b32 s96, s3, 11
	v_lshl_add_u64 v[198:199], v[184:185], 0, s[96:97]
	v_lshl_add_u64 v[200:201], v[186:187], 0, s[96:97]
	s_waitcnt vmcnt(8) lgkmcnt(3)
	v_mfma_f32_16x16x32_bf16 v[16:19], v[236:239], v[128:131], v[16:19]
	v_mfma_f32_16x16x32_bf16 v[24:27], v[236:239], v[132:135], v[24:27]
	v_mfma_f32_16x16x32_bf16 v[0:3], v[236:239], v[136:139], v[0:3]
	v_mfma_f32_16x16x32_bf16 v[8:11], v[236:239], v[140:143], v[8:11]
	ds_read_b128 v[236:239], v196 offset:12288
	s_waitcnt lgkmcnt(3)
	v_mfma_f32_16x16x32_bf16 v[20:23], v[240:243], v[128:131], v[20:23]
	v_mfma_f32_16x16x32_bf16 v[28:31], v[240:243], v[132:135], v[28:31]
	v_mfma_f32_16x16x32_bf16 v[4:7], v[240:243], v[136:139], v[4:7]
	v_mfma_f32_16x16x32_bf16 v[12:15], v[240:243], v[140:143], v[12:15]
	ds_read_b128 v[240:243], v162 offset:12288
	s_waitcnt lgkmcnt(3)
	v_mfma_f32_16x16x32_bf16 v[112:115], v[244:247], v[128:131], v[112:115]
	v_mfma_f32_16x16x32_bf16 v[120:123], v[244:247], v[132:135], v[120:123]
	v_mfma_f32_16x16x32_bf16 v[96:99], v[244:247], v[136:139], v[96:99]
	v_mfma_f32_16x16x32_bf16 v[104:107], v[244:247], v[140:143], v[104:107]
	ds_read_b128 v[244:247], v196 offset:14336
	s_waitcnt lgkmcnt(3)
	v_mfma_f32_16x16x32_bf16 v[116:119], v[248:251], v[128:131], v[116:119]
	v_mfma_f32_16x16x32_bf16 v[124:127], v[248:251], v[132:135], v[124:127]
	v_mfma_f32_16x16x32_bf16 v[100:103], v[248:251], v[136:139], v[100:103]
	v_mfma_f32_16x16x32_bf16 v[108:111], v[248:251], v[140:143], v[108:111]
	ds_read_b128 v[248:251], v162 offset:14336
	s_waitcnt lgkmcnt(3)
	v_mfma_f32_16x16x32_bf16 v[80:83], v[236:239], v[128:131], v[80:83]
	v_mfma_f32_16x16x32_bf16 v[88:91], v[236:239], v[132:135], v[88:91]
	v_mfma_f32_16x16x32_bf16 v[48:51], v[236:239], v[136:139], v[48:51]
	v_mfma_f32_16x16x32_bf16 v[56:59], v[236:239], v[140:143], v[56:59]
	s_waitcnt lgkmcnt(2)
	v_mfma_f32_16x16x32_bf16 v[84:87], v[240:243], v[128:131], v[84:87]
	v_mfma_f32_16x16x32_bf16 v[92:95], v[240:243], v[132:135], v[92:95]
	v_mfma_f32_16x16x32_bf16 v[52:55], v[240:243], v[136:139], v[52:55]
	v_mfma_f32_16x16x32_bf16 v[60:63], v[240:243], v[140:143], v[60:63]
	s_waitcnt lgkmcnt(1)
	v_mfma_f32_16x16x32_bf16 v[64:67], v[244:247], v[128:131], v[64:67]
	v_mfma_f32_16x16x32_bf16 v[72:75], v[244:247], v[132:135], v[72:75]
	v_mfma_f32_16x16x32_bf16 v[32:35], v[244:247], v[136:139], v[32:35]
	v_mfma_f32_16x16x32_bf16 v[40:43], v[244:247], v[140:143], v[40:43]
	s_waitcnt lgkmcnt(0)
	v_mfma_f32_16x16x32_bf16 v[68:71], v[248:251], v[128:131], v[68:71]
	v_mfma_f32_16x16x32_bf16 v[76:79], v[248:251], v[132:135], v[76:79]
	v_mfma_f32_16x16x32_bf16 v[36:39], v[248:251], v[136:139], v[36:39]
	v_mfma_f32_16x16x32_bf16 v[44:47], v[248:251], v[140:143], v[44:47]
	global_load_dwordx4 v[128:131], v[198:199], off
	global_load_dwordx4 v[132:135], v[198:199], off offset:256
	global_load_dwordx4 v[136:139], v[200:201], off
	global_load_dwordx4 v[140:143], v[200:201], off offset:256
	s_waitcnt vmcnt(10)
	s_barrier
	s_add_i32 s3, s1, 7
	s_lshl_b32 s96, s3, 13
	s_add_i32 m0, vcc_lo, 8192
	v_lshl_add_u64 v[160:161], v[188:189], 0, s[96:97]
	global_load_lds_dwordx4 v[160:161], off
	global_load_lds_dwordx4 v[160:161], off offset:1024
	ds_read_b128 v[236:239], v196 offset:16384
	ds_read_b128 v[240:243], v162 offset:16384
	ds_read_b128 v[244:247], v196 offset:18432
	ds_read_b128 v[248:251], v162 offset:18432
	s_add_i32 s3, s1, 7
	s_lshl_b32 s96, s3, 11
	v_lshl_add_u64 v[198:199], v[184:185], 0, s[96:97]
	v_lshl_add_u64 v[200:201], v[186:187], 0, s[96:97]
	s_waitcnt vmcnt(8) lgkmcnt(3)
	v_mfma_f32_16x16x32_bf16 v[16:19], v[236:239], v[144:147], v[16:19]
	v_mfma_f32_16x16x32_bf16 v[24:27], v[236:239], v[148:151], v[24:27]
	v_mfma_f32_16x16x32_bf16 v[0:3], v[236:239], v[152:155], v[0:3]
	v_mfma_f32_16x16x32_bf16 v[8:11], v[236:239], v[156:159], v[8:11]
	ds_read_b128 v[236:239], v196 offset:20480
	s_waitcnt lgkmcnt(3)
	v_mfma_f32_16x16x32_bf16 v[20:23], v[240:243], v[144:147], v[20:23]
	v_mfma_f32_16x16x32_bf16 v[28:31], v[240:243], v[148:151], v[28:31]
	v_mfma_f32_16x16x32_bf16 v[4:7], v[240:243], v[152:155], v[4:7]
	v_mfma_f32_16x16x32_bf16 v[12:15], v[240:243], v[156:159], v[12:15]
	ds_read_b128 v[240:243], v162 offset:20480
	s_waitcnt lgkmcnt(3)
	v_mfma_f32_16x16x32_bf16 v[112:115], v[244:247], v[144:147], v[112:115]
	v_mfma_f32_16x16x32_bf16 v[120:123], v[244:247], v[148:151], v[120:123]
	v_mfma_f32_16x16x32_bf16 v[96:99], v[244:247], v[152:155], v[96:99]
	v_mfma_f32_16x16x32_bf16 v[104:107], v[244:247], v[156:159], v[104:107]
	ds_read_b128 v[244:247], v196 offset:22528
	s_waitcnt lgkmcnt(3)
	v_mfma_f32_16x16x32_bf16 v[116:119], v[248:251], v[144:147], v[116:119]
	v_mfma_f32_16x16x32_bf16 v[124:127], v[248:251], v[148:151], v[124:127]
	v_mfma_f32_16x16x32_bf16 v[100:103], v[248:251], v[152:155], v[100:103]
	v_mfma_f32_16x16x32_bf16 v[108:111], v[248:251], v[156:159], v[108:111]
	ds_read_b128 v[248:251], v162 offset:22528
	s_waitcnt lgkmcnt(3)
	v_mfma_f32_16x16x32_bf16 v[80:83], v[236:239], v[144:147], v[80:83]
	v_mfma_f32_16x16x32_bf16 v[88:91], v[236:239], v[148:151], v[88:91]
	v_mfma_f32_16x16x32_bf16 v[48:51], v[236:239], v[152:155], v[48:51]
	v_mfma_f32_16x16x32_bf16 v[56:59], v[236:239], v[156:159], v[56:59]
	s_waitcnt lgkmcnt(2)
	v_mfma_f32_16x16x32_bf16 v[84:87], v[240:243], v[144:147], v[84:87]
	v_mfma_f32_16x16x32_bf16 v[92:95], v[240:243], v[148:151], v[92:95]
	v_mfma_f32_16x16x32_bf16 v[52:55], v[240:243], v[152:155], v[52:55]
	v_mfma_f32_16x16x32_bf16 v[60:63], v[240:243], v[156:159], v[60:63]
	s_waitcnt lgkmcnt(1)
	v_mfma_f32_16x16x32_bf16 v[64:67], v[244:247], v[144:147], v[64:67]
	v_mfma_f32_16x16x32_bf16 v[72:75], v[244:247], v[148:151], v[72:75]
	v_mfma_f32_16x16x32_bf16 v[32:35], v[244:247], v[152:155], v[32:35]
	v_mfma_f32_16x16x32_bf16 v[40:43], v[244:247], v[156:159], v[40:43]
	s_waitcnt lgkmcnt(0)
	v_mfma_f32_16x16x32_bf16 v[68:71], v[248:251], v[144:147], v[68:71]
	v_mfma_f32_16x16x32_bf16 v[76:79], v[248:251], v[148:151], v[76:79]
	v_mfma_f32_16x16x32_bf16 v[36:39], v[248:251], v[152:155], v[36:39]
	v_mfma_f32_16x16x32_bf16 v[44:47], v[248:251], v[156:159], v[44:47]
	global_load_dwordx4 v[144:147], v[198:199], off
	global_load_dwordx4 v[148:151], v[198:199], off offset:256
	global_load_dwordx4 v[152:155], v[200:201], off
	global_load_dwordx4 v[156:159], v[200:201], off offset:256
	s_waitcnt vmcnt(10)
	s_barrier
	s_add_i32 s1, s1, 6
	s_cmp_lt_u32 s1, 30
	s_cbranch_scc1 .Lg16_proj_k
	ds_read_b128 v[236:239], v196 offset:0
	ds_read_b128 v[240:243], v162 offset:0
	ds_read_b128 v[244:247], v196 offset:2048
	ds_read_b128 v[248:251], v162 offset:2048
	s_waitcnt vmcnt(6) lgkmcnt(3)
	v_mfma_f32_16x16x32_bf16 v[16:19], v[236:239], v[128:131], v[16:19]
	v_mfma_f32_16x16x32_bf16 v[24:27], v[236:239], v[132:135], v[24:27]
	v_mfma_f32_16x16x32_bf16 v[0:3], v[236:239], v[136:139], v[0:3]
	v_mfma_f32_16x16x32_bf16 v[8:11], v[236:239], v[140:143], v[8:11]
	ds_read_b128 v[236:239], v196 offset:4096
	s_waitcnt lgkmcnt(3)
	v_mfma_f32_16x16x32_bf16 v[20:23], v[240:243], v[128:131], v[20:23]
	v_mfma_f32_16x16x32_bf16 v[28:31], v[240:243], v[132:135], v[28:31]
	v_mfma_f32_16x16x32_bf16 v[4:7], v[240:243], v[136:139], v[4:7]
	v_mfma_f32_16x16x32_bf16 v[12:15], v[240:243], v[140:143], v[12:15]
	ds_read_b128 v[240:243], v162 offset:4096
	s_waitcnt lgkmcnt(3)
	v_mfma_f32_16x16x32_bf16 v[112:115], v[244:247], v[128:131], v[112:115]
	v_mfma_f32_16x16x32_bf16 v[120:123], v[244:247], v[132:135], v[120:123]
	v_mfma_f32_16x16x32_bf16 v[96:99], v[244:247], v[136:139], v[96:99]
	v_mfma_f32_16x16x32_bf16 v[104:107], v[244:247], v[140:143], v[104:107]
	ds_read_b128 v[244:247], v196 offset:6144
	s_waitcnt lgkmcnt(3)
	v_mfma_f32_16x16x32_bf16 v[116:119], v[248:251], v[128:131], v[116:119]
	v_mfma_f32_16x16x32_bf16 v[124:127], v[248:251], v[132:135], v[124:127]
	v_mfma_f32_16x16x32_bf16 v[100:103], v[248:251], v[136:139], v[100:103]
	v_mfma_f32_16x16x32_bf16 v[108:111], v[248:251], v[140:143], v[108:111]
	ds_read_b128 v[248:251], v162 offset:6144
	s_waitcnt lgkmcnt(3)
	v_mfma_f32_16x16x32_bf16 v[80:83], v[236:239], v[128:131], v[80:83]
	v_mfma_f32_16x16x32_bf16 v[88:91], v[236:239], v[132:135], v[88:91]
	v_mfma_f32_16x16x32_bf16 v[48:51], v[236:239], v[136:139], v[48:51]
	v_mfma_f32_16x16x32_bf16 v[56:59], v[236:239], v[140:143], v[56:59]
	s_waitcnt lgkmcnt(2)
	v_mfma_f32_16x16x32_bf16 v[84:87], v[240:243], v[128:131], v[84:87]
	v_mfma_f32_16x16x32_bf16 v[92:95], v[240:243], v[132:135], v[92:95]
	v_mfma_f32_16x16x32_bf16 v[52:55], v[240:243], v[136:139], v[52:55]
	v_mfma_f32_16x16x32_bf16 v[60:63], v[240:243], v[140:143], v[60:63]
	s_waitcnt lgkmcnt(1)
	v_mfma_f32_16x16x32_bf16 v[64:67], v[244:247], v[128:131], v[64:67]
	v_mfma_f32_16x16x32_bf16 v[72:75], v[244:247], v[132:135], v[72:75]
	v_mfma_f32_16x16x32_bf16 v[32:35], v[244:247], v[136:139], v[32:35]
	v_mfma_f32_16x16x32_bf16 v[40:43], v[244:247], v[140:143], v[40:43]
	s_waitcnt lgkmcnt(0)
	v_mfma_f32_16x16x32_bf16 v[68:71], v[248:251], v[128:131], v[68:71]
	v_mfma_f32_16x16x32_bf16 v[76:79], v[248:251], v[132:135], v[76:79]
	v_mfma_f32_16x16x32_bf16 v[36:39], v[248:251], v[136:139], v[36:39]
	v_mfma_f32_16x16x32_bf16 v[44:47], v[248:251], v[140:143], v[44:47]
	s_waitcnt vmcnt(4)
	s_barrier
	ds_read_b128 v[236:239], v196 offset:8192
	ds_read_b128 v[240:243], v162 offset:8192
	ds_read_b128 v[244:247], v196 offset:10240
	ds_read_b128 v[248:251], v162 offset:10240
	s_waitcnt vmcnt(0) lgkmcnt(3)
	v_mfma_f32_16x16x32_bf16 v[16:19], v[236:239], v[144:147], v[16:19]
	v_mfma_f32_16x16x32_bf16 v[24:27], v[236:239], v[148:151], v[24:27]
	v_mfma_f32_16x16x32_bf16 v[0:3], v[236:239], v[152:155], v[0:3]
	v_mfma_f32_16x16x32_bf16 v[8:11], v[236:239], v[156:159], v[8:11]
	ds_read_b128 v[236:239], v196 offset:12288
	s_waitcnt lgkmcnt(3)
	v_mfma_f32_16x16x32_bf16 v[20:23], v[240:243], v[144:147], v[20:23]
	v_mfma_f32_16x16x32_bf16 v[28:31], v[240:243], v[148:151], v[28:31]
	v_mfma_f32_16x16x32_bf16 v[4:7], v[240:243], v[152:155], v[4:7]
	v_mfma_f32_16x16x32_bf16 v[12:15], v[240:243], v[156:159], v[12:15]
	ds_read_b128 v[240:243], v162 offset:12288
	s_waitcnt lgkmcnt(3)
	v_mfma_f32_16x16x32_bf16 v[112:115], v[244:247], v[144:147], v[112:115]
	v_mfma_f32_16x16x32_bf16 v[120:123], v[244:247], v[148:151], v[120:123]
	v_mfma_f32_16x16x32_bf16 v[96:99], v[244:247], v[152:155], v[96:99]
	v_mfma_f32_16x16x32_bf16 v[104:107], v[244:247], v[156:159], v[104:107]
	ds_read_b128 v[244:247], v196 offset:14336
	s_waitcnt lgkmcnt(3)
	v_mfma_f32_16x16x32_bf16 v[116:119], v[248:251], v[144:147], v[116:119]
	v_mfma_f32_16x16x32_bf16 v[124:127], v[248:251], v[148:151], v[124:127]
	v_mfma_f32_16x16x32_bf16 v[100:103], v[248:251], v[152:155], v[100:103]
	v_mfma_f32_16x16x32_bf16 v[108:111], v[248:251], v[156:159], v[108:111]
	ds_read_b128 v[248:251], v162 offset:14336
	s_waitcnt lgkmcnt(3)
	v_mfma_f32_16x16x32_bf16 v[80:83], v[236:239], v[144:147], v[80:83]
	v_mfma_f32_16x16x32_bf16 v[88:91], v[236:239], v[148:151], v[88:91]
	v_mfma_f32_16x16x32_bf16 v[48:51], v[236:239], v[152:155], v[48:51]
	v_mfma_f32_16x16x32_bf16 v[56:59], v[236:239], v[156:159], v[56:59]
	s_waitcnt lgkmcnt(2)
	v_mfma_f32_16x16x32_bf16 v[84:87], v[240:243], v[144:147], v[84:87]
	v_mfma_f32_16x16x32_bf16 v[92:95], v[240:243], v[148:151], v[92:95]
	v_mfma_f32_16x16x32_bf16 v[52:55], v[240:243], v[152:155], v[52:55]
	v_mfma_f32_16x16x32_bf16 v[60:63], v[240:243], v[156:159], v[60:63]
	s_waitcnt lgkmcnt(1)
	v_mfma_f32_16x16x32_bf16 v[64:67], v[244:247], v[144:147], v[64:67]
	v_mfma_f32_16x16x32_bf16 v[72:75], v[244:247], v[148:151], v[72:75]
	v_mfma_f32_16x16x32_bf16 v[32:35], v[244:247], v[152:155], v[32:35]
	v_mfma_f32_16x16x32_bf16 v[40:43], v[244:247], v[156:159], v[40:43]
	s_waitcnt lgkmcnt(0)
	v_mfma_f32_16x16x32_bf16 v[68:71], v[248:251], v[144:147], v[68:71]
	v_mfma_f32_16x16x32_bf16 v[76:79], v[248:251], v[148:151], v[76:79]
	v_mfma_f32_16x16x32_bf16 v[36:39], v[248:251], v[152:155], v[36:39]
	v_mfma_f32_16x16x32_bf16 v[44:47], v[248:251], v[156:159], v[44:47]
	s_barrier
	s_nop 7
	s_nop 1
	s_waitcnt vmcnt(0)
	s_waitcnt vmcnt(0)
	v_and_b32_e32 v128, 63, v179
	v_lshrrev_b32_e32 v129, 6, v179
	s_lshl_b32 s20, s2, 8
	s_cmp_eq_u32 s0, 23
	s_cbranch_scc1 .Lpe_proj_ab
	v_readlane_b32 s14, v254, 15
	v_readlane_b32 s15, v254, 16
	v_readlane_b32 s16, v254, 17
	v_readlane_b32 s17, v254, 18
	s_movk_i32 s22, 0x900
	s_movk_i32 s23, 0x300
	s_cmp_lt_u32 s0, 20
	s_cselect_b32 s14, s14, s16
	s_cselect_b32 s15, s15, s17
	s_cselect_b32 s18, s22, s23
	s_movk_i32 s22, 0xf500
	s_movk_i32 s23, 0xec00
	s_cselect_b32 s19, s22, s23
	s_movk_i32 s22, 0xb00
	s_cmp_lt_u32 s0, 11
	s_cselect_b32 s14, s66, s14
	s_cselect_b32 s15, s67, s15
	s_cselect_b32 s18, s22, s18
	s_cselect_b32 s19, 0, s19
	s_mul_hi_u32 s21, s20, s18
	s_mul_i32 s20, s20, s18
	s_lshl_b32 s22, s0, 8
	s_add_i32 s22, s22, s19
	s_add_u32 s12, s14, s20
	s_addc_u32 s13, s15, s21
	s_add_u32 s12, s12, s22
	s_addc_u32 s13, s13, 0
	v_mul_u32_u24_e32 v188, 0x2400, v129
	v_and_b32_e32 v189, 15, v128
	v_mul_u32_u24_e32 v189, 0x90, v189
	v_add_u32_e32 v130, v188, v189
	v_lshrrev_b32_e32 v189, 4, v128
	v_lshl_add_u32 v130, v189, 4, v130
	v_lshrrev_b32_e32 v189, 3, v128
	v_mul_u32_u24_e32 v132, 0x90, v189
	v_add_u32_e32 v131, v188, v132
	v_and_b32_e32 v188, 7, v128
	v_lshlrev_b32_e32 v188, 4, v188
	v_add_u32_e32 v131, v131, v188
	v_lshl_add_u32 v189, v129, 6, v189
	v_add_u32_e32 v132, 0, v189
	v_add_u32_e32 v133, 8, v189
	v_add_u32_e32 v134, 16, v189
	v_add_u32_e32 v135, 24, v189
	v_add_u32_e32 v136, 32, v189
	v_add_u32_e32 v137, 40, v189
	v_add_u32_e32 v138, 48, v189
	v_add_u32_e32 v139, 56, v189
	v_mul_lo_u32 v132, v132, s18
	v_mul_lo_u32 v133, v133, s18
	v_mul_lo_u32 v134, v134, s18
	v_mul_lo_u32 v135, v135, s18
	v_mul_lo_u32 v136, v136, s18
	v_mul_lo_u32 v137, v137, s18
	v_mul_lo_u32 v138, v138, s18
	v_mul_lo_u32 v139, v139, s18
	v_add_u32_e32 v132, v132, v188
	v_add_u32_e32 v133, v133, v188
	v_add_u32_e32 v134, v134, v188
	v_add_u32_e32 v135, v135, v188
	v_add_u32_e32 v136, v136, v188
	v_add_u32_e32 v137, v137, v188
	v_add_u32_e32 v138, v138, v188
	v_add_u32_e32 v139, v139, v188
	v_cvt_pk_bf16_f32 v140, v16, v17
	v_cvt_pk_bf16_f32 v141, v18, v19
	v_cvt_pk_bf16_f32 v142, v20, v21
	v_cvt_pk_bf16_f32 v143, v22, v23
	ds_write_b128 v130, v[140:143]
	v_cvt_pk_bf16_f32 v144, v112, v113
	v_cvt_pk_bf16_f32 v145, v114, v115
	v_cvt_pk_bf16_f32 v146, v116, v117
	v_cvt_pk_bf16_f32 v147, v118, v119
	ds_write_b128 v130, v[144:147] offset:64
	v_cvt_pk_bf16_f32 v140, v24, v25
	v_cvt_pk_bf16_f32 v141, v26, v27
	v_cvt_pk_bf16_f32 v142, v28, v29
	v_cvt_pk_bf16_f32 v143, v30, v31
	ds_write_b128 v130, v[140:143] offset:2304
	v_cvt_pk_bf16_f32 v144, v120, v121
	v_cvt_pk_bf16_f32 v145, v122, v123
	v_cvt_pk_bf16_f32 v146, v124, v125
	v_cvt_pk_bf16_f32 v147, v126, v127
	ds_write_b128 v130, v[144:147] offset:2368
	v_cvt_pk_bf16_f32 v140, v0, v1
	v_cvt_pk_bf16_f32 v141, v2, v3
	v_cvt_pk_bf16_f32 v142, v4, v5
	v_cvt_pk_bf16_f32 v143, v6, v7
	ds_write_b128 v130, v[140:143] offset:4608
	v_cvt_pk_bf16_f32 v144, v96, v97
	v_cvt_pk_bf16_f32 v145, v98, v99
	v_cvt_pk_bf16_f32 v146, v100, v101
	v_cvt_pk_bf16_f32 v147, v102, v103
	ds_write_b128 v130, v[144:147] offset:4672
	v_cvt_pk_bf16_f32 v140, v8, v9
	v_cvt_pk_bf16_f32 v141, v10, v11
	v_cvt_pk_bf16_f32 v142, v12, v13
	v_cvt_pk_bf16_f32 v143, v14, v15
	ds_write_b128 v130, v[140:143] offset:6912
	v_cvt_pk_bf16_f32 v144, v104, v105
	v_cvt_pk_bf16_f32 v145, v106, v107
	v_cvt_pk_bf16_f32 v146, v108, v109
	v_cvt_pk_bf16_f32 v147, v110, v111
	ds_write_b128 v130, v[144:147] offset:6976
	s_waitcnt lgkmcnt(0)
	ds_read_b128 v[148:151], v131
	ds_read_b128 v[152:155], v131 offset:1152
	ds_read_b128 v[156:159], v131 offset:2304
	ds_read_b128 v[160:163], v131 offset:3456
	ds_read_b128 v[164:167], v131 offset:4608
	ds_read_b128 v[168:171], v131 offset:5760
	ds_read_b128 v[172:175], v131 offset:6912
	ds_read_b128 v[184:187], v131 offset:8064
	s_waitcnt lgkmcnt(7)
	global_store_dwordx4 v132, v[148:151], s[12:13] sc0 sc1
	s_waitcnt lgkmcnt(6)
	global_store_dwordx4 v133, v[152:155], s[12:13] sc0 sc1
	s_waitcnt lgkmcnt(5)
	global_store_dwordx4 v134, v[156:159], s[12:13] sc0 sc1
	s_waitcnt lgkmcnt(4)
	global_store_dwordx4 v135, v[160:163], s[12:13] sc0 sc1
	s_waitcnt lgkmcnt(3)
	global_store_dwordx4 v136, v[164:167], s[12:13] sc0 sc1
	s_waitcnt lgkmcnt(2)
	global_store_dwordx4 v137, v[168:171], s[12:13] sc0 sc1
	s_waitcnt lgkmcnt(1)
	global_store_dwordx4 v138, v[172:175], s[12:13] sc0 sc1
	s_waitcnt lgkmcnt(0)
	global_store_dwordx4 v139, v[184:187], s[12:13] sc0 sc1
	v_cvt_pk_bf16_f32 v140, v80, v81
	v_cvt_pk_bf16_f32 v141, v82, v83
	v_cvt_pk_bf16_f32 v142, v84, v85
	v_cvt_pk_bf16_f32 v143, v86, v87
	ds_write_b128 v130, v[140:143]
	v_cvt_pk_bf16_f32 v144, v64, v65
	v_cvt_pk_bf16_f32 v145, v66, v67
	v_cvt_pk_bf16_f32 v146, v68, v69
	v_cvt_pk_bf16_f32 v147, v70, v71
	ds_write_b128 v130, v[144:147] offset:64
	v_cvt_pk_bf16_f32 v140, v88, v89
	v_cvt_pk_bf16_f32 v141, v90, v91
	v_cvt_pk_bf16_f32 v142, v92, v93
	v_cvt_pk_bf16_f32 v143, v94, v95
	ds_write_b128 v130, v[140:143] offset:2304
	v_cvt_pk_bf16_f32 v144, v72, v73
	v_cvt_pk_bf16_f32 v145, v74, v75
	v_cvt_pk_bf16_f32 v146, v76, v77
	v_cvt_pk_bf16_f32 v147, v78, v79
	ds_write_b128 v130, v[144:147] offset:2368
	v_cvt_pk_bf16_f32 v140, v48, v49
	v_cvt_pk_bf16_f32 v141, v50, v51
	v_cvt_pk_bf16_f32 v142, v52, v53
	v_cvt_pk_bf16_f32 v143, v54, v55
	ds_write_b128 v130, v[140:143] offset:4608
	v_cvt_pk_bf16_f32 v144, v32, v33
	v_cvt_pk_bf16_f32 v145, v34, v35
	v_cvt_pk_bf16_f32 v146, v36, v37
	v_cvt_pk_bf16_f32 v147, v38, v39
	ds_write_b128 v130, v[144:147] offset:4672
	v_cvt_pk_bf16_f32 v140, v56, v57
	v_cvt_pk_bf16_f32 v141, v58, v59
	v_cvt_pk_bf16_f32 v142, v60, v61
	v_cvt_pk_bf16_f32 v143, v62, v63
	ds_write_b128 v130, v[140:143] offset:6912
	v_cvt_pk_bf16_f32 v144, v40, v41
	v_cvt_pk_bf16_f32 v145, v42, v43
	v_cvt_pk_bf16_f32 v146, v44, v45
	v_cvt_pk_bf16_f32 v147, v46, v47
	ds_write_b128 v130, v[144:147] offset:6976
	s_waitcnt lgkmcnt(0)
	ds_read_b128 v[148:151], v131
	ds_read_b128 v[152:155], v131 offset:1152
	ds_read_b128 v[156:159], v131 offset:2304
	ds_read_b128 v[160:163], v131 offset:3456
	ds_read_b128 v[164:167], v131 offset:4608
	ds_read_b128 v[168:171], v131 offset:5760
	ds_read_b128 v[172:175], v131 offset:6912
	ds_read_b128 v[184:187], v131 offset:8064
	s_waitcnt lgkmcnt(7)
	global_store_dwordx4 v132, v[148:151], s[12:13] offset:128 sc0 sc1
	s_waitcnt lgkmcnt(6)
	global_store_dwordx4 v133, v[152:155], s[12:13] offset:128 sc0 sc1
	s_waitcnt lgkmcnt(5)
	global_store_dwordx4 v134, v[156:159], s[12:13] offset:128 sc0 sc1
	s_waitcnt lgkmcnt(4)
	global_store_dwordx4 v135, v[160:163], s[12:13] offset:128 sc0 sc1
	s_waitcnt lgkmcnt(3)
	global_store_dwordx4 v136, v[164:167], s[12:13] offset:128 sc0 sc1
	s_waitcnt lgkmcnt(2)
	global_store_dwordx4 v137, v[168:171], s[12:13] offset:128 sc0 sc1
	s_waitcnt lgkmcnt(1)
	global_store_dwordx4 v138, v[172:175], s[12:13] offset:128 sc0 sc1
	s_waitcnt lgkmcnt(0)
	global_store_dwordx4 v139, v[184:187], s[12:13] offset:128 sc0 sc1
	s_branch .Lpe_proj_end
.Lpe_proj_ab:
	v_readlane_b32 s14, v254, 19
	v_readlane_b32 s15, v254, 20
	s_mul_i32 s20, s20, 0x60
	s_add_u32 s12, s14, s20
	s_addc_u32 s13, s15, 0
	v_and_b32_e32 v189, 15, v128
	v_lshl_add_u32 v189, v129, 6, v189
	v_mul_u32_u24_e32 v189, 0x60, v189
	v_lshrrev_b32_e32 v188, 4, v128
	v_lshl_add_u32 v189, v188, 5, v189
	v_cmp_gt_u32_e32 vcc, 48, v128
	s_and_saveexec_b64 s[14:15], vcc
	global_store_dwordx4 v189, v[16:19], s[12:13] sc0 sc1
	global_store_dwordx4 v189, v[20:23], s[12:13] offset:16 sc0 sc1
	global_store_dwordx4 v189, v[24:27], s[12:13] offset:1536 sc0 sc1
	global_store_dwordx4 v189, v[28:31], s[12:13] offset:1552 sc0 sc1
	s_add_u32 s12, s12, 0xc00
	s_addc_u32 s13, s13, 0
	global_store_dwordx4 v189, v[0:3], s[12:13] sc0 sc1
	global_store_dwordx4 v189, v[4:7], s[12:13] offset:16 sc0 sc1
	global_store_dwordx4 v189, v[8:11], s[12:13] offset:1536 sc0 sc1
	global_store_dwordx4 v189, v[12:15], s[12:13] offset:1552 sc0 sc1
	s_mov_b64 exec, s[14:15]

.Lg16_out_k:
	s_add_i32 s9, s3, 2
	s_lshl_b32 s96, s9, 13
	s_add_i32 m0, vcc_lo, 16384
	v_lshl_add_u64 v[160:161], v[188:189], 0, s[96:97]
	global_load_lds_dwordx4 v[160:161], off
	global_load_lds_dwordx4 v[160:161], off offset:1024
	ds_read_b128 v[196:199], v246 offset:0
	ds_read_b128 v[200:203], v162 offset:0
	ds_read_b128 v[204:207], v246 offset:2048
	ds_read_b128 v[242:245], v162 offset:2048
	s_add_i32 s9, s3, 2
	s_lshl_b32 s96, s9, 11
	v_lshl_add_u64 v[248:249], v[184:185], 0, s[96:97]
	v_lshl_add_u64 v[250:251], v[186:187], 0, s[96:97]
	s_waitcnt vmcnt(8) lgkmcnt(3)
	v_mfma_f32_16x16x32_bf16 v[112:115], v[196:199], v[128:131], v[112:115]
	v_mfma_f32_16x16x32_bf16 v[120:123], v[196:199], v[132:135], v[120:123]
	v_mfma_f32_16x16x32_bf16 v[48:51], v[196:199], v[136:139], v[48:51]
	v_mfma_f32_16x16x32_bf16 v[56:59], v[196:199], v[140:143], v[56:59]
	ds_read_b128 v[196:199], v246 offset:4096
	s_waitcnt lgkmcnt(3)
	v_mfma_f32_16x16x32_bf16 v[116:119], v[200:203], v[128:131], v[116:119]
	v_mfma_f32_16x16x32_bf16 v[124:127], v[200:203], v[132:135], v[124:127]
	v_mfma_f32_16x16x32_bf16 v[52:55], v[200:203], v[136:139], v[52:55]
	v_mfma_f32_16x16x32_bf16 v[60:63], v[200:203], v[140:143], v[60:63]
	ds_read_b128 v[200:203], v162 offset:4096
	s_waitcnt lgkmcnt(3)
	v_mfma_f32_16x16x32_bf16 v[96:99], v[204:207], v[128:131], v[96:99]
	v_mfma_f32_16x16x32_bf16 v[104:107], v[204:207], v[132:135], v[104:107]
	v_mfma_f32_16x16x32_bf16 v[32:35], v[204:207], v[136:139], v[32:35]
	v_mfma_f32_16x16x32_bf16 v[40:43], v[204:207], v[140:143], v[40:43]
	ds_read_b128 v[204:207], v246 offset:6144
	s_waitcnt lgkmcnt(3)
	v_mfma_f32_16x16x32_bf16 v[100:103], v[242:245], v[128:131], v[100:103]
	v_mfma_f32_16x16x32_bf16 v[108:111], v[242:245], v[132:135], v[108:111]
	v_mfma_f32_16x16x32_bf16 v[36:39], v[242:245], v[136:139], v[36:39]
	v_mfma_f32_16x16x32_bf16 v[44:47], v[242:245], v[140:143], v[44:47]
	ds_read_b128 v[242:245], v162 offset:6144
	s_waitcnt lgkmcnt(3)
	v_mfma_f32_16x16x32_bf16 v[80:83], v[196:199], v[128:131], v[80:83]
	v_mfma_f32_16x16x32_bf16 v[88:91], v[196:199], v[132:135], v[88:91]
	v_mfma_f32_16x16x32_bf16 v[16:19], v[196:199], v[136:139], v[16:19]
	v_mfma_f32_16x16x32_bf16 v[24:27], v[196:199], v[140:143], v[24:27]
	s_waitcnt lgkmcnt(2)
	v_mfma_f32_16x16x32_bf16 v[84:87], v[200:203], v[128:131], v[84:87]
	v_mfma_f32_16x16x32_bf16 v[92:95], v[200:203], v[132:135], v[92:95]
	v_mfma_f32_16x16x32_bf16 v[20:23], v[200:203], v[136:139], v[20:23]
	v_mfma_f32_16x16x32_bf16 v[28:31], v[200:203], v[140:143], v[28:31]
	s_waitcnt lgkmcnt(1)
	v_mfma_f32_16x16x32_bf16 v[64:67], v[204:207], v[128:131], v[64:67]
	v_mfma_f32_16x16x32_bf16 v[72:75], v[204:207], v[132:135], v[72:75]
	v_mfma_f32_16x16x32_bf16 v[0:3], v[204:207], v[136:139], v[0:3]
	v_mfma_f32_16x16x32_bf16 v[8:11], v[204:207], v[140:143], v[8:11]
	s_waitcnt lgkmcnt(0)
	v_mfma_f32_16x16x32_bf16 v[68:71], v[242:245], v[128:131], v[68:71]
	v_mfma_f32_16x16x32_bf16 v[76:79], v[242:245], v[132:135], v[76:79]
	v_mfma_f32_16x16x32_bf16 v[4:7], v[242:245], v[136:139], v[4:7]
	v_mfma_f32_16x16x32_bf16 v[12:15], v[242:245], v[140:143], v[12:15]
	global_load_dwordx4 v[128:131], v[248:249], off
	global_load_dwordx4 v[132:135], v[248:249], off offset:256
	global_load_dwordx4 v[136:139], v[250:251], off
	global_load_dwordx4 v[140:143], v[250:251], off offset:256
	s_waitcnt vmcnt(10)
	s_barrier
	s_add_i32 s9, s3, 3
	s_lshl_b32 s96, s9, 13
	s_mov_b32 m0, vcc_lo
	v_lshl_add_u64 v[160:161], v[188:189], 0, s[96:97]
	global_load_lds_dwordx4 v[160:161], off
	global_load_lds_dwordx4 v[160:161], off offset:1024
	ds_read_b128 v[196:199], v246 offset:8192
	ds_read_b128 v[200:203], v162 offset:8192
	ds_read_b128 v[204:207], v246 offset:10240
	ds_read_b128 v[242:245], v162 offset:10240
	s_add_i32 s9, s3, 3
	s_lshl_b32 s96, s9, 11
	v_lshl_add_u64 v[248:249], v[184:185], 0, s[96:97]
	v_lshl_add_u64 v[250:251], v[186:187], 0, s[96:97]
	s_waitcnt vmcnt(8) lgkmcnt(3)
	v_mfma_f32_16x16x32_bf16 v[112:115], v[196:199], v[144:147], v[112:115]
	v_mfma_f32_16x16x32_bf16 v[120:123], v[196:199], v[148:151], v[120:123]
	v_mfma_f32_16x16x32_bf16 v[48:51], v[196:199], v[152:155], v[48:51]
	v_mfma_f32_16x16x32_bf16 v[56:59], v[196:199], v[156:159], v[56:59]
	ds_read_b128 v[196:199], v246 offset:12288
	s_waitcnt lgkmcnt(3)
	v_mfma_f32_16x16x32_bf16 v[116:119], v[200:203], v[144:147], v[116:119]
	v_mfma_f32_16x16x32_bf16 v[124:127], v[200:203], v[148:151], v[124:127]
	v_mfma_f32_16x16x32_bf16 v[52:55], v[200:203], v[152:155], v[52:55]
	v_mfma_f32_16x16x32_bf16 v[60:63], v[200:203], v[156:159], v[60:63]
	ds_read_b128 v[200:203], v162 offset:12288
	s_waitcnt lgkmcnt(3)
	v_mfma_f32_16x16x32_bf16 v[96:99], v[204:207], v[144:147], v[96:99]
	v_mfma_f32_16x16x32_bf16 v[104:107], v[204:207], v[148:151], v[104:107]
	v_mfma_f32_16x16x32_bf16 v[32:35], v[204:207], v[152:155], v[32:35]
	v_mfma_f32_16x16x32_bf16 v[40:43], v[204:207], v[156:159], v[40:43]
	ds_read_b128 v[204:207], v246 offset:14336
	s_waitcnt lgkmcnt(3)
	v_mfma_f32_16x16x32_bf16 v[100:103], v[242:245], v[144:147], v[100:103]
	v_mfma_f32_16x16x32_bf16 v[108:111], v[242:245], v[148:151], v[108:111]
	v_mfma_f32_16x16x32_bf16 v[36:39], v[242:245], v[152:155], v[36:39]
	v_mfma_f32_16x16x32_bf16 v[44:47], v[242:245], v[156:159], v[44:47]
	ds_read_b128 v[242:245], v162 offset:14336
	s_waitcnt lgkmcnt(3)
	v_mfma_f32_16x16x32_bf16 v[80:83], v[196:199], v[144:147], v[80:83]
	v_mfma_f32_16x16x32_bf16 v[88:91], v[196:199], v[148:151], v[88:91]
	v_mfma_f32_16x16x32_bf16 v[16:19], v[196:199], v[152:155], v[16:19]
	v_mfma_f32_16x16x32_bf16 v[24:27], v[196:199], v[156:159], v[24:27]
	s_waitcnt lgkmcnt(2)
	v_mfma_f32_16x16x32_bf16 v[84:87], v[200:203], v[144:147], v[84:87]
	v_mfma_f32_16x16x32_bf16 v[92:95], v[200:203], v[148:151], v[92:95]
	v_mfma_f32_16x16x32_bf16 v[20:23], v[200:203], v[152:155], v[20:23]
	v_mfma_f32_16x16x32_bf16 v[28:31], v[200:203], v[156:159], v[28:31]
	s_waitcnt lgkmcnt(1)
	v_mfma_f32_16x16x32_bf16 v[64:67], v[204:207], v[144:147], v[64:67]
	v_mfma_f32_16x16x32_bf16 v[72:75], v[204:207], v[148:151], v[72:75]
	v_mfma_f32_16x16x32_bf16 v[0:3], v[204:207], v[152:155], v[0:3]
	v_mfma_f32_16x16x32_bf16 v[8:11], v[204:207], v[156:159], v[8:11]
	s_waitcnt lgkmcnt(0)
	v_mfma_f32_16x16x32_bf16 v[68:71], v[242:245], v[144:147], v[68:71]
	v_mfma_f32_16x16x32_bf16 v[76:79], v[242:245], v[148:151], v[76:79]
	v_mfma_f32_16x16x32_bf16 v[4:7], v[242:245], v[152:155], v[4:7]
	v_mfma_f32_16x16x32_bf16 v[12:15], v[242:245], v[156:159], v[12:15]
	global_load_dwordx4 v[144:147], v[248:249], off
	global_load_dwordx4 v[148:151], v[248:249], off offset:256
	global_load_dwordx4 v[152:155], v[250:251], off
	global_load_dwordx4 v[156:159], v[250:251], off offset:256
	s_waitcnt vmcnt(10)
	s_barrier
	s_add_i32 s9, s3, 4
	s_lshl_b32 s96, s9, 13
	s_add_i32 m0, vcc_lo, 8192
	v_lshl_add_u64 v[160:161], v[188:189], 0, s[96:97]
	global_load_lds_dwordx4 v[160:161], off
	global_load_lds_dwordx4 v[160:161], off offset:1024
	ds_read_b128 v[196:199], v246 offset:16384
	ds_read_b128 v[200:203], v162 offset:16384
	ds_read_b128 v[204:207], v246 offset:18432
	ds_read_b128 v[242:245], v162 offset:18432
	s_add_i32 s9, s3, 4
	s_lshl_b32 s96, s9, 11
	v_lshl_add_u64 v[248:249], v[184:185], 0, s[96:97]
	v_lshl_add_u64 v[250:251], v[186:187], 0, s[96:97]
	s_waitcnt vmcnt(8) lgkmcnt(3)
	v_mfma_f32_16x16x32_bf16 v[112:115], v[196:199], v[128:131], v[112:115]
	v_mfma_f32_16x16x32_bf16 v[120:123], v[196:199], v[132:135], v[120:123]
	v_mfma_f32_16x16x32_bf16 v[48:51], v[196:199], v[136:139], v[48:51]
	v_mfma_f32_16x16x32_bf16 v[56:59], v[196:199], v[140:143], v[56:59]
	ds_read_b128 v[196:199], v246 offset:20480
	s_waitcnt lgkmcnt(3)
	v_mfma_f32_16x16x32_bf16 v[116:119], v[200:203], v[128:131], v[116:119]
	v_mfma_f32_16x16x32_bf16 v[124:127], v[200:203], v[132:135], v[124:127]
	v_mfma_f32_16x16x32_bf16 v[52:55], v[200:203], v[136:139], v[52:55]
	v_mfma_f32_16x16x32_bf16 v[60:63], v[200:203], v[140:143], v[60:63]
	ds_read_b128 v[200:203], v162 offset:20480
	s_waitcnt lgkmcnt(3)
	v_mfma_f32_16x16x32_bf16 v[96:99], v[204:207], v[128:131], v[96:99]
	v_mfma_f32_16x16x32_bf16 v[104:107], v[204:207], v[132:135], v[104:107]
	v_mfma_f32_16x16x32_bf16 v[32:35], v[204:207], v[136:139], v[32:35]
	v_mfma_f32_16x16x32_bf16 v[40:43], v[204:207], v[140:143], v[40:43]
	ds_read_b128 v[204:207], v246 offset:22528
	s_waitcnt lgkmcnt(3)
	v_mfma_f32_16x16x32_bf16 v[100:103], v[242:245], v[128:131], v[100:103]
	v_mfma_f32_16x16x32_bf16 v[108:111], v[242:245], v[132:135], v[108:111]
	v_mfma_f32_16x16x32_bf16 v[36:39], v[242:245], v[136:139], v[36:39]
	v_mfma_f32_16x16x32_bf16 v[44:47], v[242:245], v[140:143], v[44:47]
	ds_read_b128 v[242:245], v162 offset:22528
	s_waitcnt lgkmcnt(3)
	v_mfma_f32_16x16x32_bf16 v[80:83], v[196:199], v[128:131], v[80:83]
	v_mfma_f32_16x16x32_bf16 v[88:91], v[196:199], v[132:135], v[88:91]
	v_mfma_f32_16x16x32_bf16 v[16:19], v[196:199], v[136:139], v[16:19]
	v_mfma_f32_16x16x32_bf16 v[24:27], v[196:199], v[140:143], v[24:27]
	s_waitcnt lgkmcnt(2)
	v_mfma_f32_16x16x32_bf16 v[84:87], v[200:203], v[128:131], v[84:87]
	v_mfma_f32_16x16x32_bf16 v[92:95], v[200:203], v[132:135], v[92:95]
	v_mfma_f32_16x16x32_bf16 v[20:23], v[200:203], v[136:139], v[20:23]
	v_mfma_f32_16x16x32_bf16 v[28:31], v[200:203], v[140:143], v[28:31]
	s_waitcnt lgkmcnt(1)
	v_mfma_f32_16x16x32_bf16 v[64:67], v[204:207], v[128:131], v[64:67]
	v_mfma_f32_16x16x32_bf16 v[72:75], v[204:207], v[132:135], v[72:75]
	v_mfma_f32_16x16x32_bf16 v[0:3], v[204:207], v[136:139], v[0:3]
	v_mfma_f32_16x16x32_bf16 v[8:11], v[204:207], v[140:143], v[8:11]
	s_waitcnt lgkmcnt(0)
	v_mfma_f32_16x16x32_bf16 v[68:71], v[242:245], v[128:131], v[68:71]
	v_mfma_f32_16x16x32_bf16 v[76:79], v[242:245], v[132:135], v[76:79]
	v_mfma_f32_16x16x32_bf16 v[4:7], v[242:245], v[136:139], v[4:7]
	v_mfma_f32_16x16x32_bf16 v[12:15], v[242:245], v[140:143], v[12:15]
	global_load_dwordx4 v[128:131], v[248:249], off
	global_load_dwordx4 v[132:135], v[248:249], off offset:256
	global_load_dwordx4 v[136:139], v[250:251], off
	global_load_dwordx4 v[140:143], v[250:251], off offset:256
	s_waitcnt vmcnt(10)
	s_barrier
	s_add_i32 s9, s3, 5
	s_lshl_b32 s96, s9, 13
	s_add_i32 m0, vcc_lo, 16384
	v_lshl_add_u64 v[160:161], v[188:189], 0, s[96:97]
	global_load_lds_dwordx4 v[160:161], off
	global_load_lds_dwordx4 v[160:161], off offset:1024
	ds_read_b128 v[196:199], v246 offset:0
	ds_read_b128 v[200:203], v162 offset:0
	ds_read_b128 v[204:207], v246 offset:2048
	ds_read_b128 v[242:245], v162 offset:2048
	s_add_i32 s9, s3, 5
	s_lshl_b32 s96, s9, 11
	v_lshl_add_u64 v[248:249], v[184:185], 0, s[96:97]
	v_lshl_add_u64 v[250:251], v[186:187], 0, s[96:97]
	s_waitcnt vmcnt(8) lgkmcnt(3)
	v_mfma_f32_16x16x32_bf16 v[112:115], v[196:199], v[144:147], v[112:115]
	v_mfma_f32_16x16x32_bf16 v[120:123], v[196:199], v[148:151], v[120:123]
	v_mfma_f32_16x16x32_bf16 v[48:51], v[196:199], v[152:155], v[48:51]
	v_mfma_f32_16x16x32_bf16 v[56:59], v[196:199], v[156:159], v[56:59]
	ds_read_b128 v[196:199], v246 offset:4096
	s_waitcnt lgkmcnt(3)
	v_mfma_f32_16x16x32_bf16 v[116:119], v[200:203], v[144:147], v[116:119]
	v_mfma_f32_16x16x32_bf16 v[124:127], v[200:203], v[148:151], v[124:127]
	v_mfma_f32_16x16x32_bf16 v[52:55], v[200:203], v[152:155], v[52:55]
	v_mfma_f32_16x16x32_bf16 v[60:63], v[200:203], v[156:159], v[60:63]
	ds_read_b128 v[200:203], v162 offset:4096
	s_waitcnt lgkmcnt(3)
	v_mfma_f32_16x16x32_bf16 v[96:99], v[204:207], v[144:147], v[96:99]
	v_mfma_f32_16x16x32_bf16 v[104:107], v[204:207], v[148:151], v[104:107]
	v_mfma_f32_16x16x32_bf16 v[32:35], v[204:207], v[152:155], v[32:35]
	v_mfma_f32_16x16x32_bf16 v[40:43], v[204:207], v[156:159], v[40:43]
	ds_read_b128 v[204:207], v246 offset:6144
	s_waitcnt lgkmcnt(3)
	v_mfma_f32_16x16x32_bf16 v[100:103], v[242:245], v[144:147], v[100:103]
	v_mfma_f32_16x16x32_bf16 v[108:111], v[242:245], v[148:151], v[108:111]
	v_mfma_f32_16x16x32_bf16 v[36:39], v[242:245], v[152:155], v[36:39]
	v_mfma_f32_16x16x32_bf16 v[44:47], v[242:245], v[156:159], v[44:47]
	ds_read_b128 v[242:245], v162 offset:6144
	s_waitcnt lgkmcnt(3)
	v_mfma_f32_16x16x32_bf16 v[80:83], v[196:199], v[144:147], v[80:83]
	v_mfma_f32_16x16x32_bf16 v[88:91], v[196:199], v[148:151], v[88:91]
	v_mfma_f32_16x16x32_bf16 v[16:19], v[196:199], v[152:155], v[16:19]
	v_mfma_f32_16x16x32_bf16 v[24:27], v[196:199], v[156:159], v[24:27]
	s_waitcnt lgkmcnt(2)
	v_mfma_f32_16x16x32_bf16 v[84:87], v[200:203], v[144:147], v[84:87]
	v_mfma_f32_16x16x32_bf16 v[92:95], v[200:203], v[148:151], v[92:95]
	v_mfma_f32_16x16x32_bf16 v[20:23], v[200:203], v[152:155], v[20:23]
	v_mfma_f32_16x16x32_bf16 v[28:31], v[200:203], v[156:159], v[28:31]
	s_waitcnt lgkmcnt(1)
	v_mfma_f32_16x16x32_bf16 v[64:67], v[204:207], v[144:147], v[64:67]
	v_mfma_f32_16x16x32_bf16 v[72:75], v[204:207], v[148:151], v[72:75]
	v_mfma_f32_16x16x32_bf16 v[0:3], v[204:207], v[152:155], v[0:3]
	v_mfma_f32_16x16x32_bf16 v[8:11], v[204:207], v[156:159], v[8:11]
	s_waitcnt lgkmcnt(0)
	v_mfma_f32_16x16x32_bf16 v[68:71], v[242:245], v[144:147], v[68:71]
	v_mfma_f32_16x16x32_bf16 v[76:79], v[242:245], v[148:151], v[76:79]
	v_mfma_f32_16x16x32_bf16 v[4:7], v[242:245], v[152:155], v[4:7]
	v_mfma_f32_16x16x32_bf16 v[12:15], v[242:245], v[156:159], v[12:15]
	global_load_dwordx4 v[144:147], v[248:249], off
	global_load_dwordx4 v[148:151], v[248:249], off offset:256
	global_load_dwordx4 v[152:155], v[250:251], off
	global_load_dwordx4 v[156:159], v[250:251], off offset:256
	s_waitcnt vmcnt(10)
	s_barrier
	s_add_i32 s9, s3, 6
	s_lshl_b32 s96, s9, 13
	s_mov_b32 m0, vcc_lo
	v_lshl_add_u64 v[160:161], v[188:189], 0, s[96:97]
	global_load_lds_dwordx4 v[160:161], off
	global_load_lds_dwordx4 v[160:161], off offset:1024
	ds_read_b128 v[196:199], v246 offset:8192
	ds_read_b128 v[200:203], v162 offset:8192
	ds_read_b128 v[204:207], v246 offset:10240
	ds_read_b128 v[242:245], v162 offset:10240
	s_add_i32 s9, s3, 6
	s_lshl_b32 s96, s9, 11
	v_lshl_add_u64 v[248:249], v[184:185], 0, s[96:97]
	v_lshl_add_u64 v[250:251], v[186:187], 0, s[96:97]
	s_waitcnt vmcnt(8) lgkmcnt(3)
	v_mfma_f32_16x16x32_bf16 v[112:115], v[196:199], v[128:131], v[112:115]
	v_mfma_f32_16x16x32_bf16 v[120:123], v[196:199], v[132:135], v[120:123]
	v_mfma_f32_16x16x32_bf16 v[48:51], v[196:199], v[136:139], v[48:51]
	v_mfma_f32_16x16x32_bf16 v[56:59], v[196:199], v[140:143], v[56:59]
	ds_read_b128 v[196:199], v246 offset:12288
	s_waitcnt lgkmcnt(3)
	v_mfma_f32_16x16x32_bf16 v[116:119], v[200:203], v[128:131], v[116:119]
	v_mfma_f32_16x16x32_bf16 v[124:127], v[200:203], v[132:135], v[124:127]
	v_mfma_f32_16x16x32_bf16 v[52:55], v[200:203], v[136:139], v[52:55]
	v_mfma_f32_16x16x32_bf16 v[60:63], v[200:203], v[140:143], v[60:63]
	ds_read_b128 v[200:203], v162 offset:12288
	s_waitcnt lgkmcnt(3)
	v_mfma_f32_16x16x32_bf16 v[96:99], v[204:207], v[128:131], v[96:99]
	v_mfma_f32_16x16x32_bf16 v[104:107], v[204:207], v[132:135], v[104:107]
	v_mfma_f32_16x16x32_bf16 v[32:35], v[204:207], v[136:139], v[32:35]
	v_mfma_f32_16x16x32_bf16 v[40:43], v[204:207], v[140:143], v[40:43]
	ds_read_b128 v[204:207], v246 offset:14336
	s_waitcnt lgkmcnt(3)
	v_mfma_f32_16x16x32_bf16 v[100:103], v[242:245], v[128:131], v[100:103]
	v_mfma_f32_16x16x32_bf16 v[108:111], v[242:245], v[132:135], v[108:111]
	v_mfma_f32_16x16x32_bf16 v[36:39], v[242:245], v[136:139], v[36:39]
	v_mfma_f32_16x16x32_bf16 v[44:47], v[242:245], v[140:143], v[44:47]
	ds_read_b128 v[242:245], v162 offset:14336
	s_waitcnt lgkmcnt(3)
	v_mfma_f32_16x16x32_bf16 v[80:83], v[196:199], v[128:131], v[80:83]
	v_mfma_f32_16x16x32_bf16 v[88:91], v[196:199], v[132:135], v[88:91]
	v_mfma_f32_16x16x32_bf16 v[16:19], v[196:199], v[136:139], v[16:19]
	v_mfma_f32_16x16x32_bf16 v[24:27], v[196:199], v[140:143], v[24:27]
	s_waitcnt lgkmcnt(2)
	v_mfma_f32_16x16x32_bf16 v[84:87], v[200:203], v[128:131], v[84:87]
	v_mfma_f32_16x16x32_bf16 v[92:95], v[200:203], v[132:135], v[92:95]
	v_mfma_f32_16x16x32_bf16 v[20:23], v[200:203], v[136:139], v[20:23]
	v_mfma_f32_16x16x32_bf16 v[28:31], v[200:203], v[140:143], v[28:31]
	s_waitcnt lgkmcnt(1)
	v_mfma_f32_16x16x32_bf16 v[64:67], v[204:207], v[128:131], v[64:67]
	v_mfma_f32_16x16x32_bf16 v[72:75], v[204:207], v[132:135], v[72:75]
	v_mfma_f32_16x16x32_bf16 v[0:3], v[204:207], v[136:139], v[0:3]
	v_mfma_f32_16x16x32_bf16 v[8:11], v[204:207], v[140:143], v[8:11]
	s_waitcnt lgkmcnt(0)
	v_mfma_f32_16x16x32_bf16 v[68:71], v[242:245], v[128:131], v[68:71]
	v_mfma_f32_16x16x32_bf16 v[76:79], v[242:245], v[132:135], v[76:79]
	v_mfma_f32_16x16x32_bf16 v[4:7], v[242:245], v[136:139], v[4:7]
	v_mfma_f32_16x16x32_bf16 v[12:15], v[242:245], v[140:143], v[12:15]
	global_load_dwordx4 v[128:131], v[248:249], off
	global_load_dwordx4 v[132:135], v[248:249], off offset:256
	global_load_dwordx4 v[136:139], v[250:251], off
	global_load_dwordx4 v[140:143], v[250:251], off offset:256
	s_waitcnt vmcnt(10)
	s_barrier
	s_add_i32 s9, s3, 7
	s_lshl_b32 s96, s9, 13
	s_add_i32 m0, vcc_lo, 8192
	v_lshl_add_u64 v[160:161], v[188:189], 0, s[96:97]
	global_load_lds_dwordx4 v[160:161], off
	global_load_lds_dwordx4 v[160:161], off offset:1024
	ds_read_b128 v[196:199], v246 offset:16384
	ds_read_b128 v[200:203], v162 offset:16384
	ds_read_b128 v[204:207], v246 offset:18432
	ds_read_b128 v[242:245], v162 offset:18432
	s_add_i32 s9, s3, 7
	s_lshl_b32 s96, s9, 11
	v_lshl_add_u64 v[248:249], v[184:185], 0, s[96:97]
	v_lshl_add_u64 v[250:251], v[186:187], 0, s[96:97]
	s_waitcnt vmcnt(8) lgkmcnt(3)
	v_mfma_f32_16x16x32_bf16 v[112:115], v[196:199], v[144:147], v[112:115]
	v_mfma_f32_16x16x32_bf16 v[120:123], v[196:199], v[148:151], v[120:123]
	v_mfma_f32_16x16x32_bf16 v[48:51], v[196:199], v[152:155], v[48:51]
	v_mfma_f32_16x16x32_bf16 v[56:59], v[196:199], v[156:159], v[56:59]
	ds_read_b128 v[196:199], v246 offset:20480
	s_waitcnt lgkmcnt(3)
	v_mfma_f32_16x16x32_bf16 v[116:119], v[200:203], v[144:147], v[116:119]
	v_mfma_f32_16x16x32_bf16 v[124:127], v[200:203], v[148:151], v[124:127]
	v_mfma_f32_16x16x32_bf16 v[52:55], v[200:203], v[152:155], v[52:55]
	v_mfma_f32_16x16x32_bf16 v[60:63], v[200:203], v[156:159], v[60:63]
	ds_read_b128 v[200:203], v162 offset:20480
	s_waitcnt lgkmcnt(3)
	v_mfma_f32_16x16x32_bf16 v[96:99], v[204:207], v[144:147], v[96:99]
	v_mfma_f32_16x16x32_bf16 v[104:107], v[204:207], v[148:151], v[104:107]
	v_mfma_f32_16x16x32_bf16 v[32:35], v[204:207], v[152:155], v[32:35]
	v_mfma_f32_16x16x32_bf16 v[40:43], v[204:207], v[156:159], v[40:43]
	ds_read_b128 v[204:207], v246 offset:22528
	s_waitcnt lgkmcnt(3)
	v_mfma_f32_16x16x32_bf16 v[100:103], v[242:245], v[144:147], v[100:103]
	v_mfma_f32_16x16x32_bf16 v[108:111], v[242:245], v[148:151], v[108:111]
	v_mfma_f32_16x16x32_bf16 v[36:39], v[242:245], v[152:155], v[36:39]
	v_mfma_f32_16x16x32_bf16 v[44:47], v[242:245], v[156:159], v[44:47]
	ds_read_b128 v[242:245], v162 offset:22528
	s_waitcnt lgkmcnt(3)
	v_mfma_f32_16x16x32_bf16 v[80:83], v[196:199], v[144:147], v[80:83]
	v_mfma_f32_16x16x32_bf16 v[88:91], v[196:199], v[148:151], v[88:91]
	v_mfma_f32_16x16x32_bf16 v[16:19], v[196:199], v[152:155], v[16:19]
	v_mfma_f32_16x16x32_bf16 v[24:27], v[196:199], v[156:159], v[24:27]
	s_waitcnt lgkmcnt(2)
	v_mfma_f32_16x16x32_bf16 v[84:87], v[200:203], v[144:147], v[84:87]
	v_mfma_f32_16x16x32_bf16 v[92:95], v[200:203], v[148:151], v[92:95]
	v_mfma_f32_16x16x32_bf16 v[20:23], v[200:203], v[152:155], v[20:23]
	v_mfma_f32_16x16x32_bf16 v[28:31], v[200:203], v[156:159], v[28:31]
	s_waitcnt lgkmcnt(1)
	v_mfma_f32_16x16x32_bf16 v[64:67], v[204:207], v[144:147], v[64:67]
	v_mfma_f32_16x16x32_bf16 v[72:75], v[204:207], v[148:151], v[72:75]
	v_mfma_f32_16x16x32_bf16 v[0:3], v[204:207], v[152:155], v[0:3]
	v_mfma_f32_16x16x32_bf16 v[8:11], v[204:207], v[156:159], v[8:11]
	s_waitcnt lgkmcnt(0)
	v_mfma_f32_16x16x32_bf16 v[68:71], v[242:245], v[144:147], v[68:71]
	v_mfma_f32_16x16x32_bf16 v[76:79], v[242:245], v[148:151], v[76:79]
	v_mfma_f32_16x16x32_bf16 v[4:7], v[242:245], v[152:155], v[4:7]
	v_mfma_f32_16x16x32_bf16 v[12:15], v[242:245], v[156:159], v[12:15]
	global_load_dwordx4 v[144:147], v[248:249], off
	global_load_dwordx4 v[148:151], v[248:249], off offset:256
	global_load_dwordx4 v[152:155], v[250:251], off
	global_load_dwordx4 v[156:159], v[250:251], off offset:256
	s_waitcnt vmcnt(10)
	s_barrier
	s_add_i32 s3, s3, 6
	s_cmp_lt_u32 s3, 30
	s_cbranch_scc1 .Lg16_out_k
	ds_read_b128 v[196:199], v246 offset:0
	ds_read_b128 v[200:203], v162 offset:0
	ds_read_b128 v[204:207], v246 offset:2048
	ds_read_b128 v[242:245], v162 offset:2048
	s_waitcnt vmcnt(6) lgkmcnt(3)
	v_mfma_f32_16x16x32_bf16 v[112:115], v[196:199], v[128:131], v[112:115]
	v_mfma_f32_16x16x32_bf16 v[120:123], v[196:199], v[132:135], v[120:123]
	v_mfma_f32_16x16x32_bf16 v[48:51], v[196:199], v[136:139], v[48:51]
	v_mfma_f32_16x16x32_bf16 v[56:59], v[196:199], v[140:143], v[56:59]
	ds_read_b128 v[196:199], v246 offset:4096
	s_waitcnt lgkmcnt(3)
	v_mfma_f32_16x16x32_bf16 v[116:119], v[200:203], v[128:131], v[116:119]
	v_mfma_f32_16x16x32_bf16 v[124:127], v[200:203], v[132:135], v[124:127]
	v_mfma_f32_16x16x32_bf16 v[52:55], v[200:203], v[136:139], v[52:55]
	v_mfma_f32_16x16x32_bf16 v[60:63], v[200:203], v[140:143], v[60:63]
	ds_read_b128 v[200:203], v162 offset:4096
	s_waitcnt lgkmcnt(3)
	v_mfma_f32_16x16x32_bf16 v[96:99], v[204:207], v[128:131], v[96:99]
	v_mfma_f32_16x16x32_bf16 v[104:107], v[204:207], v[132:135], v[104:107]
	v_mfma_f32_16x16x32_bf16 v[32:35], v[204:207], v[136:139], v[32:35]
	v_mfma_f32_16x16x32_bf16 v[40:43], v[204:207], v[140:143], v[40:43]
	ds_read_b128 v[204:207], v246 offset:6144
	s_waitcnt lgkmcnt(3)
	v_mfma_f32_16x16x32_bf16 v[100:103], v[242:245], v[128:131], v[100:103]
	v_mfma_f32_16x16x32_bf16 v[108:111], v[242:245], v[132:135], v[108:111]
	v_mfma_f32_16x16x32_bf16 v[36:39], v[242:245], v[136:139], v[36:39]
	v_mfma_f32_16x16x32_bf16 v[44:47], v[242:245], v[140:143], v[44:47]
	ds_read_b128 v[242:245], v162 offset:6144
	s_waitcnt lgkmcnt(3)
	v_mfma_f32_16x16x32_bf16 v[80:83], v[196:199], v[128:131], v[80:83]
	v_mfma_f32_16x16x32_bf16 v[88:91], v[196:199], v[132:135], v[88:91]
	v_mfma_f32_16x16x32_bf16 v[16:19], v[196:199], v[136:139], v[16:19]
	v_mfma_f32_16x16x32_bf16 v[24:27], v[196:199], v[140:143], v[24:27]
	s_waitcnt lgkmcnt(2)
	v_mfma_f32_16x16x32_bf16 v[84:87], v[200:203], v[128:131], v[84:87]
	v_mfma_f32_16x16x32_bf16 v[92:95], v[200:203], v[132:135], v[92:95]
	v_mfma_f32_16x16x32_bf16 v[20:23], v[200:203], v[136:139], v[20:23]
	v_mfma_f32_16x16x32_bf16 v[28:31], v[200:203], v[140:143], v[28:31]
	s_waitcnt lgkmcnt(1)
	v_mfma_f32_16x16x32_bf16 v[64:67], v[204:207], v[128:131], v[64:67]
	v_mfma_f32_16x16x32_bf16 v[72:75], v[204:207], v[132:135], v[72:75]
	v_mfma_f32_16x16x32_bf16 v[0:3], v[204:207], v[136:139], v[0:3]
	v_mfma_f32_16x16x32_bf16 v[8:11], v[204:207], v[140:143], v[8:11]
	s_waitcnt lgkmcnt(0)
	v_mfma_f32_16x16x32_bf16 v[68:71], v[242:245], v[128:131], v[68:71]
	v_mfma_f32_16x16x32_bf16 v[76:79], v[242:245], v[132:135], v[76:79]
	v_mfma_f32_16x16x32_bf16 v[4:7], v[242:245], v[136:139], v[4:7]
	v_mfma_f32_16x16x32_bf16 v[12:15], v[242:245], v[140:143], v[12:15]
	s_waitcnt vmcnt(4)
	s_barrier
	ds_read_b128 v[196:199], v246 offset:8192
	ds_read_b128 v[200:203], v162 offset:8192
	ds_read_b128 v[204:207], v246 offset:10240
	ds_read_b128 v[242:245], v162 offset:10240
	s_waitcnt vmcnt(0) lgkmcnt(3)
	v_mfma_f32_16x16x32_bf16 v[112:115], v[196:199], v[144:147], v[112:115]
	v_mfma_f32_16x16x32_bf16 v[120:123], v[196:199], v[148:151], v[120:123]
	v_mfma_f32_16x16x32_bf16 v[48:51], v[196:199], v[152:155], v[48:51]
	v_mfma_f32_16x16x32_bf16 v[56:59], v[196:199], v[156:159], v[56:59]
	ds_read_b128 v[196:199], v246 offset:12288
	s_waitcnt lgkmcnt(3)
	v_mfma_f32_16x16x32_bf16 v[116:119], v[200:203], v[144:147], v[116:119]
	v_mfma_f32_16x16x32_bf16 v[124:127], v[200:203], v[148:151], v[124:127]
	v_mfma_f32_16x16x32_bf16 v[52:55], v[200:203], v[152:155], v[52:55]
	v_mfma_f32_16x16x32_bf16 v[60:63], v[200:203], v[156:159], v[60:63]
	ds_read_b128 v[200:203], v162 offset:12288
	s_waitcnt lgkmcnt(3)
	v_mfma_f32_16x16x32_bf16 v[96:99], v[204:207], v[144:147], v[96:99]
	v_mfma_f32_16x16x32_bf16 v[104:107], v[204:207], v[148:151], v[104:107]
	v_mfma_f32_16x16x32_bf16 v[32:35], v[204:207], v[152:155], v[32:35]
	v_mfma_f32_16x16x32_bf16 v[40:43], v[204:207], v[156:159], v[40:43]
	ds_read_b128 v[204:207], v246 offset:14336
	s_waitcnt lgkmcnt(3)
	v_mfma_f32_16x16x32_bf16 v[100:103], v[242:245], v[144:147], v[100:103]
	v_mfma_f32_16x16x32_bf16 v[108:111], v[242:245], v[148:151], v[108:111]
	v_mfma_f32_16x16x32_bf16 v[36:39], v[242:245], v[152:155], v[36:39]
	v_mfma_f32_16x16x32_bf16 v[44:47], v[242:245], v[156:159], v[44:47]
	ds_read_b128 v[242:245], v162 offset:14336
	s_waitcnt lgkmcnt(3)
	v_mfma_f32_16x16x32_bf16 v[80:83], v[196:199], v[144:147], v[80:83]
	v_mfma_f32_16x16x32_bf16 v[88:91], v[196:199], v[148:151], v[88:91]
	v_mfma_f32_16x16x32_bf16 v[16:19], v[196:199], v[152:155], v[16:19]
	v_mfma_f32_16x16x32_bf16 v[24:27], v[196:199], v[156:159], v[24:27]
	s_waitcnt lgkmcnt(2)
	v_mfma_f32_16x16x32_bf16 v[84:87], v[200:203], v[144:147], v[84:87]
	v_mfma_f32_16x16x32_bf16 v[92:95], v[200:203], v[148:151], v[92:95]
	v_mfma_f32_16x16x32_bf16 v[20:23], v[200:203], v[152:155], v[20:23]
	v_mfma_f32_16x16x32_bf16 v[28:31], v[200:203], v[156:159], v[28:31]
	s_waitcnt lgkmcnt(1)
	v_mfma_f32_16x16x32_bf16 v[64:67], v[204:207], v[144:147], v[64:67]
	v_mfma_f32_16x16x32_bf16 v[72:75], v[204:207], v[148:151], v[72:75]
	v_mfma_f32_16x16x32_bf16 v[0:3], v[204:207], v[152:155], v[0:3]
	v_mfma_f32_16x16x32_bf16 v[8:11], v[204:207], v[156:159], v[8:11]
	s_waitcnt lgkmcnt(0)
	v_mfma_f32_16x16x32_bf16 v[68:71], v[242:245], v[144:147], v[68:71]
	v_mfma_f32_16x16x32_bf16 v[76:79], v[242:245], v[148:151], v[76:79]
	v_mfma_f32_16x16x32_bf16 v[4:7], v[242:245], v[152:155], v[4:7]
	v_mfma_f32_16x16x32_bf16 v[12:15], v[242:245], v[156:159], v[12:15]
	s_barrier
	s_nop 7
	s_nop 1
	s_waitcnt vmcnt(0)
	s_waitcnt vmcnt(0)
	v_and_b32_e32 v188, 63, v179
	v_lshrrev_b32_e32 v189, 6, v179
	v_mul_u32_u24_e32 v249, 0x2400, v189
	v_mov_b32_e32 v250, v249
	v_and_b32_e32 v251, 15, v188
	v_mul_u32_u24_e32 v251, 0x110, v251
	v_add_u32_e32 v249, v249, v251
	v_lshrrev_b32_e32 v251, 4, v188
	v_lshl_add_u32 v249, v251, 5, v249
	v_lshrrev_b32_e32 v237, 4, v188
	v_mul_u32_u24_e32 v251, 0x110, v237
	v_add_u32_e32 v250, v250, v251
	v_and_b32_e32 v251, 15, v188
	v_lshlrev_b32_e32 v251, 4, v251
	v_add_u32_e32 v250, v250, v251
	v_lshl_add_u32 v237, v189, 6, v237
	v_lshl_add_u32 v237, v237, 12, v251
	v_add_u32_e32 v238, 16384, v237
	v_add_u32_e32 v239, 32768, v237
	v_add_u32_e32 v240, 49152, v237
	v_add_u32_e32 v241, 65536, v237
	v_add_u32_e32 v242, 81920, v237
	v_add_u32_e32 v243, 98304, v237
	v_add_u32_e32 v248, 114688, v237
	s_lshl_b32 s16, s8, 8
	s_lshl_b32 s18, s2, 9
	s_lshr_b32 s19, s8, 4
	v_readlane_b32 s12, v254, 38
	v_readlane_b32 s13, v254, 37
	v_readlane_b32 s14, v253, 46
	v_readlane_b32 s15, v253, 47
	v_readlane_b32 s22, v254, 40
	v_readlane_b32 s23, v254, 39
	s_add_i32 s17, s16, 0xffff8000
	s_cmpk_lt_u32 s8, 0x80
	s_cselect_b32 s12, s12, s22
	s_cselect_b32 s13, s13, s23
	s_cselect_b32 s14, s14, s62
	s_cselect_b32 s15, s15, s63
	s_cselect_b32 s19, s19, 8
	s_cselect_b32 s16, s16, s17
	s_mov_b32 s17, 0
	s_lshl_b64 s[16:17], s[16:17], 12
	s_add_u32 s16, s16, s18
	s_addc_u32 s17, s17, 0
	s_add_u32 s12, s12, s16
	s_addc_u32 s13, s13, s17
	s_add_u32 s14, s14, s16
	s_addc_u32 s15, s15, s17
	s_mul_i32 s19, s19, 0x6000
	s_add_u32 s20, s0, s19
	s_addc_u32 s21, s1, 0
	s_add_u32 s20, s20, s18
	s_addc_u32 s21, s21, 0
	global_load_dwordx4 v[244:247], v251, s[20:21]
	global_load_dwordx4 v[160:163], v237, s[12:13]
	global_load_dwordx4 v[164:167], v238, s[12:13]
	global_load_dwordx4 v[168:171], v239, s[12:13]
	global_load_dwordx4 v[172:175], v240, s[12:13]
	global_load_dwordx4 v[196:199], v241, s[12:13]
	global_load_dwordx4 v[200:203], v242, s[12:13]
	global_load_dwordx4 v[204:207], v243, s[12:13]
	global_load_dwordx4 v[184:187], v248, s[12:13]
	ds_write_b128 v249, v[112:115]
	ds_write_b128 v249, v[116:119] offset:16
	ds_write_b128 v249, v[96:99] offset:128
	ds_write_b128 v249, v[100:103] offset:144
	ds_write_b128 v249, v[120:123] offset:4352
	ds_write_b128 v249, v[124:127] offset:4368
	ds_write_b128 v249, v[104:107] offset:4480
	ds_write_b128 v249, v[108:111] offset:4496
	s_waitcnt lgkmcnt(0)
	ds_read_b128 v[128:131], v250
	ds_read_b128 v[132:135], v250 offset:1088
	ds_read_b128 v[136:139], v250 offset:2176
	ds_read_b128 v[140:143], v250 offset:3264
	ds_read_b128 v[144:147], v250 offset:4352
	ds_read_b128 v[148:151], v250 offset:5440
	ds_read_b128 v[152:155], v250 offset:6528
	ds_read_b128 v[156:159], v250 offset:7616
	s_waitcnt vmcnt(7) lgkmcnt(7)
	v_fma_f32 v128, v244, v128, v160
	v_fma_f32 v129, v245, v129, v161
	v_fma_f32 v130, v246, v130, v162
	v_fma_f32 v131, v247, v131, v163
	global_store_dwordx4 v237, v[128:131], s[14:15] sc0 sc1
	s_waitcnt vmcnt(7) lgkmcnt(6)
	v_fma_f32 v132, v244, v132, v164
	v_fma_f32 v133, v245, v133, v165
	v_fma_f32 v134, v246, v134, v166
	v_fma_f32 v135, v247, v135, v167
	global_store_dwordx4 v238, v[132:135], s[14:15] sc0 sc1
	s_waitcnt vmcnt(7) lgkmcnt(5)
	v_fma_f32 v136, v244, v136, v168
	v_fma_f32 v137, v245, v137, v169
	v_fma_f32 v138, v246, v138, v170
	v_fma_f32 v139, v247, v139, v171
	global_store_dwordx4 v239, v[136:139], s[14:15] sc0 sc1
	s_waitcnt vmcnt(7) lgkmcnt(4)
	v_fma_f32 v140, v244, v140, v172
	v_fma_f32 v141, v245, v141, v173
	v_fma_f32 v142, v246, v142, v174
	v_fma_f32 v143, v247, v143, v175
	global_store_dwordx4 v240, v[140:143], s[14:15] sc0 sc1
	s_waitcnt vmcnt(7) lgkmcnt(3)
	v_fma_f32 v144, v244, v144, v196
	v_fma_f32 v145, v245, v145, v197
	v_fma_f32 v146, v246, v146, v198
	v_fma_f32 v147, v247, v147, v199
	global_store_dwordx4 v241, v[144:147], s[14:15] sc0 sc1
	s_waitcnt vmcnt(7) lgkmcnt(2)
	v_fma_f32 v148, v244, v148, v200
	v_fma_f32 v149, v245, v149, v201
	v_fma_f32 v150, v246, v150, v202
	v_fma_f32 v151, v247, v151, v203
	global_store_dwordx4 v242, v[148:151], s[14:15] sc0 sc1
	s_waitcnt vmcnt(7) lgkmcnt(1)
	v_fma_f32 v152, v244, v152, v204
	v_fma_f32 v153, v245, v153, v205
	v_fma_f32 v154, v246, v154, v206
	v_fma_f32 v155, v247, v155, v207
	global_store_dwordx4 v243, v[152:155], s[14:15] sc0 sc1
	s_waitcnt vmcnt(7) lgkmcnt(0)
	v_fma_f32 v156, v244, v156, v184
	v_fma_f32 v157, v245, v157, v185
	v_fma_f32 v158, v246, v158, v186
	v_fma_f32 v159, v247, v159, v187
	global_store_dwordx4 v248, v[156:159], s[14:15] sc0 sc1
	global_load_dwordx4 v[244:247], v251, s[20:21] offset:256
	global_load_dwordx4 v[160:163], v237, s[12:13] offset:256
	global_load_dwordx4 v[164:167], v238, s[12:13] offset:256
	global_load_dwordx4 v[168:171], v239, s[12:13] offset:256
	global_load_dwordx4 v[172:175], v240, s[12:13] offset:256
	global_load_dwordx4 v[196:199], v241, s[12:13] offset:256
	global_load_dwordx4 v[200:203], v242, s[12:13] offset:256
	global_load_dwordx4 v[204:207], v243, s[12:13] offset:256
	global_load_dwordx4 v[184:187], v248, s[12:13] offset:256
	ds_write_b128 v249, v[80:83]
	ds_write_b128 v249, v[84:87] offset:16
	ds_write_b128 v249, v[64:67] offset:128
	ds_write_b128 v249, v[68:71] offset:144
	ds_write_b128 v249, v[88:91] offset:4352
	ds_write_b128 v249, v[92:95] offset:4368
	ds_write_b128 v249, v[72:75] offset:4480
	ds_write_b128 v249, v[76:79] offset:4496
	s_waitcnt lgkmcnt(0)
	ds_read_b128 v[128:131], v250
	ds_read_b128 v[132:135], v250 offset:1088
	ds_read_b128 v[136:139], v250 offset:2176
	ds_read_b128 v[140:143], v250 offset:3264
	ds_read_b128 v[144:147], v250 offset:4352
	ds_read_b128 v[148:151], v250 offset:5440
	ds_read_b128 v[152:155], v250 offset:6528
	ds_read_b128 v[156:159], v250 offset:7616
	s_waitcnt vmcnt(7) lgkmcnt(7)
	v_fma_f32 v128, v244, v128, v160
	v_fma_f32 v129, v245, v129, v161
	v_fma_f32 v130, v246, v130, v162
	v_fma_f32 v131, v247, v131, v163
	global_store_dwordx4 v237, v[128:131], s[14:15] offset:256 sc0 sc1
	s_waitcnt vmcnt(7) lgkmcnt(6)
	v_fma_f32 v132, v244, v132, v164
	v_fma_f32 v133, v245, v133, v165
	v_fma_f32 v134, v246, v134, v166
	v_fma_f32 v135, v247, v135, v167
	global_store_dwordx4 v238, v[132:135], s[14:15] offset:256 sc0 sc1
	s_waitcnt vmcnt(7) lgkmcnt(5)
	v_fma_f32 v136, v244, v136, v168
	v_fma_f32 v137, v245, v137, v169
	v_fma_f32 v138, v246, v138, v170
	v_fma_f32 v139, v247, v139, v171
	global_store_dwordx4 v239, v[136:139], s[14:15] offset:256 sc0 sc1
	s_waitcnt vmcnt(7) lgkmcnt(4)
	v_fma_f32 v140, v244, v140, v172
	v_fma_f32 v141, v245, v141, v173
	v_fma_f32 v142, v246, v142, v174
	v_fma_f32 v143, v247, v143, v175
	global_store_dwordx4 v240, v[140:143], s[14:15] offset:256 sc0 sc1
	s_waitcnt vmcnt(7) lgkmcnt(3)
	v_fma_f32 v144, v244, v144, v196
	v_fma_f32 v145, v245, v145, v197
	v_fma_f32 v146, v246, v146, v198
	v_fma_f32 v147, v247, v147, v199
	global_store_dwordx4 v241, v[144:147], s[14:15] offset:256 sc0 sc1
	s_waitcnt vmcnt(7) lgkmcnt(2)
	v_fma_f32 v148, v244, v148, v200
	v_fma_f32 v149, v245, v149, v201
	v_fma_f32 v150, v246, v150, v202
	v_fma_f32 v151, v247, v151, v203
	global_store_dwordx4 v242, v[148:151], s[14:15] offset:256 sc0 sc1
	s_waitcnt vmcnt(7) lgkmcnt(1)
	v_fma_f32 v152, v244, v152, v204
	v_fma_f32 v153, v245, v153, v205
	v_fma_f32 v154, v246, v154, v206
	v_fma_f32 v155, v247, v155, v207
	global_store_dwordx4 v243, v[152:155], s[14:15] offset:256 sc0 sc1
	s_waitcnt vmcnt(7) lgkmcnt(0)
	v_fma_f32 v156, v244, v156, v184
	v_fma_f32 v157, v245, v157, v185
	v_fma_f32 v158, v246, v158, v186
	v_fma_f32 v159, v247, v159, v187
	global_store_dwordx4 v248, v[156:159], s[14:15] offset:256 sc0 sc1
	s_add_u32 s12, s12, 0x20000
	s_addc_u32 s13, s13, 0
	s_add_u32 s14, s14, 0x20000
	s_addc_u32 s15, s15, 0
	global_load_dwordx4 v[244:247], v251, s[20:21]
	global_load_dwordx4 v[160:163], v237, s[12:13]
	global_load_dwordx4 v[164:167], v238, s[12:13]
	global_load_dwordx4 v[168:171], v239, s[12:13]
	global_load_dwordx4 v[172:175], v240, s[12:13]
	global_load_dwordx4 v[196:199], v241, s[12:13]
	global_load_dwordx4 v[200:203], v242, s[12:13]
	global_load_dwordx4 v[204:207], v243, s[12:13]
	global_load_dwordx4 v[184:187], v248, s[12:13]
	ds_write_b128 v249, v[48:51]
	ds_write_b128 v249, v[52:55] offset:16
	ds_write_b128 v249, v[32:35] offset:128
	ds_write_b128 v249, v[36:39] offset:144
	ds_write_b128 v249, v[56:59] offset:4352
	ds_write_b128 v249, v[60:63] offset:4368
	ds_write_b128 v249, v[40:43] offset:4480
	ds_write_b128 v249, v[44:47] offset:4496
	s_waitcnt lgkmcnt(0)
	ds_read_b128 v[128:131], v250
	ds_read_b128 v[132:135], v250 offset:1088
	ds_read_b128 v[136:139], v250 offset:2176
	ds_read_b128 v[140:143], v250 offset:3264
	ds_read_b128 v[144:147], v250 offset:4352
	ds_read_b128 v[148:151], v250 offset:5440
	ds_read_b128 v[152:155], v250 offset:6528
	ds_read_b128 v[156:159], v250 offset:7616
	s_waitcnt vmcnt(7) lgkmcnt(7)
	v_fma_f32 v128, v244, v128, v160
	v_fma_f32 v129, v245, v129, v161
	v_fma_f32 v130, v246, v130, v162
	v_fma_f32 v131, v247, v131, v163
	global_store_dwordx4 v237, v[128:131], s[14:15] sc0 sc1
	s_waitcnt vmcnt(7) lgkmcnt(6)
	v_fma_f32 v132, v244, v132, v164
	v_fma_f32 v133, v245, v133, v165
	v_fma_f32 v134, v246, v134, v166
	v_fma_f32 v135, v247, v135, v167
	global_store_dwordx4 v238, v[132:135], s[14:15] sc0 sc1
	s_waitcnt vmcnt(7) lgkmcnt(5)
	v_fma_f32 v136, v244, v136, v168
	v_fma_f32 v137, v245, v137, v169
	v_fma_f32 v138, v246, v138, v170
	v_fma_f32 v139, v247, v139, v171
	global_store_dwordx4 v239, v[136:139], s[14:15] sc0 sc1
	s_waitcnt vmcnt(7) lgkmcnt(4)
	v_fma_f32 v140, v244, v140, v172
	v_fma_f32 v141, v245, v141, v173
	v_fma_f32 v142, v246, v142, v174
	v_fma_f32 v143, v247, v143, v175
	global_store_dwordx4 v240, v[140:143], s[14:15] sc0 sc1
	s_waitcnt vmcnt(7) lgkmcnt(3)
	v_fma_f32 v144, v244, v144, v196
	v_fma_f32 v145, v245, v145, v197
	v_fma_f32 v146, v246, v146, v198
	v_fma_f32 v147, v247, v147, v199
	global_store_dwordx4 v241, v[144:147], s[14:15] sc0 sc1
	s_waitcnt vmcnt(7) lgkmcnt(2)
	v_fma_f32 v148, v244, v148, v200
	v_fma_f32 v149, v245, v149, v201
	v_fma_f32 v150, v246, v150, v202
	v_fma_f32 v151, v247, v151, v203
	global_store_dwordx4 v242, v[148:151], s[14:15] sc0 sc1
	s_waitcnt vmcnt(7) lgkmcnt(1)
	v_fma_f32 v152, v244, v152, v204
	v_fma_f32 v153, v245, v153, v205
	v_fma_f32 v154, v246, v154, v206
	v_fma_f32 v155, v247, v155, v207
	global_store_dwordx4 v243, v[152:155], s[14:15] sc0 sc1
	s_waitcnt vmcnt(7) lgkmcnt(0)
	v_fma_f32 v156, v244, v156, v184
	v_fma_f32 v157, v245, v157, v185
	v_fma_f32 v158, v246, v158, v186
	v_fma_f32 v159, v247, v159, v187
	global_store_dwordx4 v248, v[156:159], s[14:15] sc0 sc1
	global_load_dwordx4 v[244:247], v251, s[20:21] offset:256
	global_load_dwordx4 v[160:163], v237, s[12:13] offset:256
	global_load_dwordx4 v[164:167], v238, s[12:13] offset:256
	global_load_dwordx4 v[168:171], v239, s[12:13] offset:256
	global_load_dwordx4 v[172:175], v240, s[12:13] offset:256
	global_load_dwordx4 v[196:199], v241, s[12:13] offset:256
	global_load_dwordx4 v[200:203], v242, s[12:13] offset:256
	global_load_dwordx4 v[204:207], v243, s[12:13] offset:256
	global_load_dwordx4 v[184:187], v248, s[12:13] offset:256
	ds_write_b128 v249, v[16:19]
	ds_write_b128 v249, v[20:23] offset:16
	ds_write_b128 v249, v[0:3] offset:128
	ds_write_b128 v249, v[4:7] offset:144
	ds_write_b128 v249, v[24:27] offset:4352
	ds_write_b128 v249, v[28:31] offset:4368
	ds_write_b128 v249, v[8:11] offset:4480
	ds_write_b128 v249, v[12:15] offset:4496
	s_waitcnt lgkmcnt(0)
	ds_read_b128 v[128:131], v250
	ds_read_b128 v[132:135], v250 offset:1088
	ds_read_b128 v[136:139], v250 offset:2176
	ds_read_b128 v[140:143], v250 offset:3264
	ds_read_b128 v[144:147], v250 offset:4352
	ds_read_b128 v[148:151], v250 offset:5440
	ds_read_b128 v[152:155], v250 offset:6528
	ds_read_b128 v[156:159], v250 offset:7616
	s_waitcnt vmcnt(7) lgkmcnt(7)
	v_fma_f32 v128, v244, v128, v160
	v_fma_f32 v129, v245, v129, v161
	v_fma_f32 v130, v246, v130, v162
	v_fma_f32 v131, v247, v131, v163
	global_store_dwordx4 v237, v[128:131], s[14:15] offset:256 sc0 sc1
	s_waitcnt vmcnt(7) lgkmcnt(6)
	v_fma_f32 v132, v244, v132, v164
	v_fma_f32 v133, v245, v133, v165
	v_fma_f32 v134, v246, v134, v166
	v_fma_f32 v135, v247, v135, v167
	global_store_dwordx4 v238, v[132:135], s[14:15] offset:256 sc0 sc1
	s_waitcnt vmcnt(7) lgkmcnt(5)
	v_fma_f32 v136, v244, v136, v168
	v_fma_f32 v137, v245, v137, v169
	v_fma_f32 v138, v246, v138, v170
	v_fma_f32 v139, v247, v139, v171
	global_store_dwordx4 v239, v[136:139], s[14:15] offset:256 sc0 sc1
	s_waitcnt vmcnt(7) lgkmcnt(4)
	v_fma_f32 v140, v244, v140, v172
	v_fma_f32 v141, v245, v141, v173
	v_fma_f32 v142, v246, v142, v174
	v_fma_f32 v143, v247, v143, v175
	global_store_dwordx4 v240, v[140:143], s[14:15] offset:256 sc0 sc1
	s_waitcnt vmcnt(7) lgkmcnt(3)
	v_fma_f32 v144, v244, v144, v196
	v_fma_f32 v145, v245, v145, v197
	v_fma_f32 v146, v246, v146, v198
	v_fma_f32 v147, v247, v147, v199
	global_store_dwordx4 v241, v[144:147], s[14:15] offset:256 sc0 sc1
	s_waitcnt vmcnt(7) lgkmcnt(2)
	v_fma_f32 v148, v244, v148, v200
	v_fma_f32 v149, v245, v149, v201
	v_fma_f32 v150, v246, v150, v202
	v_fma_f32 v151, v247, v151, v203
	global_store_dwordx4 v242, v[148:151], s[14:15] offset:256 sc0 sc1
	s_waitcnt vmcnt(7) lgkmcnt(1)
	v_fma_f32 v152, v244, v152, v204
	v_fma_f32 v153, v245, v153, v205
	v_fma_f32 v154, v246, v154, v206
	v_fma_f32 v155, v247, v155, v207
	global_store_dwordx4 v243, v[152:155], s[14:15] offset:256 sc0 sc1
	s_waitcnt vmcnt(7) lgkmcnt(0)
	v_fma_f32 v156, v244, v156, v184
	v_fma_f32 v157, v245, v157, v185
	v_fma_f32 v158, v246, v158, v186
	v_fma_f32 v159, v247, v159, v187
	global_store_dwordx4 v248, v[156:159], s[14:15] offset:256 sc0 sc1
	s_waitcnt lgkmcnt(0)
	v_readlane_b32 s16, v254, 11
	s_andn2_b32 s17, s26, 63
	s_add_i32 s4, s4, s16
	s_cmp_lt_i32 s4, s17
	s_cbranch_scc0 .Lhx_out_left
	s_barrier
	s_branch .LBB0_923

.Lre_outh_h0:
	global_load_dwordx4 v[244:247], v251, s[20:21]
	global_load_dwordx4 v[160:163], v237, s[12:13]
	global_load_dwordx4 v[164:167], v238, s[12:13]
	global_load_dwordx4 v[168:171], v239, s[12:13]
	global_load_dwordx4 v[172:175], v240, s[12:13]
	global_load_dwordx4 v[196:199], v241, s[12:13]
	global_load_dwordx4 v[200:203], v242, s[12:13]
	global_load_dwordx4 v[204:207], v243, s[12:13]
	global_load_dwordx4 v[184:187], v248, s[12:13]
	ds_write_b128 v249, v[112:115]
	ds_write_b128 v249, v[116:119] offset:16
	ds_write_b128 v249, v[96:99] offset:128
	ds_write_b128 v249, v[100:103] offset:144
	ds_write_b128 v249, v[120:123] offset:4352
	ds_write_b128 v249, v[124:127] offset:4368
	ds_write_b128 v249, v[104:107] offset:4480
	ds_write_b128 v249, v[108:111] offset:4496
	s_waitcnt lgkmcnt(0)
	ds_read_b128 v[128:131], v250
	ds_read_b128 v[132:135], v250 offset:1088
	ds_read_b128 v[136:139], v250 offset:2176
	ds_read_b128 v[140:143], v250 offset:3264
	ds_read_b128 v[144:147], v250 offset:4352
	ds_read_b128 v[148:151], v250 offset:5440
	ds_read_b128 v[152:155], v250 offset:6528
	ds_read_b128 v[156:159], v250 offset:7616
	s_waitcnt vmcnt(7) lgkmcnt(7)
	v_fma_f32 v128, v244, v128, v160
	v_fma_f32 v129, v245, v129, v161
	v_fma_f32 v130, v246, v130, v162
	v_fma_f32 v131, v247, v131, v163
	global_store_dwordx4 v237, v[128:131], s[14:15] sc0 sc1
	s_waitcnt vmcnt(7) lgkmcnt(6)
	v_fma_f32 v132, v244, v132, v164
	v_fma_f32 v133, v245, v133, v165
	v_fma_f32 v134, v246, v134, v166
	v_fma_f32 v135, v247, v135, v167
	global_store_dwordx4 v238, v[132:135], s[14:15] sc0 sc1
	s_waitcnt vmcnt(7) lgkmcnt(5)
	v_fma_f32 v136, v244, v136, v168
	v_fma_f32 v137, v245, v137, v169
	v_fma_f32 v138, v246, v138, v170
	v_fma_f32 v139, v247, v139, v171
	global_store_dwordx4 v239, v[136:139], s[14:15] sc0 sc1
	s_waitcnt vmcnt(7) lgkmcnt(4)
	v_fma_f32 v140, v244, v140, v172
	v_fma_f32 v141, v245, v141, v173
	v_fma_f32 v142, v246, v142, v174
	v_fma_f32 v143, v247, v143, v175
	global_store_dwordx4 v240, v[140:143], s[14:15] sc0 sc1
	s_waitcnt vmcnt(7) lgkmcnt(3)
	v_fma_f32 v144, v244, v144, v196
	v_fma_f32 v145, v245, v145, v197
	v_fma_f32 v146, v246, v146, v198
	v_fma_f32 v147, v247, v147, v199
	global_store_dwordx4 v241, v[144:147], s[14:15] sc0 sc1
	s_waitcnt vmcnt(7) lgkmcnt(2)
	v_fma_f32 v148, v244, v148, v200
	v_fma_f32 v149, v245, v149, v201
	v_fma_f32 v150, v246, v150, v202
	v_fma_f32 v151, v247, v151, v203
	global_store_dwordx4 v242, v[148:151], s[14:15] sc0 sc1
	s_waitcnt vmcnt(7) lgkmcnt(1)
	v_fma_f32 v152, v244, v152, v204
	v_fma_f32 v153, v245, v153, v205
	v_fma_f32 v154, v246, v154, v206
	v_fma_f32 v155, v247, v155, v207
	global_store_dwordx4 v243, v[152:155], s[14:15] sc0 sc1
	s_waitcnt vmcnt(7) lgkmcnt(0)
	v_fma_f32 v156, v244, v156, v184
	v_fma_f32 v157, v245, v157, v185
	v_fma_f32 v158, v246, v158, v186
	v_fma_f32 v159, v247, v159, v187
	global_store_dwordx4 v248, v[156:159], s[14:15] sc0 sc1
	global_load_dwordx4 v[244:247], v251, s[20:21] offset:256
	global_load_dwordx4 v[160:163], v237, s[12:13] offset:256
	global_load_dwordx4 v[164:167], v238, s[12:13] offset:256
	global_load_dwordx4 v[168:171], v239, s[12:13] offset:256
	global_load_dwordx4 v[172:175], v240, s[12:13] offset:256
	global_load_dwordx4 v[196:199], v241, s[12:13] offset:256
	global_load_dwordx4 v[200:203], v242, s[12:13] offset:256
	global_load_dwordx4 v[204:207], v243, s[12:13] offset:256
	global_load_dwordx4 v[184:187], v248, s[12:13] offset:256
	ds_write_b128 v249, v[80:83]
	ds_write_b128 v249, v[84:87] offset:16
	ds_write_b128 v249, v[64:67] offset:128
	ds_write_b128 v249, v[68:71] offset:144
	ds_write_b128 v249, v[88:91] offset:4352
	ds_write_b128 v249, v[92:95] offset:4368
	ds_write_b128 v249, v[72:75] offset:4480
	ds_write_b128 v249, v[76:79] offset:4496
	s_waitcnt lgkmcnt(0)
	ds_read_b128 v[128:131], v250
	ds_read_b128 v[132:135], v250 offset:1088
	ds_read_b128 v[136:139], v250 offset:2176
	ds_read_b128 v[140:143], v250 offset:3264
	ds_read_b128 v[144:147], v250 offset:4352
	ds_read_b128 v[148:151], v250 offset:5440
	ds_read_b128 v[152:155], v250 offset:6528
	ds_read_b128 v[156:159], v250 offset:7616
	s_waitcnt vmcnt(7) lgkmcnt(7)
	v_fma_f32 v128, v244, v128, v160
	v_fma_f32 v129, v245, v129, v161
	v_fma_f32 v130, v246, v130, v162
	v_fma_f32 v131, v247, v131, v163
	global_store_dwordx4 v237, v[128:131], s[14:15] offset:256 sc0 sc1
	s_waitcnt vmcnt(7) lgkmcnt(6)
	v_fma_f32 v132, v244, v132, v164
	v_fma_f32 v133, v245, v133, v165
	v_fma_f32 v134, v246, v134, v166
	v_fma_f32 v135, v247, v135, v167
	global_store_dwordx4 v238, v[132:135], s[14:15] offset:256 sc0 sc1
	s_waitcnt vmcnt(7) lgkmcnt(5)
	v_fma_f32 v136, v244, v136, v168
	v_fma_f32 v137, v245, v137, v169
	v_fma_f32 v138, v246, v138, v170
	v_fma_f32 v139, v247, v139, v171
	global_store_dwordx4 v239, v[136:139], s[14:15] offset:256 sc0 sc1
	s_waitcnt vmcnt(7) lgkmcnt(4)
	v_fma_f32 v140, v244, v140, v172
	v_fma_f32 v141, v245, v141, v173
	v_fma_f32 v142, v246, v142, v174
	v_fma_f32 v143, v247, v143, v175
	global_store_dwordx4 v240, v[140:143], s[14:15] offset:256 sc0 sc1
	s_waitcnt vmcnt(7) lgkmcnt(3)
	v_fma_f32 v144, v244, v144, v196
	v_fma_f32 v145, v245, v145, v197
	v_fma_f32 v146, v246, v146, v198
	v_fma_f32 v147, v247, v147, v199
	global_store_dwordx4 v241, v[144:147], s[14:15] offset:256 sc0 sc1
	s_waitcnt vmcnt(7) lgkmcnt(2)
	v_fma_f32 v148, v244, v148, v200
	v_fma_f32 v149, v245, v149, v201
	v_fma_f32 v150, v246, v150, v202
	v_fma_f32 v151, v247, v151, v203
	global_store_dwordx4 v242, v[148:151], s[14:15] offset:256 sc0 sc1
	s_waitcnt vmcnt(7) lgkmcnt(1)
	v_fma_f32 v152, v244, v152, v204
	v_fma_f32 v153, v245, v153, v205
	v_fma_f32 v154, v246, v154, v206
	v_fma_f32 v155, v247, v155, v207
	global_store_dwordx4 v243, v[152:155], s[14:15] offset:256 sc0 sc1
	s_waitcnt vmcnt(7) lgkmcnt(0)
	v_fma_f32 v156, v244, v156, v184
	v_fma_f32 v157, v245, v157, v185
	v_fma_f32 v158, v246, v158, v186
	v_fma_f32 v159, v247, v159, v187
	global_store_dwordx4 v248, v[156:159], s[14:15] offset:256 sc0 sc1
	s_waitcnt lgkmcnt(0)
	s_mov_b32 s100, 0
	s_barrier
	s_branch .LBB0_926

.Lg16_gu_k:
	s_add_i32 s8, s1, 2
	s_lshl_b32 s96, s8, 13
	s_add_i32 m0, vcc_lo, 16384
	v_lshl_add_u64 v[160:161], v[188:189], 0, s[96:97]
	global_load_lds_dwordx4 v[160:161], off
	global_load_lds_dwordx4 v[160:161], off offset:1024
	ds_read_b128 v[196:199], v246 offset:0
	ds_read_b128 v[200:203], v162 offset:0
	ds_read_b128 v[204:207], v246 offset:2048
	ds_read_b128 v[242:245], v162 offset:2048
	s_add_i32 s8, s1, 2
	s_lshl_b32 s96, s8, 11
	v_lshl_add_u64 v[248:249], v[184:185], 0, s[96:97]
	v_lshl_add_u64 v[250:251], v[186:187], 0, s[96:97]
	s_waitcnt vmcnt(8) lgkmcnt(3)
	v_mfma_f32_16x16x32_bf16 v[112:115], v[196:199], v[128:131], v[112:115]
	v_mfma_f32_16x16x32_bf16 v[120:123], v[196:199], v[132:135], v[120:123]
	v_mfma_f32_16x16x32_bf16 v[80:83], v[196:199], v[136:139], v[80:83]
	v_mfma_f32_16x16x32_bf16 v[88:91], v[196:199], v[140:143], v[88:91]
	ds_read_b128 v[196:199], v246 offset:4096
	s_waitcnt lgkmcnt(3)
	v_mfma_f32_16x16x32_bf16 v[116:119], v[200:203], v[128:131], v[116:119]
	v_mfma_f32_16x16x32_bf16 v[124:127], v[200:203], v[132:135], v[124:127]
	v_mfma_f32_16x16x32_bf16 v[84:87], v[200:203], v[136:139], v[84:87]
	v_mfma_f32_16x16x32_bf16 v[92:95], v[200:203], v[140:143], v[92:95]
	ds_read_b128 v[200:203], v162 offset:4096
	s_waitcnt lgkmcnt(3)
	v_mfma_f32_16x16x32_bf16 v[96:99], v[204:207], v[128:131], v[96:99]
	v_mfma_f32_16x16x32_bf16 v[104:107], v[204:207], v[132:135], v[104:107]
	v_mfma_f32_16x16x32_bf16 v[64:67], v[204:207], v[136:139], v[64:67]
	v_mfma_f32_16x16x32_bf16 v[72:75], v[204:207], v[140:143], v[72:75]
	ds_read_b128 v[204:207], v246 offset:6144
	s_waitcnt lgkmcnt(3)
	v_mfma_f32_16x16x32_bf16 v[100:103], v[242:245], v[128:131], v[100:103]
	v_mfma_f32_16x16x32_bf16 v[108:111], v[242:245], v[132:135], v[108:111]
	v_mfma_f32_16x16x32_bf16 v[68:71], v[242:245], v[136:139], v[68:71]
	v_mfma_f32_16x16x32_bf16 v[76:79], v[242:245], v[140:143], v[76:79]
	ds_read_b128 v[242:245], v162 offset:6144
	s_waitcnt lgkmcnt(3)
	v_mfma_f32_16x16x32_bf16 v[48:51], v[196:199], v[128:131], v[48:51]
	v_mfma_f32_16x16x32_bf16 v[56:59], v[196:199], v[132:135], v[56:59]
	v_mfma_f32_16x16x32_bf16 v[16:19], v[196:199], v[136:139], v[16:19]
	v_mfma_f32_16x16x32_bf16 v[24:27], v[196:199], v[140:143], v[24:27]
	s_waitcnt lgkmcnt(2)
	v_mfma_f32_16x16x32_bf16 v[52:55], v[200:203], v[128:131], v[52:55]
	v_mfma_f32_16x16x32_bf16 v[60:63], v[200:203], v[132:135], v[60:63]
	v_mfma_f32_16x16x32_bf16 v[20:23], v[200:203], v[136:139], v[20:23]
	v_mfma_f32_16x16x32_bf16 v[28:31], v[200:203], v[140:143], v[28:31]
	s_waitcnt lgkmcnt(1)
	v_mfma_f32_16x16x32_bf16 v[32:35], v[204:207], v[128:131], v[32:35]
	v_mfma_f32_16x16x32_bf16 v[40:43], v[204:207], v[132:135], v[40:43]
	v_mfma_f32_16x16x32_bf16 v[0:3], v[204:207], v[136:139], v[0:3]
	v_mfma_f32_16x16x32_bf16 v[8:11], v[204:207], v[140:143], v[8:11]
	s_waitcnt lgkmcnt(0)
	v_mfma_f32_16x16x32_bf16 v[36:39], v[242:245], v[128:131], v[36:39]
	v_mfma_f32_16x16x32_bf16 v[44:47], v[242:245], v[132:135], v[44:47]
	v_mfma_f32_16x16x32_bf16 v[4:7], v[242:245], v[136:139], v[4:7]
	v_mfma_f32_16x16x32_bf16 v[12:15], v[242:245], v[140:143], v[12:15]
	global_load_dwordx4 v[128:131], v[248:249], off
	global_load_dwordx4 v[132:135], v[248:249], off offset:256
	global_load_dwordx4 v[136:139], v[250:251], off
	global_load_dwordx4 v[140:143], v[250:251], off offset:256
	s_waitcnt vmcnt(10)
	s_barrier
	s_add_i32 s8, s1, 3
	s_lshl_b32 s96, s8, 13
	s_mov_b32 m0, vcc_lo
	v_lshl_add_u64 v[160:161], v[188:189], 0, s[96:97]
	global_load_lds_dwordx4 v[160:161], off
	global_load_lds_dwordx4 v[160:161], off offset:1024
	ds_read_b128 v[196:199], v246 offset:8192
	ds_read_b128 v[200:203], v162 offset:8192
	ds_read_b128 v[204:207], v246 offset:10240
	ds_read_b128 v[242:245], v162 offset:10240
	s_add_i32 s8, s1, 3
	s_lshl_b32 s96, s8, 11
	v_lshl_add_u64 v[248:249], v[184:185], 0, s[96:97]
	v_lshl_add_u64 v[250:251], v[186:187], 0, s[96:97]
	s_waitcnt vmcnt(8) lgkmcnt(3)
	v_mfma_f32_16x16x32_bf16 v[112:115], v[196:199], v[144:147], v[112:115]
	v_mfma_f32_16x16x32_bf16 v[120:123], v[196:199], v[148:151], v[120:123]
	v_mfma_f32_16x16x32_bf16 v[80:83], v[196:199], v[152:155], v[80:83]
	v_mfma_f32_16x16x32_bf16 v[88:91], v[196:199], v[156:159], v[88:91]
	ds_read_b128 v[196:199], v246 offset:12288
	s_waitcnt lgkmcnt(3)
	v_mfma_f32_16x16x32_bf16 v[116:119], v[200:203], v[144:147], v[116:119]
	v_mfma_f32_16x16x32_bf16 v[124:127], v[200:203], v[148:151], v[124:127]
	v_mfma_f32_16x16x32_bf16 v[84:87], v[200:203], v[152:155], v[84:87]
	v_mfma_f32_16x16x32_bf16 v[92:95], v[200:203], v[156:159], v[92:95]
	ds_read_b128 v[200:203], v162 offset:12288
	s_waitcnt lgkmcnt(3)
	v_mfma_f32_16x16x32_bf16 v[96:99], v[204:207], v[144:147], v[96:99]
	v_mfma_f32_16x16x32_bf16 v[104:107], v[204:207], v[148:151], v[104:107]
	v_mfma_f32_16x16x32_bf16 v[64:67], v[204:207], v[152:155], v[64:67]
	v_mfma_f32_16x16x32_bf16 v[72:75], v[204:207], v[156:159], v[72:75]
	ds_read_b128 v[204:207], v246 offset:14336
	s_waitcnt lgkmcnt(3)
	v_mfma_f32_16x16x32_bf16 v[100:103], v[242:245], v[144:147], v[100:103]
	v_mfma_f32_16x16x32_bf16 v[108:111], v[242:245], v[148:151], v[108:111]
	v_mfma_f32_16x16x32_bf16 v[68:71], v[242:245], v[152:155], v[68:71]
	v_mfma_f32_16x16x32_bf16 v[76:79], v[242:245], v[156:159], v[76:79]
	ds_read_b128 v[242:245], v162 offset:14336
	s_waitcnt lgkmcnt(3)
	v_mfma_f32_16x16x32_bf16 v[48:51], v[196:199], v[144:147], v[48:51]
	v_mfma_f32_16x16x32_bf16 v[56:59], v[196:199], v[148:151], v[56:59]
	v_mfma_f32_16x16x32_bf16 v[16:19], v[196:199], v[152:155], v[16:19]
	v_mfma_f32_16x16x32_bf16 v[24:27], v[196:199], v[156:159], v[24:27]
	s_waitcnt lgkmcnt(2)
	v_mfma_f32_16x16x32_bf16 v[52:55], v[200:203], v[144:147], v[52:55]
	v_mfma_f32_16x16x32_bf16 v[60:63], v[200:203], v[148:151], v[60:63]
	v_mfma_f32_16x16x32_bf16 v[20:23], v[200:203], v[152:155], v[20:23]
	v_mfma_f32_16x16x32_bf16 v[28:31], v[200:203], v[156:159], v[28:31]
	s_waitcnt lgkmcnt(1)
	v_mfma_f32_16x16x32_bf16 v[32:35], v[204:207], v[144:147], v[32:35]
	v_mfma_f32_16x16x32_bf16 v[40:43], v[204:207], v[148:151], v[40:43]
	v_mfma_f32_16x16x32_bf16 v[0:3], v[204:207], v[152:155], v[0:3]
	v_mfma_f32_16x16x32_bf16 v[8:11], v[204:207], v[156:159], v[8:11]
	s_waitcnt lgkmcnt(0)
	v_mfma_f32_16x16x32_bf16 v[36:39], v[242:245], v[144:147], v[36:39]
	v_mfma_f32_16x16x32_bf16 v[44:47], v[242:245], v[148:151], v[44:47]
	v_mfma_f32_16x16x32_bf16 v[4:7], v[242:245], v[152:155], v[4:7]
	v_mfma_f32_16x16x32_bf16 v[12:15], v[242:245], v[156:159], v[12:15]
	global_load_dwordx4 v[144:147], v[248:249], off
	global_load_dwordx4 v[148:151], v[248:249], off offset:256
	global_load_dwordx4 v[152:155], v[250:251], off
	global_load_dwordx4 v[156:159], v[250:251], off offset:256
	s_waitcnt vmcnt(10)
	s_barrier
	s_add_i32 s8, s1, 4
	s_lshl_b32 s96, s8, 13
	s_add_i32 m0, vcc_lo, 8192
	v_lshl_add_u64 v[160:161], v[188:189], 0, s[96:97]
	global_load_lds_dwordx4 v[160:161], off
	global_load_lds_dwordx4 v[160:161], off offset:1024
	ds_read_b128 v[196:199], v246 offset:16384
	ds_read_b128 v[200:203], v162 offset:16384
	ds_read_b128 v[204:207], v246 offset:18432
	ds_read_b128 v[242:245], v162 offset:18432
	s_add_i32 s8, s1, 4
	s_lshl_b32 s96, s8, 11
	v_lshl_add_u64 v[248:249], v[184:185], 0, s[96:97]
	v_lshl_add_u64 v[250:251], v[186:187], 0, s[96:97]
	s_waitcnt vmcnt(8) lgkmcnt(3)
	v_mfma_f32_16x16x32_bf16 v[112:115], v[196:199], v[128:131], v[112:115]
	v_mfma_f32_16x16x32_bf16 v[120:123], v[196:199], v[132:135], v[120:123]
	v_mfma_f32_16x16x32_bf16 v[80:83], v[196:199], v[136:139], v[80:83]
	v_mfma_f32_16x16x32_bf16 v[88:91], v[196:199], v[140:143], v[88:91]
	ds_read_b128 v[196:199], v246 offset:20480
	s_waitcnt lgkmcnt(3)
	v_mfma_f32_16x16x32_bf16 v[116:119], v[200:203], v[128:131], v[116:119]
	v_mfma_f32_16x16x32_bf16 v[124:127], v[200:203], v[132:135], v[124:127]
	v_mfma_f32_16x16x32_bf16 v[84:87], v[200:203], v[136:139], v[84:87]
	v_mfma_f32_16x16x32_bf16 v[92:95], v[200:203], v[140:143], v[92:95]
	ds_read_b128 v[200:203], v162 offset:20480
	s_waitcnt lgkmcnt(3)
	v_mfma_f32_16x16x32_bf16 v[96:99], v[204:207], v[128:131], v[96:99]
	v_mfma_f32_16x16x32_bf16 v[104:107], v[204:207], v[132:135], v[104:107]
	v_mfma_f32_16x16x32_bf16 v[64:67], v[204:207], v[136:139], v[64:67]
	v_mfma_f32_16x16x32_bf16 v[72:75], v[204:207], v[140:143], v[72:75]
	ds_read_b128 v[204:207], v246 offset:22528
	s_waitcnt lgkmcnt(3)
	v_mfma_f32_16x16x32_bf16 v[100:103], v[242:245], v[128:131], v[100:103]
	v_mfma_f32_16x16x32_bf16 v[108:111], v[242:245], v[132:135], v[108:111]
	v_mfma_f32_16x16x32_bf16 v[68:71], v[242:245], v[136:139], v[68:71]
	v_mfma_f32_16x16x32_bf16 v[76:79], v[242:245], v[140:143], v[76:79]
	ds_read_b128 v[242:245], v162 offset:22528
	s_waitcnt lgkmcnt(3)
	v_mfma_f32_16x16x32_bf16 v[48:51], v[196:199], v[128:131], v[48:51]
	v_mfma_f32_16x16x32_bf16 v[56:59], v[196:199], v[132:135], v[56:59]
	v_mfma_f32_16x16x32_bf16 v[16:19], v[196:199], v[136:139], v[16:19]
	v_mfma_f32_16x16x32_bf16 v[24:27], v[196:199], v[140:143], v[24:27]
	s_waitcnt lgkmcnt(2)
	v_mfma_f32_16x16x32_bf16 v[52:55], v[200:203], v[128:131], v[52:55]
	v_mfma_f32_16x16x32_bf16 v[60:63], v[200:203], v[132:135], v[60:63]
	v_mfma_f32_16x16x32_bf16 v[20:23], v[200:203], v[136:139], v[20:23]
	v_mfma_f32_16x16x32_bf16 v[28:31], v[200:203], v[140:143], v[28:31]
	s_waitcnt lgkmcnt(1)
	v_mfma_f32_16x16x32_bf16 v[32:35], v[204:207], v[128:131], v[32:35]
	v_mfma_f32_16x16x32_bf16 v[40:43], v[204:207], v[132:135], v[40:43]
	v_mfma_f32_16x16x32_bf16 v[0:3], v[204:207], v[136:139], v[0:3]
	v_mfma_f32_16x16x32_bf16 v[8:11], v[204:207], v[140:143], v[8:11]
	s_waitcnt lgkmcnt(0)
	v_mfma_f32_16x16x32_bf16 v[36:39], v[242:245], v[128:131], v[36:39]
	v_mfma_f32_16x16x32_bf16 v[44:47], v[242:245], v[132:135], v[44:47]
	v_mfma_f32_16x16x32_bf16 v[4:7], v[242:245], v[136:139], v[4:7]
	v_mfma_f32_16x16x32_bf16 v[12:15], v[242:245], v[140:143], v[12:15]
	global_load_dwordx4 v[128:131], v[248:249], off
	global_load_dwordx4 v[132:135], v[248:249], off offset:256
	global_load_dwordx4 v[136:139], v[250:251], off
	global_load_dwordx4 v[140:143], v[250:251], off offset:256
	s_waitcnt vmcnt(10)
	s_barrier
	s_add_i32 s8, s1, 5
	s_lshl_b32 s96, s8, 13
	s_add_i32 m0, vcc_lo, 16384
	v_lshl_add_u64 v[160:161], v[188:189], 0, s[96:97]
	global_load_lds_dwordx4 v[160:161], off
	global_load_lds_dwordx4 v[160:161], off offset:1024
	ds_read_b128 v[196:199], v246 offset:0
	ds_read_b128 v[200:203], v162 offset:0
	ds_read_b128 v[204:207], v246 offset:2048
	ds_read_b128 v[242:245], v162 offset:2048
	s_add_i32 s8, s1, 5
	s_lshl_b32 s96, s8, 11
	v_lshl_add_u64 v[248:249], v[184:185], 0, s[96:97]
	v_lshl_add_u64 v[250:251], v[186:187], 0, s[96:97]
	s_waitcnt vmcnt(8) lgkmcnt(3)
	v_mfma_f32_16x16x32_bf16 v[112:115], v[196:199], v[144:147], v[112:115]
	v_mfma_f32_16x16x32_bf16 v[120:123], v[196:199], v[148:151], v[120:123]
	v_mfma_f32_16x16x32_bf16 v[80:83], v[196:199], v[152:155], v[80:83]
	v_mfma_f32_16x16x32_bf16 v[88:91], v[196:199], v[156:159], v[88:91]
	ds_read_b128 v[196:199], v246 offset:4096
	s_waitcnt lgkmcnt(3)
	v_mfma_f32_16x16x32_bf16 v[116:119], v[200:203], v[144:147], v[116:119]
	v_mfma_f32_16x16x32_bf16 v[124:127], v[200:203], v[148:151], v[124:127]
	v_mfma_f32_16x16x32_bf16 v[84:87], v[200:203], v[152:155], v[84:87]
	v_mfma_f32_16x16x32_bf16 v[92:95], v[200:203], v[156:159], v[92:95]
	ds_read_b128 v[200:203], v162 offset:4096
	s_waitcnt lgkmcnt(3)
	v_mfma_f32_16x16x32_bf16 v[96:99], v[204:207], v[144:147], v[96:99]
	v_mfma_f32_16x16x32_bf16 v[104:107], v[204:207], v[148:151], v[104:107]
	v_mfma_f32_16x16x32_bf16 v[64:67], v[204:207], v[152:155], v[64:67]
	v_mfma_f32_16x16x32_bf16 v[72:75], v[204:207], v[156:159], v[72:75]
	ds_read_b128 v[204:207], v246 offset:6144
	s_waitcnt lgkmcnt(3)
	v_mfma_f32_16x16x32_bf16 v[100:103], v[242:245], v[144:147], v[100:103]
	v_mfma_f32_16x16x32_bf16 v[108:111], v[242:245], v[148:151], v[108:111]
	v_mfma_f32_16x16x32_bf16 v[68:71], v[242:245], v[152:155], v[68:71]
	v_mfma_f32_16x16x32_bf16 v[76:79], v[242:245], v[156:159], v[76:79]
	ds_read_b128 v[242:245], v162 offset:6144
	s_waitcnt lgkmcnt(3)
	v_mfma_f32_16x16x32_bf16 v[48:51], v[196:199], v[144:147], v[48:51]
	v_mfma_f32_16x16x32_bf16 v[56:59], v[196:199], v[148:151], v[56:59]
	v_mfma_f32_16x16x32_bf16 v[16:19], v[196:199], v[152:155], v[16:19]
	v_mfma_f32_16x16x32_bf16 v[24:27], v[196:199], v[156:159], v[24:27]
	s_waitcnt lgkmcnt(2)
	v_mfma_f32_16x16x32_bf16 v[52:55], v[200:203], v[144:147], v[52:55]
	v_mfma_f32_16x16x32_bf16 v[60:63], v[200:203], v[148:151], v[60:63]
	v_mfma_f32_16x16x32_bf16 v[20:23], v[200:203], v[152:155], v[20:23]
	v_mfma_f32_16x16x32_bf16 v[28:31], v[200:203], v[156:159], v[28:31]
	s_waitcnt lgkmcnt(1)
	v_mfma_f32_16x16x32_bf16 v[32:35], v[204:207], v[144:147], v[32:35]
	v_mfma_f32_16x16x32_bf16 v[40:43], v[204:207], v[148:151], v[40:43]
	v_mfma_f32_16x16x32_bf16 v[0:3], v[204:207], v[152:155], v[0:3]
	v_mfma_f32_16x16x32_bf16 v[8:11], v[204:207], v[156:159], v[8:11]
	s_waitcnt lgkmcnt(0)
	v_mfma_f32_16x16x32_bf16 v[36:39], v[242:245], v[144:147], v[36:39]
	v_mfma_f32_16x16x32_bf16 v[44:47], v[242:245], v[148:151], v[44:47]
	v_mfma_f32_16x16x32_bf16 v[4:7], v[242:245], v[152:155], v[4:7]
	v_mfma_f32_16x16x32_bf16 v[12:15], v[242:245], v[156:159], v[12:15]
	global_load_dwordx4 v[144:147], v[248:249], off
	global_load_dwordx4 v[148:151], v[248:249], off offset:256
	global_load_dwordx4 v[152:155], v[250:251], off
	global_load_dwordx4 v[156:159], v[250:251], off offset:256
	s_waitcnt vmcnt(10)
	s_barrier
	s_add_i32 s8, s1, 6
	s_lshl_b32 s96, s8, 13
	s_mov_b32 m0, vcc_lo
	v_lshl_add_u64 v[160:161], v[188:189], 0, s[96:97]
	global_load_lds_dwordx4 v[160:161], off
	global_load_lds_dwordx4 v[160:161], off offset:1024
	ds_read_b128 v[196:199], v246 offset:8192
	ds_read_b128 v[200:203], v162 offset:8192
	ds_read_b128 v[204:207], v246 offset:10240
	ds_read_b128 v[242:245], v162 offset:10240
	s_add_i32 s8, s1, 6
	s_lshl_b32 s96, s8, 11
	v_lshl_add_u64 v[248:249], v[184:185], 0, s[96:97]
	v_lshl_add_u64 v[250:251], v[186:187], 0, s[96:97]
	s_waitcnt vmcnt(8) lgkmcnt(3)
	v_mfma_f32_16x16x32_bf16 v[112:115], v[196:199], v[128:131], v[112:115]
	v_mfma_f32_16x16x32_bf16 v[120:123], v[196:199], v[132:135], v[120:123]
	v_mfma_f32_16x16x32_bf16 v[80:83], v[196:199], v[136:139], v[80:83]
	v_mfma_f32_16x16x32_bf16 v[88:91], v[196:199], v[140:143], v[88:91]
	ds_read_b128 v[196:199], v246 offset:12288
	s_waitcnt lgkmcnt(3)
	v_mfma_f32_16x16x32_bf16 v[116:119], v[200:203], v[128:131], v[116:119]
	v_mfma_f32_16x16x32_bf16 v[124:127], v[200:203], v[132:135], v[124:127]
	v_mfma_f32_16x16x32_bf16 v[84:87], v[200:203], v[136:139], v[84:87]
	v_mfma_f32_16x16x32_bf16 v[92:95], v[200:203], v[140:143], v[92:95]
	ds_read_b128 v[200:203], v162 offset:12288
	s_waitcnt lgkmcnt(3)
	v_mfma_f32_16x16x32_bf16 v[96:99], v[204:207], v[128:131], v[96:99]
	v_mfma_f32_16x16x32_bf16 v[104:107], v[204:207], v[132:135], v[104:107]
	v_mfma_f32_16x16x32_bf16 v[64:67], v[204:207], v[136:139], v[64:67]
	v_mfma_f32_16x16x32_bf16 v[72:75], v[204:207], v[140:143], v[72:75]
	ds_read_b128 v[204:207], v246 offset:14336
	s_waitcnt lgkmcnt(3)
	v_mfma_f32_16x16x32_bf16 v[100:103], v[242:245], v[128:131], v[100:103]
	v_mfma_f32_16x16x32_bf16 v[108:111], v[242:245], v[132:135], v[108:111]
	v_mfma_f32_16x16x32_bf16 v[68:71], v[242:245], v[136:139], v[68:71]
	v_mfma_f32_16x16x32_bf16 v[76:79], v[242:245], v[140:143], v[76:79]
	ds_read_b128 v[242:245], v162 offset:14336
	s_waitcnt lgkmcnt(3)
	v_mfma_f32_16x16x32_bf16 v[48:51], v[196:199], v[128:131], v[48:51]
	v_mfma_f32_16x16x32_bf16 v[56:59], v[196:199], v[132:135], v[56:59]
	v_mfma_f32_16x16x32_bf16 v[16:19], v[196:199], v[136:139], v[16:19]
	v_mfma_f32_16x16x32_bf16 v[24:27], v[196:199], v[140:143], v[24:27]
	s_waitcnt lgkmcnt(2)
	v_mfma_f32_16x16x32_bf16 v[52:55], v[200:203], v[128:131], v[52:55]
	v_mfma_f32_16x16x32_bf16 v[60:63], v[200:203], v[132:135], v[60:63]
	v_mfma_f32_16x16x32_bf16 v[20:23], v[200:203], v[136:139], v[20:23]
	v_mfma_f32_16x16x32_bf16 v[28:31], v[200:203], v[140:143], v[28:31]
	s_waitcnt lgkmcnt(1)
	v_mfma_f32_16x16x32_bf16 v[32:35], v[204:207], v[128:131], v[32:35]
	v_mfma_f32_16x16x32_bf16 v[40:43], v[204:207], v[132:135], v[40:43]
	v_mfma_f32_16x16x32_bf16 v[0:3], v[204:207], v[136:139], v[0:3]
	v_mfma_f32_16x16x32_bf16 v[8:11], v[204:207], v[140:143], v[8:11]
	s_waitcnt lgkmcnt(0)
	v_mfma_f32_16x16x32_bf16 v[36:39], v[242:245], v[128:131], v[36:39]
	v_mfma_f32_16x16x32_bf16 v[44:47], v[242:245], v[132:135], v[44:47]
	v_mfma_f32_16x16x32_bf16 v[4:7], v[242:245], v[136:139], v[4:7]
	v_mfma_f32_16x16x32_bf16 v[12:15], v[242:245], v[140:143], v[12:15]
	global_load_dwordx4 v[128:131], v[248:249], off
	global_load_dwordx4 v[132:135], v[248:249], off offset:256
	global_load_dwordx4 v[136:139], v[250:251], off
	global_load_dwordx4 v[140:143], v[250:251], off offset:256
	s_waitcnt vmcnt(10)
	s_barrier
	s_add_i32 s8, s1, 7
	s_lshl_b32 s96, s8, 13
	s_add_i32 m0, vcc_lo, 8192
	v_lshl_add_u64 v[160:161], v[188:189], 0, s[96:97]
	global_load_lds_dwordx4 v[160:161], off
	global_load_lds_dwordx4 v[160:161], off offset:1024
	ds_read_b128 v[196:199], v246 offset:16384
	ds_read_b128 v[200:203], v162 offset:16384
	ds_read_b128 v[204:207], v246 offset:18432
	ds_read_b128 v[242:245], v162 offset:18432
	s_add_i32 s8, s1, 7
	s_lshl_b32 s96, s8, 11
	v_lshl_add_u64 v[248:249], v[184:185], 0, s[96:97]
	v_lshl_add_u64 v[250:251], v[186:187], 0, s[96:97]
	s_waitcnt vmcnt(8) lgkmcnt(3)
	v_mfma_f32_16x16x32_bf16 v[112:115], v[196:199], v[144:147], v[112:115]
	v_mfma_f32_16x16x32_bf16 v[120:123], v[196:199], v[148:151], v[120:123]
	v_mfma_f32_16x16x32_bf16 v[80:83], v[196:199], v[152:155], v[80:83]
	v_mfma_f32_16x16x32_bf16 v[88:91], v[196:199], v[156:159], v[88:91]
	ds_read_b128 v[196:199], v246 offset:20480
	s_waitcnt lgkmcnt(3)
	v_mfma_f32_16x16x32_bf16 v[116:119], v[200:203], v[144:147], v[116:119]
	v_mfma_f32_16x16x32_bf16 v[124:127], v[200:203], v[148:151], v[124:127]
	v_mfma_f32_16x16x32_bf16 v[84:87], v[200:203], v[152:155], v[84:87]
	v_mfma_f32_16x16x32_bf16 v[92:95], v[200:203], v[156:159], v[92:95]
	ds_read_b128 v[200:203], v162 offset:20480
	s_waitcnt lgkmcnt(3)
	v_mfma_f32_16x16x32_bf16 v[96:99], v[204:207], v[144:147], v[96:99]
	v_mfma_f32_16x16x32_bf16 v[104:107], v[204:207], v[148:151], v[104:107]
	v_mfma_f32_16x16x32_bf16 v[64:67], v[204:207], v[152:155], v[64:67]
	v_mfma_f32_16x16x32_bf16 v[72:75], v[204:207], v[156:159], v[72:75]
	ds_read_b128 v[204:207], v246 offset:22528
	s_waitcnt lgkmcnt(3)
	v_mfma_f32_16x16x32_bf16 v[100:103], v[242:245], v[144:147], v[100:103]
	v_mfma_f32_16x16x32_bf16 v[108:111], v[242:245], v[148:151], v[108:111]
	v_mfma_f32_16x16x32_bf16 v[68:71], v[242:245], v[152:155], v[68:71]
	v_mfma_f32_16x16x32_bf16 v[76:79], v[242:245], v[156:159], v[76:79]
	ds_read_b128 v[242:245], v162 offset:22528
	s_waitcnt lgkmcnt(3)
	v_mfma_f32_16x16x32_bf16 v[48:51], v[196:199], v[144:147], v[48:51]
	v_mfma_f32_16x16x32_bf16 v[56:59], v[196:199], v[148:151], v[56:59]
	v_mfma_f32_16x16x32_bf16 v[16:19], v[196:199], v[152:155], v[16:19]
	v_mfma_f32_16x16x32_bf16 v[24:27], v[196:199], v[156:159], v[24:27]
	s_waitcnt lgkmcnt(2)
	v_mfma_f32_16x16x32_bf16 v[52:55], v[200:203], v[144:147], v[52:55]
	v_mfma_f32_16x16x32_bf16 v[60:63], v[200:203], v[148:151], v[60:63]
	v_mfma_f32_16x16x32_bf16 v[20:23], v[200:203], v[152:155], v[20:23]
	v_mfma_f32_16x16x32_bf16 v[28:31], v[200:203], v[156:159], v[28:31]
	s_waitcnt lgkmcnt(1)
	v_mfma_f32_16x16x32_bf16 v[32:35], v[204:207], v[144:147], v[32:35]
	v_mfma_f32_16x16x32_bf16 v[40:43], v[204:207], v[148:151], v[40:43]
	v_mfma_f32_16x16x32_bf16 v[0:3], v[204:207], v[152:155], v[0:3]
	v_mfma_f32_16x16x32_bf16 v[8:11], v[204:207], v[156:159], v[8:11]
	s_waitcnt lgkmcnt(0)
	v_mfma_f32_16x16x32_bf16 v[36:39], v[242:245], v[144:147], v[36:39]
	v_mfma_f32_16x16x32_bf16 v[44:47], v[242:245], v[148:151], v[44:47]
	v_mfma_f32_16x16x32_bf16 v[4:7], v[242:245], v[152:155], v[4:7]
	v_mfma_f32_16x16x32_bf16 v[12:15], v[242:245], v[156:159], v[12:15]
	global_load_dwordx4 v[144:147], v[248:249], off
	global_load_dwordx4 v[148:151], v[248:249], off offset:256
	global_load_dwordx4 v[152:155], v[250:251], off
	global_load_dwordx4 v[156:159], v[250:251], off offset:256
	s_waitcnt vmcnt(10)
	s_barrier
	s_add_i32 s1, s1, 6
	s_cmp_lt_u32 s1, 30
	s_cbranch_scc1 .Lg16_gu_k
	ds_read_b128 v[196:199], v246 offset:0
	ds_read_b128 v[200:203], v162 offset:0
	ds_read_b128 v[204:207], v246 offset:2048
	ds_read_b128 v[242:245], v162 offset:2048
	s_waitcnt vmcnt(6) lgkmcnt(3)
	v_mfma_f32_16x16x32_bf16 v[112:115], v[196:199], v[128:131], v[112:115]
	v_mfma_f32_16x16x32_bf16 v[120:123], v[196:199], v[132:135], v[120:123]
	v_mfma_f32_16x16x32_bf16 v[80:83], v[196:199], v[136:139], v[80:83]
	v_mfma_f32_16x16x32_bf16 v[88:91], v[196:199], v[140:143], v[88:91]
	ds_read_b128 v[196:199], v246 offset:4096
	s_waitcnt lgkmcnt(3)
	v_mfma_f32_16x16x32_bf16 v[116:119], v[200:203], v[128:131], v[116:119]
	v_mfma_f32_16x16x32_bf16 v[124:127], v[200:203], v[132:135], v[124:127]
	v_mfma_f32_16x16x32_bf16 v[84:87], v[200:203], v[136:139], v[84:87]
	v_mfma_f32_16x16x32_bf16 v[92:95], v[200:203], v[140:143], v[92:95]
	ds_read_b128 v[200:203], v162 offset:4096
	s_waitcnt lgkmcnt(3)
	v_mfma_f32_16x16x32_bf16 v[96:99], v[204:207], v[128:131], v[96:99]
	v_mfma_f32_16x16x32_bf16 v[104:107], v[204:207], v[132:135], v[104:107]
	v_mfma_f32_16x16x32_bf16 v[64:67], v[204:207], v[136:139], v[64:67]
	v_mfma_f32_16x16x32_bf16 v[72:75], v[204:207], v[140:143], v[72:75]
	ds_read_b128 v[204:207], v246 offset:6144
	s_waitcnt lgkmcnt(3)
	v_mfma_f32_16x16x32_bf16 v[100:103], v[242:245], v[128:131], v[100:103]
	v_mfma_f32_16x16x32_bf16 v[108:111], v[242:245], v[132:135], v[108:111]
	v_mfma_f32_16x16x32_bf16 v[68:71], v[242:245], v[136:139], v[68:71]
	v_mfma_f32_16x16x32_bf16 v[76:79], v[242:245], v[140:143], v[76:79]
	ds_read_b128 v[242:245], v162 offset:6144
	s_waitcnt lgkmcnt(3)
	v_mfma_f32_16x16x32_bf16 v[48:51], v[196:199], v[128:131], v[48:51]
	v_mfma_f32_16x16x32_bf16 v[56:59], v[196:199], v[132:135], v[56:59]
	v_mfma_f32_16x16x32_bf16 v[16:19], v[196:199], v[136:139], v[16:19]
	v_mfma_f32_16x16x32_bf16 v[24:27], v[196:199], v[140:143], v[24:27]
	s_waitcnt lgkmcnt(2)
	v_mfma_f32_16x16x32_bf16 v[52:55], v[200:203], v[128:131], v[52:55]
	v_mfma_f32_16x16x32_bf16 v[60:63], v[200:203], v[132:135], v[60:63]
	v_mfma_f32_16x16x32_bf16 v[20:23], v[200:203], v[136:139], v[20:23]
	v_mfma_f32_16x16x32_bf16 v[28:31], v[200:203], v[140:143], v[28:31]
	s_waitcnt lgkmcnt(1)
	v_mfma_f32_16x16x32_bf16 v[32:35], v[204:207], v[128:131], v[32:35]
	v_mfma_f32_16x16x32_bf16 v[40:43], v[204:207], v[132:135], v[40:43]
	v_mfma_f32_16x16x32_bf16 v[0:3], v[204:207], v[136:139], v[0:3]
	v_mfma_f32_16x16x32_bf16 v[8:11], v[204:207], v[140:143], v[8:11]
	s_waitcnt lgkmcnt(0)
	v_mfma_f32_16x16x32_bf16 v[36:39], v[242:245], v[128:131], v[36:39]
	v_mfma_f32_16x16x32_bf16 v[44:47], v[242:245], v[132:135], v[44:47]
	v_mfma_f32_16x16x32_bf16 v[4:7], v[242:245], v[136:139], v[4:7]
	v_mfma_f32_16x16x32_bf16 v[12:15], v[242:245], v[140:143], v[12:15]
	s_waitcnt vmcnt(4)
	s_barrier
	ds_read_b128 v[196:199], v246 offset:8192
	ds_read_b128 v[200:203], v162 offset:8192
	ds_read_b128 v[204:207], v246 offset:10240
	ds_read_b128 v[242:245], v162 offset:10240
	s_waitcnt vmcnt(0) lgkmcnt(3)
	v_mfma_f32_16x16x32_bf16 v[112:115], v[196:199], v[144:147], v[112:115]
	v_mfma_f32_16x16x32_bf16 v[120:123], v[196:199], v[148:151], v[120:123]
	v_mfma_f32_16x16x32_bf16 v[80:83], v[196:199], v[152:155], v[80:83]
	v_mfma_f32_16x16x32_bf16 v[88:91], v[196:199], v[156:159], v[88:91]
	ds_read_b128 v[196:199], v246 offset:12288
	s_waitcnt lgkmcnt(3)
	v_mfma_f32_16x16x32_bf16 v[116:119], v[200:203], v[144:147], v[116:119]
	v_mfma_f32_16x16x32_bf16 v[124:127], v[200:203], v[148:151], v[124:127]
	v_mfma_f32_16x16x32_bf16 v[84:87], v[200:203], v[152:155], v[84:87]
	v_mfma_f32_16x16x32_bf16 v[92:95], v[200:203], v[156:159], v[92:95]
	ds_read_b128 v[200:203], v162 offset:12288
	s_waitcnt lgkmcnt(3)
	v_mfma_f32_16x16x32_bf16 v[96:99], v[204:207], v[144:147], v[96:99]
	v_mfma_f32_16x16x32_bf16 v[104:107], v[204:207], v[148:151], v[104:107]
	v_mfma_f32_16x16x32_bf16 v[64:67], v[204:207], v[152:155], v[64:67]
	v_mfma_f32_16x16x32_bf16 v[72:75], v[204:207], v[156:159], v[72:75]
	ds_read_b128 v[204:207], v246 offset:14336
	s_waitcnt lgkmcnt(3)
	v_mfma_f32_16x16x32_bf16 v[100:103], v[242:245], v[144:147], v[100:103]
	v_mfma_f32_16x16x32_bf16 v[108:111], v[242:245], v[148:151], v[108:111]
	v_mfma_f32_16x16x32_bf16 v[68:71], v[242:245], v[152:155], v[68:71]
	v_mfma_f32_16x16x32_bf16 v[76:79], v[242:245], v[156:159], v[76:79]
	ds_read_b128 v[242:245], v162 offset:14336
	s_waitcnt lgkmcnt(3)
	v_mfma_f32_16x16x32_bf16 v[48:51], v[196:199], v[144:147], v[48:51]
	v_mfma_f32_16x16x32_bf16 v[56:59], v[196:199], v[148:151], v[56:59]
	v_mfma_f32_16x16x32_bf16 v[16:19], v[196:199], v[152:155], v[16:19]
	v_mfma_f32_16x16x32_bf16 v[24:27], v[196:199], v[156:159], v[24:27]
	s_waitcnt lgkmcnt(2)
	v_mfma_f32_16x16x32_bf16 v[52:55], v[200:203], v[144:147], v[52:55]
	v_mfma_f32_16x16x32_bf16 v[60:63], v[200:203], v[148:151], v[60:63]
	v_mfma_f32_16x16x32_bf16 v[20:23], v[200:203], v[152:155], v[20:23]
	v_mfma_f32_16x16x32_bf16 v[28:31], v[200:203], v[156:159], v[28:31]
	s_waitcnt lgkmcnt(1)
	v_mfma_f32_16x16x32_bf16 v[32:35], v[204:207], v[144:147], v[32:35]
	v_mfma_f32_16x16x32_bf16 v[40:43], v[204:207], v[148:151], v[40:43]
	v_mfma_f32_16x16x32_bf16 v[0:3], v[204:207], v[152:155], v[0:3]
	v_mfma_f32_16x16x32_bf16 v[8:11], v[204:207], v[156:159], v[8:11]
	s_waitcnt lgkmcnt(0)
	v_mfma_f32_16x16x32_bf16 v[36:39], v[242:245], v[144:147], v[36:39]
	v_mfma_f32_16x16x32_bf16 v[44:47], v[242:245], v[148:151], v[44:47]
	v_mfma_f32_16x16x32_bf16 v[4:7], v[242:245], v[152:155], v[4:7]
	v_mfma_f32_16x16x32_bf16 v[12:15], v[242:245], v[156:159], v[12:15]
	s_barrier
	s_nop 7
	s_nop 1
	s_waitcnt vmcnt(0)
	v_and_b32_e32 v128, 63, v179
	v_lshrrev_b32_e32 v129, 6, v179
	s_lshl_b32 s14, s7, 3
	s_mul_hi_u32 s15, s14, 0x2c000
	s_mul_i32 s14, s14, 0x2c000
	s_lshl_b32 s16, s0, 12
	s_add_u32 s12, s66, s14
	s_addc_u32 s13, s67, s15
	s_add_u32 s12, s12, s16
	s_addc_u32 s13, s13, 0
	v_and_b32_e32 v130, 15, v128
	v_lshlrev_b32_e32 v132, 4, v130
	v_lshrrev_b32_e32 v130, 4, v128
	v_lshl_add_u32 v132, v130, 9, v132
	v_mul_u32_u24_e32 v130, 0x58000, v129
	v_add_u32_e32 v132, v132, v130
	v_add_u32_e32 v133, 0x2c000, v132
	v_mul_f32_e32 v140, 0xbfb8aa3b, v112
	v_mul_f32_e32 v141, 0xbfb8aa3b, v113
	v_mul_f32_e32 v142, 0xbfb8aa3b, v114
	v_mul_f32_e32 v143, 0xbfb8aa3b, v115
	v_mul_f32_e32 v144, 0xbfb8aa3b, v116
	v_mul_f32_e32 v145, 0xbfb8aa3b, v117
	v_mul_f32_e32 v146, 0xbfb8aa3b, v118
	v_mul_f32_e32 v147, 0xbfb8aa3b, v119
	v_exp_f32_e32 v140, v140
	v_exp_f32_e32 v141, v141
	v_exp_f32_e32 v142, v142
	v_exp_f32_e32 v143, v143
	v_exp_f32_e32 v144, v144
	v_exp_f32_e32 v145, v145
	v_exp_f32_e32 v146, v146
	v_exp_f32_e32 v147, v147
	v_add_f32_e32 v140, 1.0, v140
	v_add_f32_e32 v141, 1.0, v141
	v_add_f32_e32 v142, 1.0, v142
	v_add_f32_e32 v143, 1.0, v143
	v_add_f32_e32 v144, 1.0, v144
	v_add_f32_e32 v145, 1.0, v145
	v_add_f32_e32 v146, 1.0, v146
	v_add_f32_e32 v147, 1.0, v147
	v_rcp_f32_e32 v140, v140
	v_rcp_f32_e32 v141, v141
	v_rcp_f32_e32 v142, v142
	v_rcp_f32_e32 v143, v143
	v_rcp_f32_e32 v144, v144
	v_rcp_f32_e32 v145, v145
	v_rcp_f32_e32 v146, v146
	v_rcp_f32_e32 v147, v147
	v_mul_f32_e32 v140, v112, v140
	v_mul_f32_e32 v141, v113, v141
	v_mul_f32_e32 v142, v114, v142
	v_mul_f32_e32 v143, v115, v143
	v_mul_f32_e32 v144, v116, v144
	v_mul_f32_e32 v145, v117, v145
	v_mul_f32_e32 v146, v118, v146
	v_mul_f32_e32 v147, v119, v147
	v_mul_f32_e32 v140, v96, v140
	v_mul_f32_e32 v141, v97, v141
	v_mul_f32_e32 v142, v98, v142
	v_mul_f32_e32 v143, v99, v143
	v_mul_f32_e32 v144, v100, v144
	v_mul_f32_e32 v145, v101, v145
	v_mul_f32_e32 v146, v102, v146
	v_mul_f32_e32 v147, v103, v147
	v_cvt_pk_bf16_f32 v148, v140, v141
	v_cvt_pk_bf16_f32 v149, v142, v143
	v_cvt_pk_bf16_f32 v150, v144, v145
	v_cvt_pk_bf16_f32 v151, v146, v147
	global_store_dwordx4 v132, v[148:151], s[12:13] sc0 sc1
	v_mul_f32_e32 v140, 0xbfb8aa3b, v120
	v_mul_f32_e32 v141, 0xbfb8aa3b, v121
	v_mul_f32_e32 v142, 0xbfb8aa3b, v122
	v_mul_f32_e32 v143, 0xbfb8aa3b, v123
	v_mul_f32_e32 v144, 0xbfb8aa3b, v124
	v_mul_f32_e32 v145, 0xbfb8aa3b, v125
	v_mul_f32_e32 v146, 0xbfb8aa3b, v126
	v_mul_f32_e32 v147, 0xbfb8aa3b, v127
	v_exp_f32_e32 v140, v140
	v_exp_f32_e32 v141, v141
	v_exp_f32_e32 v142, v142
	v_exp_f32_e32 v143, v143
	v_exp_f32_e32 v144, v144
	v_exp_f32_e32 v145, v145
	v_exp_f32_e32 v146, v146
	v_exp_f32_e32 v147, v147
	v_add_f32_e32 v140, 1.0, v140
	v_add_f32_e32 v141, 1.0, v141
	v_add_f32_e32 v142, 1.0, v142
	v_add_f32_e32 v143, 1.0, v143
	v_add_f32_e32 v144, 1.0, v144
	v_add_f32_e32 v145, 1.0, v145
	v_add_f32_e32 v146, 1.0, v146
	v_add_f32_e32 v147, 1.0, v147
	v_rcp_f32_e32 v140, v140
	v_rcp_f32_e32 v141, v141
	v_rcp_f32_e32 v142, v142
	v_rcp_f32_e32 v143, v143
	v_rcp_f32_e32 v144, v144
	v_rcp_f32_e32 v145, v145
	v_rcp_f32_e32 v146, v146
	v_rcp_f32_e32 v147, v147
	v_mul_f32_e32 v140, v120, v140
	v_mul_f32_e32 v141, v121, v141
	v_mul_f32_e32 v142, v122, v142
	v_mul_f32_e32 v143, v123, v143
	v_mul_f32_e32 v144, v124, v144
	v_mul_f32_e32 v145, v125, v145
	v_mul_f32_e32 v146, v126, v146
	v_mul_f32_e32 v147, v127, v147
	v_mul_f32_e32 v140, v104, v140
	v_mul_f32_e32 v141, v105, v141
	v_mul_f32_e32 v142, v106, v142
	v_mul_f32_e32 v143, v107, v143
	v_mul_f32_e32 v144, v108, v144
	v_mul_f32_e32 v145, v109, v145
	v_mul_f32_e32 v146, v110, v146
	v_mul_f32_e32 v147, v111, v147
	v_cvt_pk_bf16_f32 v152, v140, v141
	v_cvt_pk_bf16_f32 v153, v142, v143
	v_cvt_pk_bf16_f32 v154, v144, v145
	v_cvt_pk_bf16_f32 v155, v146, v147
	global_store_dwordx4 v132, v[152:155], s[12:13] offset:256 sc0 sc1
	v_mul_f32_e32 v140, 0xbfb8aa3b, v80
	v_mul_f32_e32 v141, 0xbfb8aa3b, v81
	v_mul_f32_e32 v142, 0xbfb8aa3b, v82
	v_mul_f32_e32 v143, 0xbfb8aa3b, v83
	v_mul_f32_e32 v144, 0xbfb8aa3b, v84
	v_mul_f32_e32 v145, 0xbfb8aa3b, v85
	v_mul_f32_e32 v146, 0xbfb8aa3b, v86
	v_mul_f32_e32 v147, 0xbfb8aa3b, v87
	v_exp_f32_e32 v140, v140
	v_exp_f32_e32 v141, v141
	v_exp_f32_e32 v142, v142
	v_exp_f32_e32 v143, v143
	v_exp_f32_e32 v144, v144
	v_exp_f32_e32 v145, v145
	v_exp_f32_e32 v146, v146
	v_exp_f32_e32 v147, v147
	v_add_f32_e32 v140, 1.0, v140
	v_add_f32_e32 v141, 1.0, v141
	v_add_f32_e32 v142, 1.0, v142
	v_add_f32_e32 v143, 1.0, v143
	v_add_f32_e32 v144, 1.0, v144
	v_add_f32_e32 v145, 1.0, v145
	v_add_f32_e32 v146, 1.0, v146
	v_add_f32_e32 v147, 1.0, v147
	v_rcp_f32_e32 v140, v140
	v_rcp_f32_e32 v141, v141
	v_rcp_f32_e32 v142, v142
	v_rcp_f32_e32 v143, v143
	v_rcp_f32_e32 v144, v144
	v_rcp_f32_e32 v145, v145
	v_rcp_f32_e32 v146, v146
	v_rcp_f32_e32 v147, v147
	v_mul_f32_e32 v140, v80, v140
	v_mul_f32_e32 v141, v81, v141
	v_mul_f32_e32 v142, v82, v142
	v_mul_f32_e32 v143, v83, v143
	v_mul_f32_e32 v144, v84, v144
	v_mul_f32_e32 v145, v85, v145
	v_mul_f32_e32 v146, v86, v146
	v_mul_f32_e32 v147, v87, v147
	v_mul_f32_e32 v140, v64, v140
	v_mul_f32_e32 v141, v65, v141
	v_mul_f32_e32 v142, v66, v142
	v_mul_f32_e32 v143, v67, v143
	v_mul_f32_e32 v144, v68, v144
	v_mul_f32_e32 v145, v69, v145
	v_mul_f32_e32 v146, v70, v146
	v_mul_f32_e32 v147, v71, v147
	v_cvt_pk_bf16_f32 v156, v140, v141
	v_cvt_pk_bf16_f32 v157, v142, v143
	v_cvt_pk_bf16_f32 v158, v144, v145
	v_cvt_pk_bf16_f32 v159, v146, v147
	global_store_dwordx4 v133, v[156:159], s[12:13] sc0 sc1
	v_mul_f32_e32 v140, 0xbfb8aa3b, v88
	v_mul_f32_e32 v141, 0xbfb8aa3b, v89
	v_mul_f32_e32 v142, 0xbfb8aa3b, v90
	v_mul_f32_e32 v143, 0xbfb8aa3b, v91
	v_mul_f32_e32 v144, 0xbfb8aa3b, v92
	v_mul_f32_e32 v145, 0xbfb8aa3b, v93
	v_mul_f32_e32 v146, 0xbfb8aa3b, v94
	v_mul_f32_e32 v147, 0xbfb8aa3b, v95
	v_exp_f32_e32 v140, v140
	v_exp_f32_e32 v141, v141
	v_exp_f32_e32 v142, v142
	v_exp_f32_e32 v143, v143
	v_exp_f32_e32 v144, v144
	v_exp_f32_e32 v145, v145
	v_exp_f32_e32 v146, v146
	v_exp_f32_e32 v147, v147
	v_add_f32_e32 v140, 1.0, v140
	v_add_f32_e32 v141, 1.0, v141
	v_add_f32_e32 v142, 1.0, v142
	v_add_f32_e32 v143, 1.0, v143
	v_add_f32_e32 v144, 1.0, v144
	v_add_f32_e32 v145, 1.0, v145
	v_add_f32_e32 v146, 1.0, v146
	v_add_f32_e32 v147, 1.0, v147
	v_rcp_f32_e32 v140, v140
	v_rcp_f32_e32 v141, v141
	v_rcp_f32_e32 v142, v142
	v_rcp_f32_e32 v143, v143
	v_rcp_f32_e32 v144, v144
	v_rcp_f32_e32 v145, v145
	v_rcp_f32_e32 v146, v146
	v_rcp_f32_e32 v147, v147
	v_mul_f32_e32 v140, v88, v140
	v_mul_f32_e32 v141, v89, v141
	v_mul_f32_e32 v142, v90, v142
	v_mul_f32_e32 v143, v91, v143
	v_mul_f32_e32 v144, v92, v144
	v_mul_f32_e32 v145, v93, v145
	v_mul_f32_e32 v146, v94, v146
	v_mul_f32_e32 v147, v95, v147
	v_mul_f32_e32 v140, v72, v140
	v_mul_f32_e32 v141, v73, v141
	v_mul_f32_e32 v142, v74, v142
	v_mul_f32_e32 v143, v75, v143
	v_mul_f32_e32 v144, v76, v144
	v_mul_f32_e32 v145, v77, v145
	v_mul_f32_e32 v146, v78, v146
	v_mul_f32_e32 v147, v79, v147
	v_cvt_pk_bf16_f32 v160, v140, v141
	v_cvt_pk_bf16_f32 v161, v142, v143
	v_cvt_pk_bf16_f32 v162, v144, v145
	v_cvt_pk_bf16_f32 v163, v146, v147
	global_store_dwordx4 v133, v[160:163], s[12:13] offset:256 sc0 sc1
	v_mul_f32_e32 v140, 0xbfb8aa3b, v48
	v_mul_f32_e32 v141, 0xbfb8aa3b, v49
	v_mul_f32_e32 v142, 0xbfb8aa3b, v50
	v_mul_f32_e32 v143, 0xbfb8aa3b, v51
	v_mul_f32_e32 v144, 0xbfb8aa3b, v52
	v_mul_f32_e32 v145, 0xbfb8aa3b, v53
	v_mul_f32_e32 v146, 0xbfb8aa3b, v54
	v_mul_f32_e32 v147, 0xbfb8aa3b, v55
	v_exp_f32_e32 v140, v140
	v_exp_f32_e32 v141, v141
	v_exp_f32_e32 v142, v142
	v_exp_f32_e32 v143, v143
	v_exp_f32_e32 v144, v144
	v_exp_f32_e32 v145, v145
	v_exp_f32_e32 v146, v146
	v_exp_f32_e32 v147, v147
	v_add_f32_e32 v140, 1.0, v140
	v_add_f32_e32 v141, 1.0, v141
	v_add_f32_e32 v142, 1.0, v142
	v_add_f32_e32 v143, 1.0, v143
	v_add_f32_e32 v144, 1.0, v144
	v_add_f32_e32 v145, 1.0, v145
	v_add_f32_e32 v146, 1.0, v146
	v_add_f32_e32 v147, 1.0, v147
	v_rcp_f32_e32 v140, v140
	v_rcp_f32_e32 v141, v141
	v_rcp_f32_e32 v142, v142
	v_rcp_f32_e32 v143, v143
	v_rcp_f32_e32 v144, v144
	v_rcp_f32_e32 v145, v145
	v_rcp_f32_e32 v146, v146
	v_rcp_f32_e32 v147, v147
	v_mul_f32_e32 v140, v48, v140
	v_mul_f32_e32 v141, v49, v141
	v_mul_f32_e32 v142, v50, v142
	v_mul_f32_e32 v143, v51, v143
	v_mul_f32_e32 v144, v52, v144
	v_mul_f32_e32 v145, v53, v145
	v_mul_f32_e32 v146, v54, v146
	v_mul_f32_e32 v147, v55, v147
	v_mul_f32_e32 v140, v32, v140
	v_mul_f32_e32 v141, v33, v141
	v_mul_f32_e32 v142, v34, v142
	v_mul_f32_e32 v143, v35, v143
	v_mul_f32_e32 v144, v36, v144
	v_mul_f32_e32 v145, v37, v145
	v_mul_f32_e32 v146, v38, v146
	v_mul_f32_e32 v147, v39, v147
	v_cvt_pk_bf16_f32 v148, v140, v141
	v_cvt_pk_bf16_f32 v149, v142, v143
	v_cvt_pk_bf16_f32 v150, v144, v145
	v_cvt_pk_bf16_f32 v151, v146, v147
	global_store_dwordx4 v132, v[148:151], s[12:13] offset:2048 sc0 sc1
	v_mul_f32_e32 v140, 0xbfb8aa3b, v56
	v_mul_f32_e32 v141, 0xbfb8aa3b, v57
	v_mul_f32_e32 v142, 0xbfb8aa3b, v58
	v_mul_f32_e32 v143, 0xbfb8aa3b, v59
	v_mul_f32_e32 v144, 0xbfb8aa3b, v60
	v_mul_f32_e32 v145, 0xbfb8aa3b, v61
	v_mul_f32_e32 v146, 0xbfb8aa3b, v62
	v_mul_f32_e32 v147, 0xbfb8aa3b, v63
	v_exp_f32_e32 v140, v140
	v_exp_f32_e32 v141, v141
	v_exp_f32_e32 v142, v142
	v_exp_f32_e32 v143, v143
	v_exp_f32_e32 v144, v144
	v_exp_f32_e32 v145, v145
	v_exp_f32_e32 v146, v146
	v_exp_f32_e32 v147, v147
	v_add_f32_e32 v140, 1.0, v140
	v_add_f32_e32 v141, 1.0, v141
	v_add_f32_e32 v142, 1.0, v142
	v_add_f32_e32 v143, 1.0, v143
	v_add_f32_e32 v144, 1.0, v144
	v_add_f32_e32 v145, 1.0, v145
	v_add_f32_e32 v146, 1.0, v146
	v_add_f32_e32 v147, 1.0, v147
	v_rcp_f32_e32 v140, v140
	v_rcp_f32_e32 v141, v141
	v_rcp_f32_e32 v142, v142
	v_rcp_f32_e32 v143, v143
	v_rcp_f32_e32 v144, v144
	v_rcp_f32_e32 v145, v145
	v_rcp_f32_e32 v146, v146
	v_rcp_f32_e32 v147, v147
	v_mul_f32_e32 v140, v56, v140
	v_mul_f32_e32 v141, v57, v141
	v_mul_f32_e32 v142, v58, v142
	v_mul_f32_e32 v143, v59, v143
	v_mul_f32_e32 v144, v60, v144
	v_mul_f32_e32 v145, v61, v145
	v_mul_f32_e32 v146, v62, v146
	v_mul_f32_e32 v147, v63, v147
	v_mul_f32_e32 v140, v40, v140
	v_mul_f32_e32 v141, v41, v141
	v_mul_f32_e32 v142, v42, v142
	v_mul_f32_e32 v143, v43, v143
	v_mul_f32_e32 v144, v44, v144
	v_mul_f32_e32 v145, v45, v145
	v_mul_f32_e32 v146, v46, v146
	v_mul_f32_e32 v147, v47, v147
	v_cvt_pk_bf16_f32 v152, v140, v141
	v_cvt_pk_bf16_f32 v153, v142, v143
	v_cvt_pk_bf16_f32 v154, v144, v145
	v_cvt_pk_bf16_f32 v155, v146, v147
	global_store_dwordx4 v132, v[152:155], s[12:13] offset:2304 sc0 sc1
	v_mul_f32_e32 v140, 0xbfb8aa3b, v16
	v_mul_f32_e32 v141, 0xbfb8aa3b, v17
	v_mul_f32_e32 v142, 0xbfb8aa3b, v18
	v_mul_f32_e32 v143, 0xbfb8aa3b, v19
	v_mul_f32_e32 v144, 0xbfb8aa3b, v20
	v_mul_f32_e32 v145, 0xbfb8aa3b, v21
	v_mul_f32_e32 v146, 0xbfb8aa3b, v22
	v_mul_f32_e32 v147, 0xbfb8aa3b, v23
	v_exp_f32_e32 v140, v140
	v_exp_f32_e32 v141, v141
	v_exp_f32_e32 v142, v142
	v_exp_f32_e32 v143, v143
	v_exp_f32_e32 v144, v144
	v_exp_f32_e32 v145, v145
	v_exp_f32_e32 v146, v146
	v_exp_f32_e32 v147, v147
	v_add_f32_e32 v140, 1.0, v140
	v_add_f32_e32 v141, 1.0, v141
	v_add_f32_e32 v142, 1.0, v142
	v_add_f32_e32 v143, 1.0, v143
	v_add_f32_e32 v144, 1.0, v144
	v_add_f32_e32 v145, 1.0, v145
	v_add_f32_e32 v146, 1.0, v146
	v_add_f32_e32 v147, 1.0, v147
	v_rcp_f32_e32 v140, v140
	v_rcp_f32_e32 v141, v141
	v_rcp_f32_e32 v142, v142
	v_rcp_f32_e32 v143, v143
	v_rcp_f32_e32 v144, v144
	v_rcp_f32_e32 v145, v145
	v_rcp_f32_e32 v146, v146
	v_rcp_f32_e32 v147, v147
	v_mul_f32_e32 v140, v16, v140
	v_mul_f32_e32 v141, v17, v141
	v_mul_f32_e32 v142, v18, v142
	v_mul_f32_e32 v143, v19, v143
	v_mul_f32_e32 v144, v20, v144
	v_mul_f32_e32 v145, v21, v145
	v_mul_f32_e32 v146, v22, v146
	v_mul_f32_e32 v147, v23, v147
	v_mul_f32_e32 v140, v0, v140
	v_mul_f32_e32 v141, v1, v141
	v_mul_f32_e32 v142, v2, v142
	v_mul_f32_e32 v143, v3, v143
	v_mul_f32_e32 v144, v4, v144
	v_mul_f32_e32 v145, v5, v145
	v_mul_f32_e32 v146, v6, v146
	v_mul_f32_e32 v147, v7, v147
	v_cvt_pk_bf16_f32 v156, v140, v141
	v_cvt_pk_bf16_f32 v157, v142, v143
	v_cvt_pk_bf16_f32 v158, v144, v145
	v_cvt_pk_bf16_f32 v159, v146, v147
	global_store_dwordx4 v133, v[156:159], s[12:13] offset:2048 sc0 sc1
	v_mul_f32_e32 v140, 0xbfb8aa3b, v24
	v_mul_f32_e32 v141, 0xbfb8aa3b, v25
	v_mul_f32_e32 v142, 0xbfb8aa3b, v26
	v_mul_f32_e32 v143, 0xbfb8aa3b, v27
	v_mul_f32_e32 v144, 0xbfb8aa3b, v28
	v_mul_f32_e32 v145, 0xbfb8aa3b, v29
	v_mul_f32_e32 v146, 0xbfb8aa3b, v30
	v_mul_f32_e32 v147, 0xbfb8aa3b, v31
	v_exp_f32_e32 v140, v140
	v_exp_f32_e32 v141, v141
	v_exp_f32_e32 v142, v142
	v_exp_f32_e32 v143, v143
	v_exp_f32_e32 v144, v144
	v_exp_f32_e32 v145, v145
	v_exp_f32_e32 v146, v146
	v_exp_f32_e32 v147, v147
	v_add_f32_e32 v140, 1.0, v140
	v_add_f32_e32 v141, 1.0, v141
	v_add_f32_e32 v142, 1.0, v142
	v_add_f32_e32 v143, 1.0, v143
	v_add_f32_e32 v144, 1.0, v144
	v_add_f32_e32 v145, 1.0, v145
	v_add_f32_e32 v146, 1.0, v146
	v_add_f32_e32 v147, 1.0, v147
	v_rcp_f32_e32 v140, v140
	v_rcp_f32_e32 v141, v141
	v_rcp_f32_e32 v142, v142
	v_rcp_f32_e32 v143, v143
	v_rcp_f32_e32 v144, v144
	v_rcp_f32_e32 v145, v145
	v_rcp_f32_e32 v146, v146
	v_rcp_f32_e32 v147, v147
	v_mul_f32_e32 v140, v24, v140
	v_mul_f32_e32 v141, v25, v141
	v_mul_f32_e32 v142, v26, v142
	v_mul_f32_e32 v143, v27, v143
	v_mul_f32_e32 v144, v28, v144
	v_mul_f32_e32 v145, v29, v145
	v_mul_f32_e32 v146, v30, v146
	v_mul_f32_e32 v147, v31, v147
	v_mul_f32_e32 v140, v8, v140
	v_mul_f32_e32 v141, v9, v141
	v_mul_f32_e32 v142, v10, v142
	v_mul_f32_e32 v143, v11, v143
	v_mul_f32_e32 v144, v12, v144
	v_mul_f32_e32 v145, v13, v145
	v_mul_f32_e32 v146, v14, v146
	v_mul_f32_e32 v147, v15, v147
	v_cvt_pk_bf16_f32 v160, v140, v141
	v_cvt_pk_bf16_f32 v161, v142, v143
	v_cvt_pk_bf16_f32 v162, v144, v145
	v_cvt_pk_bf16_f32 v163, v146, v147
	global_store_dwordx4 v133, v[160:163], s[12:13] offset:2304 sc0 sc1
	v_readlane_b32 s0, v254, 11
	s_add_i32 s2, s2, s0
	s_cmp_lt_i32 s2, s3
	s_barrier
	s_cbranch_scc1 .LBB0_1031

.Lg16_down_k:
	s_add_i32 s9, s8, 2
	s_lshl_b32 s96, s9, 13
	s_add_i32 m0, vcc_lo, 16384
	v_lshl_add_u64 v[160:161], v[188:189], 0, s[96:97]
	global_load_lds_dwordx4 v[160:161], off
	global_load_lds_dwordx4 v[160:161], off offset:1024
	ds_read_b128 v[196:199], v246 offset:0
	ds_read_b128 v[200:203], v162 offset:0
	ds_read_b128 v[204:207], v246 offset:2048
	ds_read_b128 v[242:245], v162 offset:2048
	s_add_i32 s9, s8, 2
	s_lshl_b32 s96, s9, 11
	v_lshl_add_u64 v[248:249], v[184:185], 0, s[96:97]
	v_lshl_add_u64 v[250:251], v[186:187], 0, s[96:97]
	s_waitcnt vmcnt(8) lgkmcnt(3)
	v_mfma_f32_16x16x32_bf16 v[112:115], v[196:199], v[128:131], v[112:115]
	v_mfma_f32_16x16x32_bf16 v[120:123], v[196:199], v[132:135], v[120:123]
	v_mfma_f32_16x16x32_bf16 v[48:51], v[196:199], v[136:139], v[48:51]
	v_mfma_f32_16x16x32_bf16 v[56:59], v[196:199], v[140:143], v[56:59]
	ds_read_b128 v[196:199], v246 offset:4096
	s_waitcnt lgkmcnt(3)
	v_mfma_f32_16x16x32_bf16 v[116:119], v[200:203], v[128:131], v[116:119]
	v_mfma_f32_16x16x32_bf16 v[124:127], v[200:203], v[132:135], v[124:127]
	v_mfma_f32_16x16x32_bf16 v[52:55], v[200:203], v[136:139], v[52:55]
	v_mfma_f32_16x16x32_bf16 v[60:63], v[200:203], v[140:143], v[60:63]
	ds_read_b128 v[200:203], v162 offset:4096
	s_waitcnt lgkmcnt(3)
	v_mfma_f32_16x16x32_bf16 v[96:99], v[204:207], v[128:131], v[96:99]
	v_mfma_f32_16x16x32_bf16 v[104:107], v[204:207], v[132:135], v[104:107]
	v_mfma_f32_16x16x32_bf16 v[32:35], v[204:207], v[136:139], v[32:35]
	v_mfma_f32_16x16x32_bf16 v[40:43], v[204:207], v[140:143], v[40:43]
	ds_read_b128 v[204:207], v246 offset:6144
	s_waitcnt lgkmcnt(3)
	v_mfma_f32_16x16x32_bf16 v[100:103], v[242:245], v[128:131], v[100:103]
	v_mfma_f32_16x16x32_bf16 v[108:111], v[242:245], v[132:135], v[108:111]
	v_mfma_f32_16x16x32_bf16 v[36:39], v[242:245], v[136:139], v[36:39]
	v_mfma_f32_16x16x32_bf16 v[44:47], v[242:245], v[140:143], v[44:47]
	ds_read_b128 v[242:245], v162 offset:6144
	s_waitcnt lgkmcnt(3)
	v_mfma_f32_16x16x32_bf16 v[80:83], v[196:199], v[128:131], v[80:83]
	v_mfma_f32_16x16x32_bf16 v[88:91], v[196:199], v[132:135], v[88:91]
	v_mfma_f32_16x16x32_bf16 v[16:19], v[196:199], v[136:139], v[16:19]
	v_mfma_f32_16x16x32_bf16 v[24:27], v[196:199], v[140:143], v[24:27]
	s_waitcnt lgkmcnt(2)
	v_mfma_f32_16x16x32_bf16 v[84:87], v[200:203], v[128:131], v[84:87]
	v_mfma_f32_16x16x32_bf16 v[92:95], v[200:203], v[132:135], v[92:95]
	v_mfma_f32_16x16x32_bf16 v[20:23], v[200:203], v[136:139], v[20:23]
	v_mfma_f32_16x16x32_bf16 v[28:31], v[200:203], v[140:143], v[28:31]
	s_waitcnt lgkmcnt(1)
	v_mfma_f32_16x16x32_bf16 v[64:67], v[204:207], v[128:131], v[64:67]
	v_mfma_f32_16x16x32_bf16 v[72:75], v[204:207], v[132:135], v[72:75]
	v_mfma_f32_16x16x32_bf16 v[0:3], v[204:207], v[136:139], v[0:3]
	v_mfma_f32_16x16x32_bf16 v[8:11], v[204:207], v[140:143], v[8:11]
	s_waitcnt lgkmcnt(0)
	v_mfma_f32_16x16x32_bf16 v[68:71], v[242:245], v[128:131], v[68:71]
	v_mfma_f32_16x16x32_bf16 v[76:79], v[242:245], v[132:135], v[76:79]
	v_mfma_f32_16x16x32_bf16 v[4:7], v[242:245], v[136:139], v[4:7]
	v_mfma_f32_16x16x32_bf16 v[12:15], v[242:245], v[140:143], v[12:15]
	global_load_dwordx4 v[128:131], v[248:249], off
	global_load_dwordx4 v[132:135], v[248:249], off offset:256
	global_load_dwordx4 v[136:139], v[250:251], off
	global_load_dwordx4 v[140:143], v[250:251], off offset:256
	s_waitcnt vmcnt(10)
	s_barrier
	s_add_i32 s9, s8, 3
	s_lshl_b32 s96, s9, 13
	s_mov_b32 m0, vcc_lo
	v_lshl_add_u64 v[160:161], v[188:189], 0, s[96:97]
	global_load_lds_dwordx4 v[160:161], off
	global_load_lds_dwordx4 v[160:161], off offset:1024
	ds_read_b128 v[196:199], v246 offset:8192
	ds_read_b128 v[200:203], v162 offset:8192
	ds_read_b128 v[204:207], v246 offset:10240
	ds_read_b128 v[242:245], v162 offset:10240
	s_add_i32 s9, s8, 3
	s_lshl_b32 s96, s9, 11
	v_lshl_add_u64 v[248:249], v[184:185], 0, s[96:97]
	v_lshl_add_u64 v[250:251], v[186:187], 0, s[96:97]
	s_waitcnt vmcnt(8) lgkmcnt(3)
	v_mfma_f32_16x16x32_bf16 v[112:115], v[196:199], v[144:147], v[112:115]
	v_mfma_f32_16x16x32_bf16 v[120:123], v[196:199], v[148:151], v[120:123]
	v_mfma_f32_16x16x32_bf16 v[48:51], v[196:199], v[152:155], v[48:51]
	v_mfma_f32_16x16x32_bf16 v[56:59], v[196:199], v[156:159], v[56:59]
	ds_read_b128 v[196:199], v246 offset:12288
	s_waitcnt lgkmcnt(3)
	v_mfma_f32_16x16x32_bf16 v[116:119], v[200:203], v[144:147], v[116:119]
	v_mfma_f32_16x16x32_bf16 v[124:127], v[200:203], v[148:151], v[124:127]
	v_mfma_f32_16x16x32_bf16 v[52:55], v[200:203], v[152:155], v[52:55]
	v_mfma_f32_16x16x32_bf16 v[60:63], v[200:203], v[156:159], v[60:63]
	ds_read_b128 v[200:203], v162 offset:12288
	s_waitcnt lgkmcnt(3)
	v_mfma_f32_16x16x32_bf16 v[96:99], v[204:207], v[144:147], v[96:99]
	v_mfma_f32_16x16x32_bf16 v[104:107], v[204:207], v[148:151], v[104:107]
	v_mfma_f32_16x16x32_bf16 v[32:35], v[204:207], v[152:155], v[32:35]
	v_mfma_f32_16x16x32_bf16 v[40:43], v[204:207], v[156:159], v[40:43]
	ds_read_b128 v[204:207], v246 offset:14336
	s_waitcnt lgkmcnt(3)
	v_mfma_f32_16x16x32_bf16 v[100:103], v[242:245], v[144:147], v[100:103]
	v_mfma_f32_16x16x32_bf16 v[108:111], v[242:245], v[148:151], v[108:111]
	v_mfma_f32_16x16x32_bf16 v[36:39], v[242:245], v[152:155], v[36:39]
	v_mfma_f32_16x16x32_bf16 v[44:47], v[242:245], v[156:159], v[44:47]
	ds_read_b128 v[242:245], v162 offset:14336
	s_waitcnt lgkmcnt(3)
	v_mfma_f32_16x16x32_bf16 v[80:83], v[196:199], v[144:147], v[80:83]
	v_mfma_f32_16x16x32_bf16 v[88:91], v[196:199], v[148:151], v[88:91]
	v_mfma_f32_16x16x32_bf16 v[16:19], v[196:199], v[152:155], v[16:19]
	v_mfma_f32_16x16x32_bf16 v[24:27], v[196:199], v[156:159], v[24:27]
	s_waitcnt lgkmcnt(2)
	v_mfma_f32_16x16x32_bf16 v[84:87], v[200:203], v[144:147], v[84:87]
	v_mfma_f32_16x16x32_bf16 v[92:95], v[200:203], v[148:151], v[92:95]
	v_mfma_f32_16x16x32_bf16 v[20:23], v[200:203], v[152:155], v[20:23]
	v_mfma_f32_16x16x32_bf16 v[28:31], v[200:203], v[156:159], v[28:31]
	s_waitcnt lgkmcnt(1)
	v_mfma_f32_16x16x32_bf16 v[64:67], v[204:207], v[144:147], v[64:67]
	v_mfma_f32_16x16x32_bf16 v[72:75], v[204:207], v[148:151], v[72:75]
	v_mfma_f32_16x16x32_bf16 v[0:3], v[204:207], v[152:155], v[0:3]
	v_mfma_f32_16x16x32_bf16 v[8:11], v[204:207], v[156:159], v[8:11]
	s_waitcnt lgkmcnt(0)
	v_mfma_f32_16x16x32_bf16 v[68:71], v[242:245], v[144:147], v[68:71]
	v_mfma_f32_16x16x32_bf16 v[76:79], v[242:245], v[148:151], v[76:79]
	v_mfma_f32_16x16x32_bf16 v[4:7], v[242:245], v[152:155], v[4:7]
	v_mfma_f32_16x16x32_bf16 v[12:15], v[242:245], v[156:159], v[12:15]
	global_load_dwordx4 v[144:147], v[248:249], off
	global_load_dwordx4 v[148:151], v[248:249], off offset:256
	global_load_dwordx4 v[152:155], v[250:251], off
	global_load_dwordx4 v[156:159], v[250:251], off offset:256
	s_waitcnt vmcnt(10)
	s_barrier
	s_add_i32 s9, s8, 4
	s_lshl_b32 s96, s9, 13
	s_add_i32 m0, vcc_lo, 8192
	v_lshl_add_u64 v[160:161], v[188:189], 0, s[96:97]
	global_load_lds_dwordx4 v[160:161], off
	global_load_lds_dwordx4 v[160:161], off offset:1024
	ds_read_b128 v[196:199], v246 offset:16384
	ds_read_b128 v[200:203], v162 offset:16384
	ds_read_b128 v[204:207], v246 offset:18432
	ds_read_b128 v[242:245], v162 offset:18432
	s_add_i32 s9, s8, 4
	s_lshl_b32 s96, s9, 11
	v_lshl_add_u64 v[248:249], v[184:185], 0, s[96:97]
	v_lshl_add_u64 v[250:251], v[186:187], 0, s[96:97]
	s_waitcnt vmcnt(8) lgkmcnt(3)
	v_mfma_f32_16x16x32_bf16 v[112:115], v[196:199], v[128:131], v[112:115]
	v_mfma_f32_16x16x32_bf16 v[120:123], v[196:199], v[132:135], v[120:123]
	v_mfma_f32_16x16x32_bf16 v[48:51], v[196:199], v[136:139], v[48:51]
	v_mfma_f32_16x16x32_bf16 v[56:59], v[196:199], v[140:143], v[56:59]
	ds_read_b128 v[196:199], v246 offset:20480
	s_waitcnt lgkmcnt(3)
	v_mfma_f32_16x16x32_bf16 v[116:119], v[200:203], v[128:131], v[116:119]
	v_mfma_f32_16x16x32_bf16 v[124:127], v[200:203], v[132:135], v[124:127]
	v_mfma_f32_16x16x32_bf16 v[52:55], v[200:203], v[136:139], v[52:55]
	v_mfma_f32_16x16x32_bf16 v[60:63], v[200:203], v[140:143], v[60:63]
	ds_read_b128 v[200:203], v162 offset:20480
	s_waitcnt lgkmcnt(3)
	v_mfma_f32_16x16x32_bf16 v[96:99], v[204:207], v[128:131], v[96:99]
	v_mfma_f32_16x16x32_bf16 v[104:107], v[204:207], v[132:135], v[104:107]
	v_mfma_f32_16x16x32_bf16 v[32:35], v[204:207], v[136:139], v[32:35]
	v_mfma_f32_16x16x32_bf16 v[40:43], v[204:207], v[140:143], v[40:43]
	ds_read_b128 v[204:207], v246 offset:22528
	s_waitcnt lgkmcnt(3)
	v_mfma_f32_16x16x32_bf16 v[100:103], v[242:245], v[128:131], v[100:103]
	v_mfma_f32_16x16x32_bf16 v[108:111], v[242:245], v[132:135], v[108:111]
	v_mfma_f32_16x16x32_bf16 v[36:39], v[242:245], v[136:139], v[36:39]
	v_mfma_f32_16x16x32_bf16 v[44:47], v[242:245], v[140:143], v[44:47]
	ds_read_b128 v[242:245], v162 offset:22528
	s_waitcnt lgkmcnt(3)
	v_mfma_f32_16x16x32_bf16 v[80:83], v[196:199], v[128:131], v[80:83]
	v_mfma_f32_16x16x32_bf16 v[88:91], v[196:199], v[132:135], v[88:91]
	v_mfma_f32_16x16x32_bf16 v[16:19], v[196:199], v[136:139], v[16:19]
	v_mfma_f32_16x16x32_bf16 v[24:27], v[196:199], v[140:143], v[24:27]
	s_waitcnt lgkmcnt(2)
	v_mfma_f32_16x16x32_bf16 v[84:87], v[200:203], v[128:131], v[84:87]
	v_mfma_f32_16x16x32_bf16 v[92:95], v[200:203], v[132:135], v[92:95]
	v_mfma_f32_16x16x32_bf16 v[20:23], v[200:203], v[136:139], v[20:23]
	v_mfma_f32_16x16x32_bf16 v[28:31], v[200:203], v[140:143], v[28:31]
	s_waitcnt lgkmcnt(1)
	v_mfma_f32_16x16x32_bf16 v[64:67], v[204:207], v[128:131], v[64:67]
	v_mfma_f32_16x16x32_bf16 v[72:75], v[204:207], v[132:135], v[72:75]
	v_mfma_f32_16x16x32_bf16 v[0:3], v[204:207], v[136:139], v[0:3]
	v_mfma_f32_16x16x32_bf16 v[8:11], v[204:207], v[140:143], v[8:11]
	s_waitcnt lgkmcnt(0)
	v_mfma_f32_16x16x32_bf16 v[68:71], v[242:245], v[128:131], v[68:71]
	v_mfma_f32_16x16x32_bf16 v[76:79], v[242:245], v[132:135], v[76:79]
	v_mfma_f32_16x16x32_bf16 v[4:7], v[242:245], v[136:139], v[4:7]
	v_mfma_f32_16x16x32_bf16 v[12:15], v[242:245], v[140:143], v[12:15]
	global_load_dwordx4 v[128:131], v[248:249], off
	global_load_dwordx4 v[132:135], v[248:249], off offset:256
	global_load_dwordx4 v[136:139], v[250:251], off
	global_load_dwordx4 v[140:143], v[250:251], off offset:256
	s_waitcnt vmcnt(10)
	s_barrier
	s_add_i32 s9, s8, 5
	s_lshl_b32 s96, s9, 13
	s_add_i32 m0, vcc_lo, 16384
	v_lshl_add_u64 v[160:161], v[188:189], 0, s[96:97]
	global_load_lds_dwordx4 v[160:161], off
	global_load_lds_dwordx4 v[160:161], off offset:1024
	ds_read_b128 v[196:199], v246 offset:0
	ds_read_b128 v[200:203], v162 offset:0
	ds_read_b128 v[204:207], v246 offset:2048
	ds_read_b128 v[242:245], v162 offset:2048
	s_add_i32 s9, s8, 5
	s_lshl_b32 s96, s9, 11
	v_lshl_add_u64 v[248:249], v[184:185], 0, s[96:97]
	v_lshl_add_u64 v[250:251], v[186:187], 0, s[96:97]
	s_waitcnt vmcnt(8) lgkmcnt(3)
	v_mfma_f32_16x16x32_bf16 v[112:115], v[196:199], v[144:147], v[112:115]
	v_mfma_f32_16x16x32_bf16 v[120:123], v[196:199], v[148:151], v[120:123]
	v_mfma_f32_16x16x32_bf16 v[48:51], v[196:199], v[152:155], v[48:51]
	v_mfma_f32_16x16x32_bf16 v[56:59], v[196:199], v[156:159], v[56:59]
	ds_read_b128 v[196:199], v246 offset:4096
	s_waitcnt lgkmcnt(3)
	v_mfma_f32_16x16x32_bf16 v[116:119], v[200:203], v[144:147], v[116:119]
	v_mfma_f32_16x16x32_bf16 v[124:127], v[200:203], v[148:151], v[124:127]
	v_mfma_f32_16x16x32_bf16 v[52:55], v[200:203], v[152:155], v[52:55]
	v_mfma_f32_16x16x32_bf16 v[60:63], v[200:203], v[156:159], v[60:63]
	ds_read_b128 v[200:203], v162 offset:4096
	s_waitcnt lgkmcnt(3)
	v_mfma_f32_16x16x32_bf16 v[96:99], v[204:207], v[144:147], v[96:99]
	v_mfma_f32_16x16x32_bf16 v[104:107], v[204:207], v[148:151], v[104:107]
	v_mfma_f32_16x16x32_bf16 v[32:35], v[204:207], v[152:155], v[32:35]
	v_mfma_f32_16x16x32_bf16 v[40:43], v[204:207], v[156:159], v[40:43]
	ds_read_b128 v[204:207], v246 offset:6144
	s_waitcnt lgkmcnt(3)
	v_mfma_f32_16x16x32_bf16 v[100:103], v[242:245], v[144:147], v[100:103]
	v_mfma_f32_16x16x32_bf16 v[108:111], v[242:245], v[148:151], v[108:111]
	v_mfma_f32_16x16x32_bf16 v[36:39], v[242:245], v[152:155], v[36:39]
	v_mfma_f32_16x16x32_bf16 v[44:47], v[242:245], v[156:159], v[44:47]
	ds_read_b128 v[242:245], v162 offset:6144
	s_waitcnt lgkmcnt(3)
	v_mfma_f32_16x16x32_bf16 v[80:83], v[196:199], v[144:147], v[80:83]
	v_mfma_f32_16x16x32_bf16 v[88:91], v[196:199], v[148:151], v[88:91]
	v_mfma_f32_16x16x32_bf16 v[16:19], v[196:199], v[152:155], v[16:19]
	v_mfma_f32_16x16x32_bf16 v[24:27], v[196:199], v[156:159], v[24:27]
	s_waitcnt lgkmcnt(2)
	v_mfma_f32_16x16x32_bf16 v[84:87], v[200:203], v[144:147], v[84:87]
	v_mfma_f32_16x16x32_bf16 v[92:95], v[200:203], v[148:151], v[92:95]
	v_mfma_f32_16x16x32_bf16 v[20:23], v[200:203], v[152:155], v[20:23]
	v_mfma_f32_16x16x32_bf16 v[28:31], v[200:203], v[156:159], v[28:31]
	s_waitcnt lgkmcnt(1)
	v_mfma_f32_16x16x32_bf16 v[64:67], v[204:207], v[144:147], v[64:67]
	v_mfma_f32_16x16x32_bf16 v[72:75], v[204:207], v[148:151], v[72:75]
	v_mfma_f32_16x16x32_bf16 v[0:3], v[204:207], v[152:155], v[0:3]
	v_mfma_f32_16x16x32_bf16 v[8:11], v[204:207], v[156:159], v[8:11]
	s_waitcnt lgkmcnt(0)
	v_mfma_f32_16x16x32_bf16 v[68:71], v[242:245], v[144:147], v[68:71]
	v_mfma_f32_16x16x32_bf16 v[76:79], v[242:245], v[148:151], v[76:79]
	v_mfma_f32_16x16x32_bf16 v[4:7], v[242:245], v[152:155], v[4:7]
	v_mfma_f32_16x16x32_bf16 v[12:15], v[242:245], v[156:159], v[12:15]
	global_load_dwordx4 v[144:147], v[248:249], off
	global_load_dwordx4 v[148:151], v[248:249], off offset:256
	global_load_dwordx4 v[152:155], v[250:251], off
	global_load_dwordx4 v[156:159], v[250:251], off offset:256
	s_waitcnt vmcnt(10)
	s_barrier
	s_add_i32 s9, s8, 6
	s_lshl_b32 s96, s9, 13
	s_mov_b32 m0, vcc_lo
	v_lshl_add_u64 v[160:161], v[188:189], 0, s[96:97]
	global_load_lds_dwordx4 v[160:161], off
	global_load_lds_dwordx4 v[160:161], off offset:1024
	ds_read_b128 v[196:199], v246 offset:8192
	ds_read_b128 v[200:203], v162 offset:8192
	ds_read_b128 v[204:207], v246 offset:10240
	ds_read_b128 v[242:245], v162 offset:10240
	s_add_i32 s9, s8, 6
	s_lshl_b32 s96, s9, 11
	v_lshl_add_u64 v[248:249], v[184:185], 0, s[96:97]
	v_lshl_add_u64 v[250:251], v[186:187], 0, s[96:97]
	s_waitcnt vmcnt(8) lgkmcnt(3)
	v_mfma_f32_16x16x32_bf16 v[112:115], v[196:199], v[128:131], v[112:115]
	v_mfma_f32_16x16x32_bf16 v[120:123], v[196:199], v[132:135], v[120:123]
	v_mfma_f32_16x16x32_bf16 v[48:51], v[196:199], v[136:139], v[48:51]
	v_mfma_f32_16x16x32_bf16 v[56:59], v[196:199], v[140:143], v[56:59]
	ds_read_b128 v[196:199], v246 offset:12288
	s_waitcnt lgkmcnt(3)
	v_mfma_f32_16x16x32_bf16 v[116:119], v[200:203], v[128:131], v[116:119]
	v_mfma_f32_16x16x32_bf16 v[124:127], v[200:203], v[132:135], v[124:127]
	v_mfma_f32_16x16x32_bf16 v[52:55], v[200:203], v[136:139], v[52:55]
	v_mfma_f32_16x16x32_bf16 v[60:63], v[200:203], v[140:143], v[60:63]
	ds_read_b128 v[200:203], v162 offset:12288
	s_waitcnt lgkmcnt(3)
	v_mfma_f32_16x16x32_bf16 v[96:99], v[204:207], v[128:131], v[96:99]
	v_mfma_f32_16x16x32_bf16 v[104:107], v[204:207], v[132:135], v[104:107]
	v_mfma_f32_16x16x32_bf16 v[32:35], v[204:207], v[136:139], v[32:35]
	v_mfma_f32_16x16x32_bf16 v[40:43], v[204:207], v[140:143], v[40:43]
	ds_read_b128 v[204:207], v246 offset:14336
	s_waitcnt lgkmcnt(3)
	v_mfma_f32_16x16x32_bf16 v[100:103], v[242:245], v[128:131], v[100:103]
	v_mfma_f32_16x16x32_bf16 v[108:111], v[242:245], v[132:135], v[108:111]
	v_mfma_f32_16x16x32_bf16 v[36:39], v[242:245], v[136:139], v[36:39]
	v_mfma_f32_16x16x32_bf16 v[44:47], v[242:245], v[140:143], v[44:47]
	ds_read_b128 v[242:245], v162 offset:14336
	s_waitcnt lgkmcnt(3)
	v_mfma_f32_16x16x32_bf16 v[80:83], v[196:199], v[128:131], v[80:83]
	v_mfma_f32_16x16x32_bf16 v[88:91], v[196:199], v[132:135], v[88:91]
	v_mfma_f32_16x16x32_bf16 v[16:19], v[196:199], v[136:139], v[16:19]
	v_mfma_f32_16x16x32_bf16 v[24:27], v[196:199], v[140:143], v[24:27]
	s_waitcnt lgkmcnt(2)
	v_mfma_f32_16x16x32_bf16 v[84:87], v[200:203], v[128:131], v[84:87]
	v_mfma_f32_16x16x32_bf16 v[92:95], v[200:203], v[132:135], v[92:95]
	v_mfma_f32_16x16x32_bf16 v[20:23], v[200:203], v[136:139], v[20:23]
	v_mfma_f32_16x16x32_bf16 v[28:31], v[200:203], v[140:143], v[28:31]
	s_waitcnt lgkmcnt(1)
	v_mfma_f32_16x16x32_bf16 v[64:67], v[204:207], v[128:131], v[64:67]
	v_mfma_f32_16x16x32_bf16 v[72:75], v[204:207], v[132:135], v[72:75]
	v_mfma_f32_16x16x32_bf16 v[0:3], v[204:207], v[136:139], v[0:3]
	v_mfma_f32_16x16x32_bf16 v[8:11], v[204:207], v[140:143], v[8:11]
	s_waitcnt lgkmcnt(0)
	v_mfma_f32_16x16x32_bf16 v[68:71], v[242:245], v[128:131], v[68:71]
	v_mfma_f32_16x16x32_bf16 v[76:79], v[242:245], v[132:135], v[76:79]
	v_mfma_f32_16x16x32_bf16 v[4:7], v[242:245], v[136:139], v[4:7]
	v_mfma_f32_16x16x32_bf16 v[12:15], v[242:245], v[140:143], v[12:15]
	global_load_dwordx4 v[128:131], v[248:249], off
	global_load_dwordx4 v[132:135], v[248:249], off offset:256
	global_load_dwordx4 v[136:139], v[250:251], off
	global_load_dwordx4 v[140:143], v[250:251], off offset:256
	s_waitcnt vmcnt(10)
	s_barrier
	s_add_i32 s9, s8, 7
	s_lshl_b32 s96, s9, 13
	s_add_i32 m0, vcc_lo, 8192
	v_lshl_add_u64 v[160:161], v[188:189], 0, s[96:97]
	global_load_lds_dwordx4 v[160:161], off
	global_load_lds_dwordx4 v[160:161], off offset:1024
	ds_read_b128 v[196:199], v246 offset:16384
	ds_read_b128 v[200:203], v162 offset:16384
	ds_read_b128 v[204:207], v246 offset:18432
	ds_read_b128 v[242:245], v162 offset:18432
	s_add_i32 s9, s8, 7
	s_lshl_b32 s96, s9, 11
	v_lshl_add_u64 v[248:249], v[184:185], 0, s[96:97]
	v_lshl_add_u64 v[250:251], v[186:187], 0, s[96:97]
	s_waitcnt vmcnt(8) lgkmcnt(3)
	v_mfma_f32_16x16x32_bf16 v[112:115], v[196:199], v[144:147], v[112:115]
	v_mfma_f32_16x16x32_bf16 v[120:123], v[196:199], v[148:151], v[120:123]
	v_mfma_f32_16x16x32_bf16 v[48:51], v[196:199], v[152:155], v[48:51]
	v_mfma_f32_16x16x32_bf16 v[56:59], v[196:199], v[156:159], v[56:59]
	ds_read_b128 v[196:199], v246 offset:20480
	s_waitcnt lgkmcnt(3)
	v_mfma_f32_16x16x32_bf16 v[116:119], v[200:203], v[144:147], v[116:119]
	v_mfma_f32_16x16x32_bf16 v[124:127], v[200:203], v[148:151], v[124:127]
	v_mfma_f32_16x16x32_bf16 v[52:55], v[200:203], v[152:155], v[52:55]
	v_mfma_f32_16x16x32_bf16 v[60:63], v[200:203], v[156:159], v[60:63]
	ds_read_b128 v[200:203], v162 offset:20480
	s_waitcnt lgkmcnt(3)
	v_mfma_f32_16x16x32_bf16 v[96:99], v[204:207], v[144:147], v[96:99]
	v_mfma_f32_16x16x32_bf16 v[104:107], v[204:207], v[148:151], v[104:107]
	v_mfma_f32_16x16x32_bf16 v[32:35], v[204:207], v[152:155], v[32:35]
	v_mfma_f32_16x16x32_bf16 v[40:43], v[204:207], v[156:159], v[40:43]
	ds_read_b128 v[204:207], v246 offset:22528
	s_waitcnt lgkmcnt(3)
	v_mfma_f32_16x16x32_bf16 v[100:103], v[242:245], v[144:147], v[100:103]
	v_mfma_f32_16x16x32_bf16 v[108:111], v[242:245], v[148:151], v[108:111]
	v_mfma_f32_16x16x32_bf16 v[36:39], v[242:245], v[152:155], v[36:39]
	v_mfma_f32_16x16x32_bf16 v[44:47], v[242:245], v[156:159], v[44:47]
	ds_read_b128 v[242:245], v162 offset:22528
	s_waitcnt lgkmcnt(3)
	v_mfma_f32_16x16x32_bf16 v[80:83], v[196:199], v[144:147], v[80:83]
	v_mfma_f32_16x16x32_bf16 v[88:91], v[196:199], v[148:151], v[88:91]
	v_mfma_f32_16x16x32_bf16 v[16:19], v[196:199], v[152:155], v[16:19]
	v_mfma_f32_16x16x32_bf16 v[24:27], v[196:199], v[156:159], v[24:27]
	s_waitcnt lgkmcnt(2)
	v_mfma_f32_16x16x32_bf16 v[84:87], v[200:203], v[144:147], v[84:87]
	v_mfma_f32_16x16x32_bf16 v[92:95], v[200:203], v[148:151], v[92:95]
	v_mfma_f32_16x16x32_bf16 v[20:23], v[200:203], v[152:155], v[20:23]
	v_mfma_f32_16x16x32_bf16 v[28:31], v[200:203], v[156:159], v[28:31]
	s_waitcnt lgkmcnt(1)
	v_mfma_f32_16x16x32_bf16 v[64:67], v[204:207], v[144:147], v[64:67]
	v_mfma_f32_16x16x32_bf16 v[72:75], v[204:207], v[148:151], v[72:75]
	v_mfma_f32_16x16x32_bf16 v[0:3], v[204:207], v[152:155], v[0:3]
	v_mfma_f32_16x16x32_bf16 v[8:11], v[204:207], v[156:159], v[8:11]
	s_waitcnt lgkmcnt(0)
	v_mfma_f32_16x16x32_bf16 v[68:71], v[242:245], v[144:147], v[68:71]
	v_mfma_f32_16x16x32_bf16 v[76:79], v[242:245], v[148:151], v[76:79]
	v_mfma_f32_16x16x32_bf16 v[4:7], v[242:245], v[152:155], v[4:7]
	v_mfma_f32_16x16x32_bf16 v[12:15], v[242:245], v[156:159], v[12:15]
	global_load_dwordx4 v[144:147], v[248:249], off
	global_load_dwordx4 v[148:151], v[248:249], off offset:256
	global_load_dwordx4 v[152:155], v[250:251], off
	global_load_dwordx4 v[156:159], v[250:251], off offset:256
	s_waitcnt vmcnt(10)
	s_barrier
	s_add_i32 s8, s8, 6
	s_cmp_lt_u32 s8, 84
	s_cbranch_scc1 .Lg16_down_k
	s_mov_b32 s96, 0xac000
	s_add_i32 m0, vcc_lo, 16384
	v_lshl_add_u64 v[160:161], v[188:189], 0, s[96:97]
	global_load_lds_dwordx4 v[160:161], off
	global_load_lds_dwordx4 v[160:161], off offset:1024
	ds_read_b128 v[196:199], v246 offset:0
	ds_read_b128 v[200:203], v162 offset:0
	ds_read_b128 v[204:207], v246 offset:2048
	ds_read_b128 v[242:245], v162 offset:2048
	s_mov_b32 s96, 0x2b000
	v_lshl_add_u64 v[248:249], v[184:185], 0, s[96:97]
	v_lshl_add_u64 v[250:251], v[186:187], 0, s[96:97]
	s_waitcnt vmcnt(8) lgkmcnt(3)
	v_mfma_f32_16x16x32_bf16 v[112:115], v[196:199], v[128:131], v[112:115]
	v_mfma_f32_16x16x32_bf16 v[120:123], v[196:199], v[132:135], v[120:123]
	v_mfma_f32_16x16x32_bf16 v[48:51], v[196:199], v[136:139], v[48:51]
	v_mfma_f32_16x16x32_bf16 v[56:59], v[196:199], v[140:143], v[56:59]
	ds_read_b128 v[196:199], v246 offset:4096
	s_waitcnt lgkmcnt(3)
	v_mfma_f32_16x16x32_bf16 v[116:119], v[200:203], v[128:131], v[116:119]
	v_mfma_f32_16x16x32_bf16 v[124:127], v[200:203], v[132:135], v[124:127]
	v_mfma_f32_16x16x32_bf16 v[52:55], v[200:203], v[136:139], v[52:55]
	v_mfma_f32_16x16x32_bf16 v[60:63], v[200:203], v[140:143], v[60:63]
	ds_read_b128 v[200:203], v162 offset:4096
	s_waitcnt lgkmcnt(3)
	v_mfma_f32_16x16x32_bf16 v[96:99], v[204:207], v[128:131], v[96:99]
	v_mfma_f32_16x16x32_bf16 v[104:107], v[204:207], v[132:135], v[104:107]
	v_mfma_f32_16x16x32_bf16 v[32:35], v[204:207], v[136:139], v[32:35]
	v_mfma_f32_16x16x32_bf16 v[40:43], v[204:207], v[140:143], v[40:43]
	ds_read_b128 v[204:207], v246 offset:6144
	s_waitcnt lgkmcnt(3)
	v_mfma_f32_16x16x32_bf16 v[100:103], v[242:245], v[128:131], v[100:103]
	v_mfma_f32_16x16x32_bf16 v[108:111], v[242:245], v[132:135], v[108:111]
	v_mfma_f32_16x16x32_bf16 v[36:39], v[242:245], v[136:139], v[36:39]
	v_mfma_f32_16x16x32_bf16 v[44:47], v[242:245], v[140:143], v[44:47]
	ds_read_b128 v[242:245], v162 offset:6144
	s_waitcnt lgkmcnt(3)
	v_mfma_f32_16x16x32_bf16 v[80:83], v[196:199], v[128:131], v[80:83]
	v_mfma_f32_16x16x32_bf16 v[88:91], v[196:199], v[132:135], v[88:91]
	v_mfma_f32_16x16x32_bf16 v[16:19], v[196:199], v[136:139], v[16:19]
	v_mfma_f32_16x16x32_bf16 v[24:27], v[196:199], v[140:143], v[24:27]
	s_waitcnt lgkmcnt(2)
	v_mfma_f32_16x16x32_bf16 v[84:87], v[200:203], v[128:131], v[84:87]
	v_mfma_f32_16x16x32_bf16 v[92:95], v[200:203], v[132:135], v[92:95]
	v_mfma_f32_16x16x32_bf16 v[20:23], v[200:203], v[136:139], v[20:23]
	v_mfma_f32_16x16x32_bf16 v[28:31], v[200:203], v[140:143], v[28:31]
	s_waitcnt lgkmcnt(1)
	v_mfma_f32_16x16x32_bf16 v[64:67], v[204:207], v[128:131], v[64:67]
	v_mfma_f32_16x16x32_bf16 v[72:75], v[204:207], v[132:135], v[72:75]
	v_mfma_f32_16x16x32_bf16 v[0:3], v[204:207], v[136:139], v[0:3]
	v_mfma_f32_16x16x32_bf16 v[8:11], v[204:207], v[140:143], v[8:11]
	s_waitcnt lgkmcnt(0)
	v_mfma_f32_16x16x32_bf16 v[68:71], v[242:245], v[128:131], v[68:71]
	v_mfma_f32_16x16x32_bf16 v[76:79], v[242:245], v[132:135], v[76:79]
	v_mfma_f32_16x16x32_bf16 v[4:7], v[242:245], v[136:139], v[4:7]
	v_mfma_f32_16x16x32_bf16 v[12:15], v[242:245], v[140:143], v[12:15]
	global_load_dwordx4 v[128:131], v[248:249], off
	global_load_dwordx4 v[132:135], v[248:249], off offset:256
	global_load_dwordx4 v[136:139], v[250:251], off
	global_load_dwordx4 v[140:143], v[250:251], off offset:256
	s_waitcnt vmcnt(10)
	s_barrier
	s_mov_b32 s96, 0xae000
	s_mov_b32 m0, vcc_lo
	v_lshl_add_u64 v[160:161], v[188:189], 0, s[96:97]
	global_load_lds_dwordx4 v[160:161], off
	global_load_lds_dwordx4 v[160:161], off offset:1024
	ds_read_b128 v[196:199], v246 offset:8192
	ds_read_b128 v[200:203], v162 offset:8192
	ds_read_b128 v[204:207], v246 offset:10240
	ds_read_b128 v[242:245], v162 offset:10240
	s_mov_b32 s96, 0x2b800
	v_lshl_add_u64 v[248:249], v[184:185], 0, s[96:97]
	v_lshl_add_u64 v[250:251], v[186:187], 0, s[96:97]
	s_waitcnt vmcnt(8) lgkmcnt(3)
	v_mfma_f32_16x16x32_bf16 v[112:115], v[196:199], v[144:147], v[112:115]
	v_mfma_f32_16x16x32_bf16 v[120:123], v[196:199], v[148:151], v[120:123]
	v_mfma_f32_16x16x32_bf16 v[48:51], v[196:199], v[152:155], v[48:51]
	v_mfma_f32_16x16x32_bf16 v[56:59], v[196:199], v[156:159], v[56:59]
	ds_read_b128 v[196:199], v246 offset:12288
	s_waitcnt lgkmcnt(3)
	v_mfma_f32_16x16x32_bf16 v[116:119], v[200:203], v[144:147], v[116:119]
	v_mfma_f32_16x16x32_bf16 v[124:127], v[200:203], v[148:151], v[124:127]
	v_mfma_f32_16x16x32_bf16 v[52:55], v[200:203], v[152:155], v[52:55]
	v_mfma_f32_16x16x32_bf16 v[60:63], v[200:203], v[156:159], v[60:63]
	ds_read_b128 v[200:203], v162 offset:12288
	s_waitcnt lgkmcnt(3)
	v_mfma_f32_16x16x32_bf16 v[96:99], v[204:207], v[144:147], v[96:99]
	v_mfma_f32_16x16x32_bf16 v[104:107], v[204:207], v[148:151], v[104:107]
	v_mfma_f32_16x16x32_bf16 v[32:35], v[204:207], v[152:155], v[32:35]
	v_mfma_f32_16x16x32_bf16 v[40:43], v[204:207], v[156:159], v[40:43]
	ds_read_b128 v[204:207], v246 offset:14336
	s_waitcnt lgkmcnt(3)
	v_mfma_f32_16x16x32_bf16 v[100:103], v[242:245], v[144:147], v[100:103]
	v_mfma_f32_16x16x32_bf16 v[108:111], v[242:245], v[148:151], v[108:111]
	v_mfma_f32_16x16x32_bf16 v[36:39], v[242:245], v[152:155], v[36:39]
	v_mfma_f32_16x16x32_bf16 v[44:47], v[242:245], v[156:159], v[44:47]
	ds_read_b128 v[242:245], v162 offset:14336
	s_waitcnt lgkmcnt(3)
	v_mfma_f32_16x16x32_bf16 v[80:83], v[196:199], v[144:147], v[80:83]
	v_mfma_f32_16x16x32_bf16 v[88:91], v[196:199], v[148:151], v[88:91]
	v_mfma_f32_16x16x32_bf16 v[16:19], v[196:199], v[152:155], v[16:19]
	v_mfma_f32_16x16x32_bf16 v[24:27], v[196:199], v[156:159], v[24:27]
	s_waitcnt lgkmcnt(2)
	v_mfma_f32_16x16x32_bf16 v[84:87], v[200:203], v[144:147], v[84:87]
	v_mfma_f32_16x16x32_bf16 v[92:95], v[200:203], v[148:151], v[92:95]
	v_mfma_f32_16x16x32_bf16 v[20:23], v[200:203], v[152:155], v[20:23]
	v_mfma_f32_16x16x32_bf16 v[28:31], v[200:203], v[156:159], v[28:31]
	s_waitcnt lgkmcnt(1)
	v_mfma_f32_16x16x32_bf16 v[64:67], v[204:207], v[144:147], v[64:67]
	v_mfma_f32_16x16x32_bf16 v[72:75], v[204:207], v[148:151], v[72:75]
	v_mfma_f32_16x16x32_bf16 v[0:3], v[204:207], v[152:155], v[0:3]
	v_mfma_f32_16x16x32_bf16 v[8:11], v[204:207], v[156:159], v[8:11]
	s_waitcnt lgkmcnt(0)
	v_mfma_f32_16x16x32_bf16 v[68:71], v[242:245], v[144:147], v[68:71]
	v_mfma_f32_16x16x32_bf16 v[76:79], v[242:245], v[148:151], v[76:79]
	v_mfma_f32_16x16x32_bf16 v[4:7], v[242:245], v[152:155], v[4:7]
	v_mfma_f32_16x16x32_bf16 v[12:15], v[242:245], v[156:159], v[12:15]
	global_load_dwordx4 v[144:147], v[248:249], off
	global_load_dwordx4 v[148:151], v[248:249], off offset:256
	global_load_dwordx4 v[152:155], v[250:251], off
	global_load_dwordx4 v[156:159], v[250:251], off offset:256
	s_waitcnt vmcnt(10)
	s_barrier
	ds_read_b128 v[196:199], v246 offset:16384
	ds_read_b128 v[200:203], v162 offset:16384
	ds_read_b128 v[204:207], v246 offset:18432
	ds_read_b128 v[242:245], v162 offset:18432
	s_waitcnt vmcnt(6) lgkmcnt(3)
	v_mfma_f32_16x16x32_bf16 v[112:115], v[196:199], v[128:131], v[112:115]
	v_mfma_f32_16x16x32_bf16 v[120:123], v[196:199], v[132:135], v[120:123]
	v_mfma_f32_16x16x32_bf16 v[48:51], v[196:199], v[136:139], v[48:51]
	v_mfma_f32_16x16x32_bf16 v[56:59], v[196:199], v[140:143], v[56:59]
	ds_read_b128 v[196:199], v246 offset:20480
	s_waitcnt lgkmcnt(3)
	v_mfma_f32_16x16x32_bf16 v[116:119], v[200:203], v[128:131], v[116:119]
	v_mfma_f32_16x16x32_bf16 v[124:127], v[200:203], v[132:135], v[124:127]
	v_mfma_f32_16x16x32_bf16 v[52:55], v[200:203], v[136:139], v[52:55]
	v_mfma_f32_16x16x32_bf16 v[60:63], v[200:203], v[140:143], v[60:63]
	ds_read_b128 v[200:203], v162 offset:20480
	s_waitcnt lgkmcnt(3)
	v_mfma_f32_16x16x32_bf16 v[96:99], v[204:207], v[128:131], v[96:99]
	v_mfma_f32_16x16x32_bf16 v[104:107], v[204:207], v[132:135], v[104:107]
	v_mfma_f32_16x16x32_bf16 v[32:35], v[204:207], v[136:139], v[32:35]
	v_mfma_f32_16x16x32_bf16 v[40:43], v[204:207], v[140:143], v[40:43]
	ds_read_b128 v[204:207], v246 offset:22528
	s_waitcnt lgkmcnt(3)
	v_mfma_f32_16x16x32_bf16 v[100:103], v[242:245], v[128:131], v[100:103]
	v_mfma_f32_16x16x32_bf16 v[108:111], v[242:245], v[132:135], v[108:111]
	v_mfma_f32_16x16x32_bf16 v[36:39], v[242:245], v[136:139], v[36:39]
	v_mfma_f32_16x16x32_bf16 v[44:47], v[242:245], v[140:143], v[44:47]
	ds_read_b128 v[242:245], v162 offset:22528
	s_waitcnt lgkmcnt(3)
	v_mfma_f32_16x16x32_bf16 v[80:83], v[196:199], v[128:131], v[80:83]
	v_mfma_f32_16x16x32_bf16 v[88:91], v[196:199], v[132:135], v[88:91]
	v_mfma_f32_16x16x32_bf16 v[16:19], v[196:199], v[136:139], v[16:19]
	v_mfma_f32_16x16x32_bf16 v[24:27], v[196:199], v[140:143], v[24:27]
	s_waitcnt lgkmcnt(2)
	v_mfma_f32_16x16x32_bf16 v[84:87], v[200:203], v[128:131], v[84:87]
	v_mfma_f32_16x16x32_bf16 v[92:95], v[200:203], v[132:135], v[92:95]
	v_mfma_f32_16x16x32_bf16 v[20:23], v[200:203], v[136:139], v[20:23]
	v_mfma_f32_16x16x32_bf16 v[28:31], v[200:203], v[140:143], v[28:31]
	s_waitcnt lgkmcnt(1)
	v_mfma_f32_16x16x32_bf16 v[64:67], v[204:207], v[128:131], v[64:67]
	v_mfma_f32_16x16x32_bf16 v[72:75], v[204:207], v[132:135], v[72:75]
	v_mfma_f32_16x16x32_bf16 v[0:3], v[204:207], v[136:139], v[0:3]
	v_mfma_f32_16x16x32_bf16 v[8:11], v[204:207], v[140:143], v[8:11]
	s_waitcnt lgkmcnt(0)
	v_mfma_f32_16x16x32_bf16 v[68:71], v[242:245], v[128:131], v[68:71]
	v_mfma_f32_16x16x32_bf16 v[76:79], v[242:245], v[132:135], v[76:79]
	v_mfma_f32_16x16x32_bf16 v[4:7], v[242:245], v[136:139], v[4:7]
	v_mfma_f32_16x16x32_bf16 v[12:15], v[242:245], v[140:143], v[12:15]
	s_waitcnt vmcnt(4)
	s_barrier
	ds_read_b128 v[196:199], v246 offset:0
	ds_read_b128 v[200:203], v162 offset:0
	ds_read_b128 v[204:207], v246 offset:2048
	ds_read_b128 v[242:245], v162 offset:2048
	s_waitcnt vmcnt(0) lgkmcnt(3)
	v_mfma_f32_16x16x32_bf16 v[112:115], v[196:199], v[144:147], v[112:115]
	v_mfma_f32_16x16x32_bf16 v[120:123], v[196:199], v[148:151], v[120:123]
	v_mfma_f32_16x16x32_bf16 v[48:51], v[196:199], v[152:155], v[48:51]
	v_mfma_f32_16x16x32_bf16 v[56:59], v[196:199], v[156:159], v[56:59]
	ds_read_b128 v[196:199], v246 offset:4096
	s_waitcnt lgkmcnt(3)
	v_mfma_f32_16x16x32_bf16 v[116:119], v[200:203], v[144:147], v[116:119]
	v_mfma_f32_16x16x32_bf16 v[124:127], v[200:203], v[148:151], v[124:127]
	v_mfma_f32_16x16x32_bf16 v[52:55], v[200:203], v[152:155], v[52:55]
	v_mfma_f32_16x16x32_bf16 v[60:63], v[200:203], v[156:159], v[60:63]
	ds_read_b128 v[200:203], v162 offset:4096
	s_waitcnt lgkmcnt(3)
	v_mfma_f32_16x16x32_bf16 v[96:99], v[204:207], v[144:147], v[96:99]
	v_mfma_f32_16x16x32_bf16 v[104:107], v[204:207], v[148:151], v[104:107]
	v_mfma_f32_16x16x32_bf16 v[32:35], v[204:207], v[152:155], v[32:35]
	v_mfma_f32_16x16x32_bf16 v[40:43], v[204:207], v[156:159], v[40:43]
	ds_read_b128 v[204:207], v246 offset:6144
	s_waitcnt lgkmcnt(3)
	v_mfma_f32_16x16x32_bf16 v[100:103], v[242:245], v[144:147], v[100:103]
	v_mfma_f32_16x16x32_bf16 v[108:111], v[242:245], v[148:151], v[108:111]
	v_mfma_f32_16x16x32_bf16 v[36:39], v[242:245], v[152:155], v[36:39]
	v_mfma_f32_16x16x32_bf16 v[44:47], v[242:245], v[156:159], v[44:47]
	ds_read_b128 v[242:245], v162 offset:6144
	s_waitcnt lgkmcnt(3)
	v_mfma_f32_16x16x32_bf16 v[80:83], v[196:199], v[144:147], v[80:83]
	v_mfma_f32_16x16x32_bf16 v[88:91], v[196:199], v[148:151], v[88:91]
	v_mfma_f32_16x16x32_bf16 v[16:19], v[196:199], v[152:155], v[16:19]
	v_mfma_f32_16x16x32_bf16 v[24:27], v[196:199], v[156:159], v[24:27]
	s_waitcnt lgkmcnt(2)
	v_mfma_f32_16x16x32_bf16 v[84:87], v[200:203], v[144:147], v[84:87]
	v_mfma_f32_16x16x32_bf16 v[92:95], v[200:203], v[148:151], v[92:95]
	v_mfma_f32_16x16x32_bf16 v[20:23], v[200:203], v[152:155], v[20:23]
	v_mfma_f32_16x16x32_bf16 v[28:31], v[200:203], v[156:159], v[28:31]
	s_waitcnt lgkmcnt(1)
	v_mfma_f32_16x16x32_bf16 v[64:67], v[204:207], v[144:147], v[64:67]
	v_mfma_f32_16x16x32_bf16 v[72:75], v[204:207], v[148:151], v[72:75]
	v_mfma_f32_16x16x32_bf16 v[0:3], v[204:207], v[152:155], v[0:3]
	v_mfma_f32_16x16x32_bf16 v[8:11], v[204:207], v[156:159], v[8:11]
	s_waitcnt lgkmcnt(0)
	v_mfma_f32_16x16x32_bf16 v[68:71], v[242:245], v[144:147], v[68:71]
	v_mfma_f32_16x16x32_bf16 v[76:79], v[242:245], v[148:151], v[76:79]
	v_mfma_f32_16x16x32_bf16 v[4:7], v[242:245], v[152:155], v[4:7]
	v_mfma_f32_16x16x32_bf16 v[12:15], v[242:245], v[156:159], v[12:15]
	s_barrier
	s_nop 7
	s_nop 1
	s_waitcnt vmcnt(0)
	s_waitcnt vmcnt(0)
	v_and_b32_e32 v188, 63, v179
	v_lshrrev_b32_e32 v189, 6, v179
	v_mul_u32_u24_e32 v249, 0x2400, v189
	v_mov_b32_e32 v250, v249
	v_and_b32_e32 v251, 15, v188
	v_mul_u32_u24_e32 v251, 0x110, v251
	v_add_u32_e32 v249, v249, v251
	v_lshrrev_b32_e32 v251, 4, v188
	v_lshl_add_u32 v249, v251, 5, v249
	v_lshrrev_b32_e32 v237, 4, v188
	v_mul_u32_u24_e32 v251, 0x110, v237
	v_add_u32_e32 v250, v250, v251
	v_and_b32_e32 v251, 15, v188
	v_lshlrev_b32_e32 v251, 4, v251
	v_add_u32_e32 v250, v250, v251
	v_lshl_add_u32 v237, v189, 6, v237
	v_lshl_add_u32 v237, v237, 12, v251
	v_add_u32_e32 v238, 16384, v237
	v_add_u32_e32 v239, 32768, v237
	v_add_u32_e32 v240, 49152, v237
	v_add_u32_e32 v241, 65536, v237
	v_add_u32_e32 v242, 81920, v237
	v_add_u32_e32 v243, 98304, v237
	v_add_u32_e32 v248, 114688, v237
	s_lshl_b32 s16, s7, 8
	s_lshl_b32 s18, s6, 9
	s_lshr_b32 s19, s7, 4
	v_readlane_b32 s12, v253, 46
	v_readlane_b32 s13, v253, 47
	v_readlane_b32 s14, v253, 46
	v_readlane_b32 s15, v253, 47
	s_add_i32 s17, s16, 0xffff8000
	s_cmpk_lt_u32 s7, 0x80
	s_cselect_b32 s12, s12, s62
	s_cselect_b32 s13, s13, s63
	s_cselect_b32 s14, s14, s62
	s_cselect_b32 s15, s15, s63
	s_cselect_b32 s19, s19, 8
	s_cselect_b32 s16, s16, s17
	s_mov_b32 s17, 0
	s_lshl_b64 s[16:17], s[16:17], 12
	s_add_u32 s16, s16, s18
	s_addc_u32 s17, s17, 0
	s_add_u32 s12, s12, s16
	s_addc_u32 s13, s13, s17
	s_add_u32 s14, s14, s16
	s_addc_u32 s15, s15, s17
	s_mul_i32 s19, s19, 0x6000
	s_add_u32 s20, s0, s19
	s_addc_u32 s21, s1, 0
	s_add_u32 s20, s20, s18
	s_addc_u32 s21, s21, 0
	global_load_dwordx4 v[244:247], v251, s[20:21]
	global_load_dwordx4 v[160:163], v237, s[12:13]
	global_load_dwordx4 v[164:167], v238, s[12:13]
	global_load_dwordx4 v[168:171], v239, s[12:13]
	global_load_dwordx4 v[172:175], v240, s[12:13]
	global_load_dwordx4 v[196:199], v241, s[12:13]
	global_load_dwordx4 v[200:203], v242, s[12:13]
	global_load_dwordx4 v[204:207], v243, s[12:13]
	global_load_dwordx4 v[184:187], v248, s[12:13]
	ds_write_b128 v249, v[112:115]
	ds_write_b128 v249, v[116:119] offset:16
	ds_write_b128 v249, v[96:99] offset:128
	ds_write_b128 v249, v[100:103] offset:144
	ds_write_b128 v249, v[120:123] offset:4352
	ds_write_b128 v249, v[124:127] offset:4368
	ds_write_b128 v249, v[104:107] offset:4480
	ds_write_b128 v249, v[108:111] offset:4496
	s_waitcnt lgkmcnt(0)
	ds_read_b128 v[128:131], v250
	ds_read_b128 v[132:135], v250 offset:1088
	ds_read_b128 v[136:139], v250 offset:2176
	ds_read_b128 v[140:143], v250 offset:3264
	ds_read_b128 v[144:147], v250 offset:4352
	ds_read_b128 v[148:151], v250 offset:5440
	ds_read_b128 v[152:155], v250 offset:6528
	ds_read_b128 v[156:159], v250 offset:7616
	s_waitcnt vmcnt(7) lgkmcnt(7)
	v_fma_f32 v128, v244, v128, v160
	v_fma_f32 v129, v245, v129, v161
	v_fma_f32 v130, v246, v130, v162
	v_fma_f32 v131, v247, v131, v163
	global_store_dwordx4 v237, v[128:131], s[14:15] sc0 sc1
	s_waitcnt vmcnt(7) lgkmcnt(6)
	v_fma_f32 v132, v244, v132, v164
	v_fma_f32 v133, v245, v133, v165
	v_fma_f32 v134, v246, v134, v166
	v_fma_f32 v135, v247, v135, v167
	global_store_dwordx4 v238, v[132:135], s[14:15] sc0 sc1
	s_waitcnt vmcnt(7) lgkmcnt(5)
	v_fma_f32 v136, v244, v136, v168
	v_fma_f32 v137, v245, v137, v169
	v_fma_f32 v138, v246, v138, v170
	v_fma_f32 v139, v247, v139, v171
	global_store_dwordx4 v239, v[136:139], s[14:15] sc0 sc1
	s_waitcnt vmcnt(7) lgkmcnt(4)
	v_fma_f32 v140, v244, v140, v172
	v_fma_f32 v141, v245, v141, v173
	v_fma_f32 v142, v246, v142, v174
	v_fma_f32 v143, v247, v143, v175
	global_store_dwordx4 v240, v[140:143], s[14:15] sc0 sc1
	s_waitcnt vmcnt(7) lgkmcnt(3)
	v_fma_f32 v144, v244, v144, v196
	v_fma_f32 v145, v245, v145, v197
	v_fma_f32 v146, v246, v146, v198
	v_fma_f32 v147, v247, v147, v199
	global_store_dwordx4 v241, v[144:147], s[14:15] sc0 sc1
	s_waitcnt vmcnt(7) lgkmcnt(2)
	v_fma_f32 v148, v244, v148, v200
	v_fma_f32 v149, v245, v149, v201
	v_fma_f32 v150, v246, v150, v202
	v_fma_f32 v151, v247, v151, v203
	global_store_dwordx4 v242, v[148:151], s[14:15] sc0 sc1
	s_waitcnt vmcnt(7) lgkmcnt(1)
	v_fma_f32 v152, v244, v152, v204
	v_fma_f32 v153, v245, v153, v205
	v_fma_f32 v154, v246, v154, v206
	v_fma_f32 v155, v247, v155, v207
	global_store_dwordx4 v243, v[152:155], s[14:15] sc0 sc1
	s_waitcnt vmcnt(7) lgkmcnt(0)
	v_fma_f32 v156, v244, v156, v184
	v_fma_f32 v157, v245, v157, v185
	v_fma_f32 v158, v246, v158, v186
	v_fma_f32 v159, v247, v159, v187
	global_store_dwordx4 v248, v[156:159], s[14:15] sc0 sc1
	global_load_dwordx4 v[244:247], v251, s[20:21] offset:256
	global_load_dwordx4 v[160:163], v237, s[12:13] offset:256
	global_load_dwordx4 v[164:167], v238, s[12:13] offset:256
	global_load_dwordx4 v[168:171], v239, s[12:13] offset:256
	global_load_dwordx4 v[172:175], v240, s[12:13] offset:256
	global_load_dwordx4 v[196:199], v241, s[12:13] offset:256
	global_load_dwordx4 v[200:203], v242, s[12:13] offset:256
	global_load_dwordx4 v[204:207], v243, s[12:13] offset:256
	global_load_dwordx4 v[184:187], v248, s[12:13] offset:256
	ds_write_b128 v249, v[80:83]
	ds_write_b128 v249, v[84:87] offset:16
	ds_write_b128 v249, v[64:67] offset:128
	ds_write_b128 v249, v[68:71] offset:144
	ds_write_b128 v249, v[88:91] offset:4352
	ds_write_b128 v249, v[92:95] offset:4368
	ds_write_b128 v249, v[72:75] offset:4480
	ds_write_b128 v249, v[76:79] offset:4496
	s_waitcnt lgkmcnt(0)
	ds_read_b128 v[128:131], v250
	ds_read_b128 v[132:135], v250 offset:1088
	ds_read_b128 v[136:139], v250 offset:2176
	ds_read_b128 v[140:143], v250 offset:3264
	ds_read_b128 v[144:147], v250 offset:4352
	ds_read_b128 v[148:151], v250 offset:5440
	ds_read_b128 v[152:155], v250 offset:6528
	ds_read_b128 v[156:159], v250 offset:7616
	s_waitcnt vmcnt(7) lgkmcnt(7)
	v_fma_f32 v128, v244, v128, v160
	v_fma_f32 v129, v245, v129, v161
	v_fma_f32 v130, v246, v130, v162
	v_fma_f32 v131, v247, v131, v163
	global_store_dwordx4 v237, v[128:131], s[14:15] offset:256 sc0 sc1
	s_waitcnt vmcnt(7) lgkmcnt(6)
	v_fma_f32 v132, v244, v132, v164
	v_fma_f32 v133, v245, v133, v165
	v_fma_f32 v134, v246, v134, v166
	v_fma_f32 v135, v247, v135, v167
	global_store_dwordx4 v238, v[132:135], s[14:15] offset:256 sc0 sc1
	s_waitcnt vmcnt(7) lgkmcnt(5)
	v_fma_f32 v136, v244, v136, v168
	v_fma_f32 v137, v245, v137, v169
	v_fma_f32 v138, v246, v138, v170
	v_fma_f32 v139, v247, v139, v171
	global_store_dwordx4 v239, v[136:139], s[14:15] offset:256 sc0 sc1
	s_waitcnt vmcnt(7) lgkmcnt(4)
	v_fma_f32 v140, v244, v140, v172
	v_fma_f32 v141, v245, v141, v173
	v_fma_f32 v142, v246, v142, v174
	v_fma_f32 v143, v247, v143, v175
	global_store_dwordx4 v240, v[140:143], s[14:15] offset:256 sc0 sc1
	s_waitcnt vmcnt(7) lgkmcnt(3)
	v_fma_f32 v144, v244, v144, v196
	v_fma_f32 v145, v245, v145, v197
	v_fma_f32 v146, v246, v146, v198
	v_fma_f32 v147, v247, v147, v199
	global_store_dwordx4 v241, v[144:147], s[14:15] offset:256 sc0 sc1
	s_waitcnt vmcnt(7) lgkmcnt(2)
	v_fma_f32 v148, v244, v148, v200
	v_fma_f32 v149, v245, v149, v201
	v_fma_f32 v150, v246, v150, v202
	v_fma_f32 v151, v247, v151, v203
	global_store_dwordx4 v242, v[148:151], s[14:15] offset:256 sc0 sc1
	s_waitcnt vmcnt(7) lgkmcnt(1)
	v_fma_f32 v152, v244, v152, v204
	v_fma_f32 v153, v245, v153, v205
	v_fma_f32 v154, v246, v154, v206
	v_fma_f32 v155, v247, v155, v207
	global_store_dwordx4 v243, v[152:155], s[14:15] offset:256 sc0 sc1
	s_waitcnt vmcnt(7) lgkmcnt(0)
	v_fma_f32 v156, v244, v156, v184
	v_fma_f32 v157, v245, v157, v185
	v_fma_f32 v158, v246, v158, v186
	v_fma_f32 v159, v247, v159, v187
	global_store_dwordx4 v248, v[156:159], s[14:15] offset:256 sc0 sc1
	s_add_u32 s12, s12, 0x20000
	s_addc_u32 s13, s13, 0
	s_add_u32 s14, s14, 0x20000
	s_addc_u32 s15, s15, 0
	global_load_dwordx4 v[244:247], v251, s[20:21]
	global_load_dwordx4 v[160:163], v237, s[12:13]
	global_load_dwordx4 v[164:167], v238, s[12:13]
	global_load_dwordx4 v[168:171], v239, s[12:13]
	global_load_dwordx4 v[172:175], v240, s[12:13]
	global_load_dwordx4 v[196:199], v241, s[12:13]
	global_load_dwordx4 v[200:203], v242, s[12:13]
	global_load_dwordx4 v[204:207], v243, s[12:13]
	global_load_dwordx4 v[184:187], v248, s[12:13]
	ds_write_b128 v249, v[48:51]
	ds_write_b128 v249, v[52:55] offset:16
	ds_write_b128 v249, v[32:35] offset:128
	ds_write_b128 v249, v[36:39] offset:144
	ds_write_b128 v249, v[56:59] offset:4352
	ds_write_b128 v249, v[60:63] offset:4368
	ds_write_b128 v249, v[40:43] offset:4480
	ds_write_b128 v249, v[44:47] offset:4496
	s_waitcnt lgkmcnt(0)
	ds_read_b128 v[128:131], v250
	ds_read_b128 v[132:135], v250 offset:1088
	ds_read_b128 v[136:139], v250 offset:2176
	ds_read_b128 v[140:143], v250 offset:3264
	ds_read_b128 v[144:147], v250 offset:4352
	ds_read_b128 v[148:151], v250 offset:5440
	ds_read_b128 v[152:155], v250 offset:6528
	ds_read_b128 v[156:159], v250 offset:7616
	s_waitcnt vmcnt(7) lgkmcnt(7)
	v_fma_f32 v128, v244, v128, v160
	v_fma_f32 v129, v245, v129, v161
	v_fma_f32 v130, v246, v130, v162
	v_fma_f32 v131, v247, v131, v163
	global_store_dwordx4 v237, v[128:131], s[14:15] sc0 sc1
	s_waitcnt vmcnt(7) lgkmcnt(6)
	v_fma_f32 v132, v244, v132, v164
	v_fma_f32 v133, v245, v133, v165
	v_fma_f32 v134, v246, v134, v166
	v_fma_f32 v135, v247, v135, v167
	global_store_dwordx4 v238, v[132:135], s[14:15] sc0 sc1
	s_waitcnt vmcnt(7) lgkmcnt(5)
	v_fma_f32 v136, v244, v136, v168
	v_fma_f32 v137, v245, v137, v169
	v_fma_f32 v138, v246, v138, v170
	v_fma_f32 v139, v247, v139, v171
	global_store_dwordx4 v239, v[136:139], s[14:15] sc0 sc1
	s_waitcnt vmcnt(7) lgkmcnt(4)
	v_fma_f32 v140, v244, v140, v172
	v_fma_f32 v141, v245, v141, v173
	v_fma_f32 v142, v246, v142, v174
	v_fma_f32 v143, v247, v143, v175
	global_store_dwordx4 v240, v[140:143], s[14:15] sc0 sc1
	s_waitcnt vmcnt(7) lgkmcnt(3)
	v_fma_f32 v144, v244, v144, v196
	v_fma_f32 v145, v245, v145, v197
	v_fma_f32 v146, v246, v146, v198
	v_fma_f32 v147, v247, v147, v199
	global_store_dwordx4 v241, v[144:147], s[14:15] sc0 sc1
	s_waitcnt vmcnt(7) lgkmcnt(2)
	v_fma_f32 v148, v244, v148, v200
	v_fma_f32 v149, v245, v149, v201
	v_fma_f32 v150, v246, v150, v202
	v_fma_f32 v151, v247, v151, v203
	global_store_dwordx4 v242, v[148:151], s[14:15] sc0 sc1
	s_waitcnt vmcnt(7) lgkmcnt(1)
	v_fma_f32 v152, v244, v152, v204
	v_fma_f32 v153, v245, v153, v205
	v_fma_f32 v154, v246, v154, v206
	v_fma_f32 v155, v247, v155, v207
	global_store_dwordx4 v243, v[152:155], s[14:15] sc0 sc1
	s_waitcnt vmcnt(7) lgkmcnt(0)
	v_fma_f32 v156, v244, v156, v184
	v_fma_f32 v157, v245, v157, v185
	v_fma_f32 v158, v246, v158, v186
	v_fma_f32 v159, v247, v159, v187
	global_store_dwordx4 v248, v[156:159], s[14:15] sc0 sc1
	global_load_dwordx4 v[244:247], v251, s[20:21] offset:256
	global_load_dwordx4 v[160:163], v237, s[12:13] offset:256
	global_load_dwordx4 v[164:167], v238, s[12:13] offset:256
	global_load_dwordx4 v[168:171], v239, s[12:13] offset:256
	global_load_dwordx4 v[172:175], v240, s[12:13] offset:256
	global_load_dwordx4 v[196:199], v241, s[12:13] offset:256
	global_load_dwordx4 v[200:203], v242, s[12:13] offset:256
	global_load_dwordx4 v[204:207], v243, s[12:13] offset:256
	global_load_dwordx4 v[184:187], v248, s[12:13] offset:256
	ds_write_b128 v249, v[16:19]
	ds_write_b128 v249, v[20:23] offset:16
	ds_write_b128 v249, v[0:3] offset:128
	ds_write_b128 v249, v[4:7] offset:144
	ds_write_b128 v249, v[24:27] offset:4352
	ds_write_b128 v249, v[28:31] offset:4368
	ds_write_b128 v249, v[8:11] offset:4480
	ds_write_b128 v249, v[12:15] offset:4496
	s_waitcnt lgkmcnt(0)
	ds_read_b128 v[128:131], v250
	ds_read_b128 v[132:135], v250 offset:1088
	ds_read_b128 v[136:139], v250 offset:2176
	ds_read_b128 v[140:143], v250 offset:3264
	ds_read_b128 v[144:147], v250 offset:4352
	ds_read_b128 v[148:151], v250 offset:5440
	ds_read_b128 v[152:155], v250 offset:6528
	ds_read_b128 v[156:159], v250 offset:7616
	s_waitcnt vmcnt(7) lgkmcnt(7)
	v_fma_f32 v128, v244, v128, v160
	v_fma_f32 v129, v245, v129, v161
	v_fma_f32 v130, v246, v130, v162
	v_fma_f32 v131, v247, v131, v163
	global_store_dwordx4 v237, v[128:131], s[14:15] offset:256 sc0 sc1
	s_waitcnt vmcnt(7) lgkmcnt(6)
	v_fma_f32 v132, v244, v132, v164
	v_fma_f32 v133, v245, v133, v165
	v_fma_f32 v134, v246, v134, v166
	v_fma_f32 v135, v247, v135, v167
	global_store_dwordx4 v238, v[132:135], s[14:15] offset:256 sc0 sc1
	s_waitcnt vmcnt(7) lgkmcnt(5)
	v_fma_f32 v136, v244, v136, v168
	v_fma_f32 v137, v245, v137, v169
	v_fma_f32 v138, v246, v138, v170
	v_fma_f32 v139, v247, v139, v171
	global_store_dwordx4 v239, v[136:139], s[14:15] offset:256 sc0 sc1
	s_waitcnt vmcnt(7) lgkmcnt(4)
	v_fma_f32 v140, v244, v140, v172
	v_fma_f32 v141, v245, v141, v173
	v_fma_f32 v142, v246, v142, v174
	v_fma_f32 v143, v247, v143, v175
	global_store_dwordx4 v240, v[140:143], s[14:15] offset:256 sc0 sc1
	s_waitcnt vmcnt(7) lgkmcnt(3)
	v_fma_f32 v144, v244, v144, v196
	v_fma_f32 v145, v245, v145, v197
	v_fma_f32 v146, v246, v146, v198
	v_fma_f32 v147, v247, v147, v199
	global_store_dwordx4 v241, v[144:147], s[14:15] offset:256 sc0 sc1
	s_waitcnt vmcnt(7) lgkmcnt(2)
	v_fma_f32 v148, v244, v148, v200
	v_fma_f32 v149, v245, v149, v201
	v_fma_f32 v150, v246, v150, v202
	v_fma_f32 v151, v247, v151, v203
	global_store_dwordx4 v242, v[148:151], s[14:15] offset:256 sc0 sc1
	s_waitcnt vmcnt(7) lgkmcnt(1)
	v_fma_f32 v152, v244, v152, v204
	v_fma_f32 v153, v245, v153, v205
	v_fma_f32 v154, v246, v154, v206
	v_fma_f32 v155, v247, v155, v207
	global_store_dwordx4 v243, v[152:155], s[14:15] offset:256 sc0 sc1
	s_waitcnt vmcnt(7) lgkmcnt(0)
	v_fma_f32 v156, v244, v156, v184
	v_fma_f32 v157, v245, v157, v185
	v_fma_f32 v158, v246, v158, v186
	v_fma_f32 v159, v247, v159, v187
	global_store_dwordx4 v248, v[156:159], s[14:15] offset:256 sc0 sc1
	s_waitcnt lgkmcnt(0)
	v_readlane_b32 s16, v254, 11
	s_andn2_b32 s17, s26, 63
	s_add_i32 s2, s2, s16
	s_cmp_lt_i32 s2, s17
	s_cbranch_scc0 .Lhx_down_left
	s_barrier
	s_branch .LBB0_1086
